# fp8 K-loops: unit-scale v_mfma_scale_f32_16x16x128_f8f6f4 replaced by the unscaled v_mfma_f32_16x16x128_f8f6f4 (same e4m3 operands, scale 2^0: bit-identical) + de-serialised K-split slab epilogues
# speedup vs baseline: 1.0201x; 1.0201x over previous
; #define PG8_STAGE(bufoff, gbase, voff) do { _Pragma("unroll") for (int _i = 0; _i < 2; ++_i) \
;         __builtin_amdgcn_global_load_lds((const unsigned*)((const char*)(gbase) + (voff)[_i]), (LAS unsigned*)(lds + (bufoff) + ldsw + _i * 8192), 16, 0, 0); } while (0)
; #define PG8_LDA(dst, b, h) do { _Pragma("unroll") for (int m = 0; m < 4; ++m) _Pragma("unroll") for (int k = 0; k < 2; ++k) dst[m][k] = *(const LAS bf16x8*)(lds + PG8_SA(b, h) + aoff + m * 2048 + k * KOFF); } while (0)
; template <class Epi, bool ALIGN_EPI = true, bool FP8 = false>
; __device__ __forceinline__ void gemm_phase(LAS unsigned char* lds, const Gemm g, const StaticOrder& S, const Epi& E, const int wid) {
;     ...
;         for (int t = 0; t < nt; t += 2) {
;             const bool last = (t == nt - 2);
;             if constexpr (FP8) {
; #pragma unroll
;                 for (int a = 0; a < 2; ++a)
; #pragma unroll
;                     for (int b = 0; b < 2; ++b)
; #pragma unroll
;                         for (int m = 0; m < 4; ++m) asm volatile("" : "+v"(acc8[a][b][m]));
;             }
;             const char* a1 = cA + (size_t)(t + 1) * kstep;
;             const char* a2 = last ? nA : cA + (size_t)(t + 2) * kstep; const char* b2 = last ? nB : cB + (size_t)(t + 2) * kstep;
;             const char* a3 = a2 + kstep; const char* b3 = b2 + kstep;
;             PG8_LDB(B0, 0, 0); PG8_LDB(B1, 0, 1); PG8_SCHED; PG8_LDA(At, 0, 0); PG8_STAGE(PG8_SA(1, 1), a1 + hstep, voffA);
;             PG8_WAIT_V(8); PG8_WAIT_L(0); PG8_BAR; PG8_MMA(0, 0, At, B0); PG8_MMA(0, 1, At, B1); PG8_BAR; PG8_SCHED;
;             PG8_LDA(At, 0, 1); PG8_STAGE(PG8_SB(0, 0), b2, voffB); PG8_STAGE(PG8_SB(0, 1), b2 + hstep, voffB); PG8_STAGE(PG8_SA(0, 0), a2, voffA);
;             PG8_WAIT_V(8); PG8_WAIT_L(0); PG8_BAR; PG8_MMA(1, 0, At, B0); PG8_MMA(1, 1, At, B1); PG8_BAR; PG8_SCHED;
;             PG8_LDB(B0, 1, 0); PG8_LDB(B1, 1, 1); PG8_SCHED; PG8_LDA(At, 1, 0); PG8_STAGE(PG8_SA(0, 1), a2 + hstep, voffA);
;             PG8_WAIT_V(8); PG8_WAIT_L(0); PG8_BAR; PG8_MMA(0, 0, At, B0); PG8_MMA(0, 1, At, B1); PG8_BAR; PG8_SCHED;
;             PG8_LDA(At, 1, 1); PG8_STAGE(PG8_SB(1, 0), b3, voffB); PG8_STAGE(PG8_SB(1, 1), b3 + hstep, voffB); PG8_STAGE(PG8_SA(1, 0), a3, voffA);
;             PG8_WAIT_V(8); PG8_WAIT_L(0); PG8_BAR; PG8_MMA(1, 0, At, B0); PG8_MMA(1, 1, At, B1); PG8_BAR; PG8_SCHED;
.LBB0_506:
	ds_read_b128 v[146:149], v137
	ds_read_b128 v[154:157], v137 offset:1024
	ds_read_b128 v[158:161], v137 offset:2048
	ds_read_b128 v[162:165], v137 offset:3072
	ds_read_b128 v[166:169], v152
	ds_read_b128 v[170:173], v152 offset:1024
	ds_read_b128 v[174:177], v152 offset:2048
	ds_read_b128 v[178:181], v152 offset:3072
	s_add_i32 s52, s34, 2
	s_add_u32 s35, s30, 0xfff80080
	s_addc_u32 s36, s31, -1
	s_cmp_eq_u32 s39, s34
	s_cselect_b32 s34, s38, s42
	s_cselect_b32 s37, s3, s36
	s_cselect_b32 s36, s23, s35
	s_cselect_b32 s35, s25, s43
	v_lshl_add_u64 v[214:215], s[30:31], 0, v[140:141]
	s_add_i32 m0, s75, 0xc000
	ds_read_b128 v[182:185], v153
	ds_read_b128 v[186:189], v153 offset:1024
	ds_read_b128 v[190:193], v153 offset:2048
	ds_read_b128 v[194:197], v153 offset:3072
	ds_read_b128 v[198:201], v153 offset:4096
	ds_read_b128 v[202:205], v153 offset:5120
	ds_read_b128 v[206:209], v153 offset:6144
	ds_read_b128 v[210:213], v153 offset:7168
	global_load_lds_dwordx4 v[214:215], off
	v_lshl_add_u64 v[214:215], s[30:31], 0, v[142:143]
	s_add_i32 m0, s75, 0xe000
	s_nop 0
	global_load_lds_dwordx4 v[214:215], off
	s_waitcnt vmcnt(8)
	s_waitcnt lgkmcnt(0)
	s_barrier
	s_setprio 1
	s_waitcnt lgkmcnt(0)
	v_mfma_f32_16x16x32_bf16 v[124:127], v[146:149], v[182:185], v[124:127]
	v_mfma_f32_16x16x32_bf16 v[120:123], v[158:161], v[182:185], v[120:123]
	v_mfma_f32_16x16x32_bf16 v[108:111], v[146:149], v[190:193], v[108:111]
	v_mfma_f32_16x16x32_bf16 v[104:107], v[158:161], v[190:193], v[104:107]
	v_mfma_f32_16x16x32_bf16 v[92:95], v[146:149], v[198:201], v[92:95]
	v_mfma_f32_16x16x32_bf16 v[88:91], v[158:161], v[198:201], v[88:91]
	v_mfma_f32_16x16x32_bf16 v[76:79], v[146:149], v[206:209], v[76:79]
	v_mfma_f32_16x16x32_bf16 v[72:75], v[158:161], v[206:209], v[72:75]
	v_mfma_f32_16x16x32_bf16 v[124:127], v[154:157], v[186:189], v[124:127]
	v_mfma_f32_16x16x32_bf16 v[120:123], v[162:165], v[186:189], v[120:123]
	v_mfma_f32_16x16x32_bf16 v[108:111], v[154:157], v[194:197], v[108:111]
	v_mfma_f32_16x16x32_bf16 v[104:107], v[162:165], v[194:197], v[104:107]
	v_mfma_f32_16x16x32_bf16 v[92:95], v[154:157], v[202:205], v[92:95]
	v_mfma_f32_16x16x32_bf16 v[88:91], v[162:165], v[202:205], v[88:91]
	v_mfma_f32_16x16x32_bf16 v[76:79], v[154:157], v[210:213], v[76:79]
	v_mfma_f32_16x16x32_bf16 v[72:75], v[162:165], v[210:213], v[72:75]
	s_setprio 0
	s_setprio 1
	v_mfma_f32_16x16x32_bf16 v[116:119], v[166:169], v[182:185], v[116:119]
	v_mfma_f32_16x16x32_bf16 v[112:115], v[174:177], v[182:185], v[112:115]
	v_mfma_f32_16x16x32_bf16 v[100:103], v[166:169], v[190:193], v[100:103]
	v_mfma_f32_16x16x32_bf16 v[96:99], v[174:177], v[190:193], v[96:99]
	v_mfma_f32_16x16x32_bf16 v[84:87], v[166:169], v[198:201], v[84:87]
	v_mfma_f32_16x16x32_bf16 v[80:83], v[174:177], v[198:201], v[80:83]
	v_mfma_f32_16x16x32_bf16 v[68:71], v[166:169], v[206:209], v[68:71]
	v_mfma_f32_16x16x32_bf16 v[64:67], v[174:177], v[206:209], v[64:67]
	v_mfma_f32_16x16x32_bf16 v[116:119], v[170:173], v[186:189], v[116:119]
	v_mfma_f32_16x16x32_bf16 v[112:115], v[178:181], v[186:189], v[112:115]
	v_mfma_f32_16x16x32_bf16 v[100:103], v[170:173], v[194:197], v[100:103]
	v_mfma_f32_16x16x32_bf16 v[96:99], v[178:181], v[194:197], v[96:99]
	v_mfma_f32_16x16x32_bf16 v[84:87], v[170:173], v[202:205], v[84:87]
	v_mfma_f32_16x16x32_bf16 v[80:83], v[178:181], v[202:205], v[80:83]
	v_mfma_f32_16x16x32_bf16 v[68:71], v[170:173], v[210:213], v[68:71]
	v_mfma_f32_16x16x32_bf16 v[64:67], v[178:181], v[210:213], v[64:67]
	s_setprio 0
	s_barrier
	s_add_i32 s54, s86, s48
	v_lshl_add_u64 v[214:215], s[34:35], 0, v[132:133]
	s_mov_b32 m0, s54
	ds_read_b128 v[182:185], v153 offset:16384
	ds_read_b128 v[186:189], v153 offset:17408
	ds_read_b128 v[190:193], v153 offset:18432
	ds_read_b128 v[194:197], v153 offset:19456
	ds_read_b128 v[198:201], v153 offset:20480
	ds_read_b128 v[202:205], v153 offset:21504
	ds_read_b128 v[206:209], v153 offset:22528
	ds_read_b128 v[210:213], v153 offset:23552
	global_load_lds_dwordx4 v[214:215], off
	s_add_i32 m0, s54, 0x2000
	s_add_u32 s64, s34, 0x80000
	v_lshl_add_u64 v[216:217], s[34:35], 0, v[128:129]
	s_addc_u32 s65, s35, 0
	s_add_i32 s54, s87, s48
	global_load_lds_dwordx4 v[216:217], off
	v_lshl_add_u64 v[218:219], s[64:65], 0, v[132:133]
	s_mov_b32 m0, s54
	v_lshl_add_u64 v[220:221], s[36:37], 0, v[130:131]
	global_load_lds_dwordx4 v[218:219], off
	v_lshl_add_u64 v[218:219], s[64:65], 0, v[128:129]
	s_add_i32 m0, s54, 0x2000
	s_nop 0
	global_load_lds_dwordx4 v[218:219], off
	v_lshl_add_u64 v[218:219], s[36:37], 0, v[134:135]
	s_mov_b32 m0, s75
	s_nop 0
	global_load_lds_dwordx4 v[218:219], off
	s_mov_b32 m0, s76
	s_nop 0
	global_load_lds_dwordx4 v[220:221], off
	s_waitcnt vmcnt(8)
	s_waitcnt lgkmcnt(0)
	s_barrier
; #define PG8_STAGE(bufoff, gbase, voff) do { _Pragma("unroll") for (int _i = 0; _i < 2; ++_i) \
;         __builtin_amdgcn_global_load_lds((const unsigned*)((const char*)(gbase) + (voff)[_i]), (LAS unsigned*)(lds + (bufoff) + ldsw + _i * 8192), 16, 0, 0); } while (0)
; #define PG8_LDA(dst, b, h) do { _Pragma("unroll") for (int m = 0; m < 4; ++m) _Pragma("unroll") for (int k = 0; k < 2; ++k) dst[m][k] = *(const LAS bf16x8*)(lds + PG8_SA(b, h) + aoff + m * 2048 + k * KOFF); } while (0)
; #define PG8_LDB(dst, b, h) do { _Pragma("unroll") for (int n = 0; n < 2; ++n) _Pragma("unroll") for (int k = 0; k < 2; ++k) dst[n][k] = *(const LAS bf16x8*)(lds + PG8_SB(b, h) + boff + n * 2048 + k * KOFF); } while (0)
; #define PG8_WAIT_V(n) asm volatile("s_waitcnt vmcnt(" #n ")" ::: "memory")
; #define PG8_WAIT_L(n) asm volatile("s_waitcnt lgkmcnt(" #n ")" ::: "memory")
; template <class Epi, bool ALIGN_EPI = true, bool FP8 = false>
; __device__ __forceinline__ void gemm_phase(LAS unsigned char* lds, const Gemm g, const StaticOrder& S, const Epi& E, const int wid) {
;     ...
;             const char* a1 = cA + (size_t)(t + 1) * kstep;
;             const char* a2 = last ? nA : cA + (size_t)(t + 2) * kstep; const char* b2 = last ? nB : cB + (size_t)(t + 2) * kstep;
;             const char* a3 = a2 + kstep; const char* b3 = b2 + kstep;
;             PG8_LDB(B0, 0, 0); PG8_LDB(B1, 0, 1); PG8_SCHED; PG8_LDA(At, 0, 0); PG8_STAGE(PG8_SA(1, 1), a1 + hstep, voffA);
;             PG8_WAIT_V(8); PG8_WAIT_L(0); PG8_BAR; PG8_MMA(0, 0, At, B0); PG8_MMA(0, 1, At, B1); PG8_BAR; PG8_SCHED;
;             PG8_LDA(At, 0, 1); PG8_STAGE(PG8_SB(0, 0), b2, voffB); PG8_STAGE(PG8_SB(0, 1), b2 + hstep, voffB); PG8_STAGE(PG8_SA(0, 0), a2, voffA);
;             PG8_WAIT_V(8); PG8_WAIT_L(0); PG8_BAR; PG8_MMA(1, 0, At, B0); PG8_MMA(1, 1, At, B1); PG8_BAR; PG8_SCHED;
;             PG8_LDB(B0, 1, 0); PG8_LDB(B1, 1, 1); PG8_SCHED; PG8_LDA(At, 1, 0); PG8_STAGE(PG8_SA(0, 1), a2 + hstep, voffA);
;             PG8_WAIT_V(8); PG8_WAIT_L(0); PG8_BAR; PG8_MMA(0, 0, At, B0); PG8_MMA(0, 1, At, B1); PG8_BAR; PG8_SCHED;
;             PG8_LDA(At, 1, 1); PG8_STAGE(PG8_SB(1, 0), b3, voffB); PG8_STAGE(PG8_SB(1, 1), b3 + hstep, voffB); PG8_STAGE(PG8_SA(1, 0), a3, voffA);
;             PG8_WAIT_V(8); PG8_WAIT_L(0); PG8_BAR; PG8_MMA(1, 0, At, B0); PG8_MMA(1, 1, At, B1); PG8_BAR; PG8_SCHED;
	s_setprio 1
	s_waitcnt lgkmcnt(0)
	v_mfma_f32_16x16x32_bf16 v[60:63], v[146:149], v[182:185], v[60:63]
	v_mfma_f32_16x16x32_bf16 v[56:59], v[158:161], v[182:185], v[56:59]
	v_mfma_f32_16x16x32_bf16 v[44:47], v[146:149], v[190:193], v[44:47]
	v_mfma_f32_16x16x32_bf16 v[40:43], v[158:161], v[190:193], v[40:43]
	v_mfma_f32_16x16x32_bf16 v[28:31], v[146:149], v[198:201], v[28:31]
	v_mfma_f32_16x16x32_bf16 v[24:27], v[158:161], v[198:201], v[24:27]
	v_mfma_f32_16x16x32_bf16 v[12:15], v[146:149], v[206:209], v[12:15]
	v_mfma_f32_16x16x32_bf16 v[8:11], v[158:161], v[206:209], v[8:11]
	v_mfma_f32_16x16x32_bf16 v[60:63], v[154:157], v[186:189], v[60:63]
	v_mfma_f32_16x16x32_bf16 v[56:59], v[162:165], v[186:189], v[56:59]
	v_mfma_f32_16x16x32_bf16 v[44:47], v[154:157], v[194:197], v[44:47]
	v_mfma_f32_16x16x32_bf16 v[40:43], v[162:165], v[194:197], v[40:43]
	v_mfma_f32_16x16x32_bf16 v[28:31], v[154:157], v[202:205], v[28:31]
	v_mfma_f32_16x16x32_bf16 v[24:27], v[162:165], v[202:205], v[24:27]
	v_mfma_f32_16x16x32_bf16 v[12:15], v[154:157], v[210:213], v[12:15]
	v_mfma_f32_16x16x32_bf16 v[8:11], v[162:165], v[210:213], v[8:11]
	s_setprio 0
	s_setprio 1
	v_mfma_f32_16x16x32_bf16 v[52:55], v[166:169], v[182:185], v[52:55]
	v_mfma_f32_16x16x32_bf16 v[48:51], v[174:177], v[182:185], v[48:51]
	v_mfma_f32_16x16x32_bf16 v[36:39], v[166:169], v[190:193], v[36:39]
	v_mfma_f32_16x16x32_bf16 v[32:35], v[174:177], v[190:193], v[32:35]
	v_mfma_f32_16x16x32_bf16 v[20:23], v[166:169], v[198:201], v[20:23]
	v_mfma_f32_16x16x32_bf16 v[16:19], v[174:177], v[198:201], v[16:19]
	v_mfma_f32_16x16x32_bf16 v[4:7], v[166:169], v[206:209], v[4:7]
	v_mfma_f32_16x16x32_bf16 v[0:3], v[174:177], v[206:209], v[0:3]
	v_mfma_f32_16x16x32_bf16 v[52:55], v[170:173], v[186:189], v[52:55]
	v_mfma_f32_16x16x32_bf16 v[48:51], v[178:181], v[186:189], v[48:51]
	v_mfma_f32_16x16x32_bf16 v[36:39], v[170:173], v[194:197], v[36:39]
	v_mfma_f32_16x16x32_bf16 v[32:35], v[178:181], v[194:197], v[32:35]
	v_mfma_f32_16x16x32_bf16 v[20:23], v[170:173], v[202:205], v[20:23]
	v_mfma_f32_16x16x32_bf16 v[16:19], v[178:181], v[202:205], v[16:19]
	v_mfma_f32_16x16x32_bf16 v[4:7], v[170:173], v[210:213], v[4:7]
	v_mfma_f32_16x16x32_bf16 v[0:3], v[178:181], v[210:213], v[0:3]
	s_setprio 0
	s_barrier
	s_add_i32 s54, 0, 0x18000
	s_add_i32 s64, 0, 0x1c000
	v_add_u32_e32 v162, s54, v150
	v_add_u32_e32 v178, s64, v150
	ds_read_b128 v[146:149], v162
	ds_read_b128 v[154:157], v162 offset:1024
	ds_read_b128 v[158:161], v162 offset:2048
	ds_read_b128 v[162:165], v162 offset:3072
	ds_read_b128 v[166:169], v178
	ds_read_b128 v[170:173], v178 offset:1024
	ds_read_b128 v[174:177], v178 offset:2048
	ds_read_b128 v[178:181], v178 offset:3072
	s_add_u32 s36, s36, 0x80000
	s_addc_u32 s37, s37, 0
	s_mov_b32 m0, s77
	v_lshl_add_u64 v[222:223], s[36:37], 0, v[134:135]
	ds_read_b128 v[182:185], v153 offset:32768
	ds_read_b128 v[186:189], v153 offset:33792
	ds_read_b128 v[190:193], v153 offset:34816
	ds_read_b128 v[194:197], v153 offset:35840
	ds_read_b128 v[198:201], v153 offset:36864
	ds_read_b128 v[202:205], v153 offset:37888
	ds_read_b128 v[206:209], v153 offset:38912
	ds_read_b128 v[210:213], v153 offset:39936
	global_load_lds_dwordx4 v[222:223], off
	v_lshl_add_u64 v[222:223], s[36:37], 0, v[130:131]
	s_mov_b32 m0, s78
	s_nop 0
	global_load_lds_dwordx4 v[222:223], off
	s_waitcnt vmcnt(8)
	s_waitcnt lgkmcnt(0)
	s_barrier
	s_setprio 1
	s_waitcnt lgkmcnt(0)
	v_mfma_f32_16x16x32_bf16 v[124:127], v[146:149], v[182:185], v[124:127]
	v_mfma_f32_16x16x32_bf16 v[120:123], v[158:161], v[182:185], v[120:123]
	v_mfma_f32_16x16x32_bf16 v[108:111], v[146:149], v[190:193], v[108:111]
	v_mfma_f32_16x16x32_bf16 v[104:107], v[158:161], v[190:193], v[104:107]
	v_mfma_f32_16x16x32_bf16 v[92:95], v[146:149], v[198:201], v[92:95]
	v_mfma_f32_16x16x32_bf16 v[88:91], v[158:161], v[198:201], v[88:91]
	v_mfma_f32_16x16x32_bf16 v[76:79], v[146:149], v[206:209], v[76:79]
	v_mfma_f32_16x16x32_bf16 v[72:75], v[158:161], v[206:209], v[72:75]
	v_mfma_f32_16x16x32_bf16 v[124:127], v[154:157], v[186:189], v[124:127]
	v_mfma_f32_16x16x32_bf16 v[120:123], v[162:165], v[186:189], v[120:123]
	v_mfma_f32_16x16x32_bf16 v[108:111], v[154:157], v[194:197], v[108:111]
	v_mfma_f32_16x16x32_bf16 v[104:107], v[162:165], v[194:197], v[104:107]
	v_mfma_f32_16x16x32_bf16 v[92:95], v[154:157], v[202:205], v[92:95]
	v_mfma_f32_16x16x32_bf16 v[88:91], v[162:165], v[202:205], v[88:91]
	v_mfma_f32_16x16x32_bf16 v[76:79], v[154:157], v[210:213], v[76:79]
	v_mfma_f32_16x16x32_bf16 v[72:75], v[162:165], v[210:213], v[72:75]
	s_setprio 0
	s_setprio 1
	v_mfma_f32_16x16x32_bf16 v[116:119], v[166:169], v[182:185], v[116:119]
	v_mfma_f32_16x16x32_bf16 v[112:115], v[174:177], v[182:185], v[112:115]
	v_mfma_f32_16x16x32_bf16 v[100:103], v[166:169], v[190:193], v[100:103]
	v_mfma_f32_16x16x32_bf16 v[96:99], v[174:177], v[190:193], v[96:99]
	v_mfma_f32_16x16x32_bf16 v[84:87], v[166:169], v[198:201], v[84:87]
	v_mfma_f32_16x16x32_bf16 v[80:83], v[174:177], v[198:201], v[80:83]
	v_mfma_f32_16x16x32_bf16 v[68:71], v[166:169], v[206:209], v[68:71]
	v_mfma_f32_16x16x32_bf16 v[64:67], v[174:177], v[206:209], v[64:67]
	v_mfma_f32_16x16x32_bf16 v[116:119], v[170:173], v[186:189], v[116:119]
	v_mfma_f32_16x16x32_bf16 v[112:115], v[178:181], v[186:189], v[112:115]
	v_mfma_f32_16x16x32_bf16 v[100:103], v[170:173], v[194:197], v[100:103]
	v_mfma_f32_16x16x32_bf16 v[96:99], v[178:181], v[194:197], v[96:99]
	v_mfma_f32_16x16x32_bf16 v[84:87], v[170:173], v[202:205], v[84:87]
	v_mfma_f32_16x16x32_bf16 v[80:83], v[178:181], v[202:205], v[80:83]
	v_mfma_f32_16x16x32_bf16 v[68:71], v[170:173], v[210:213], v[68:71]
	v_mfma_f32_16x16x32_bf16 v[64:67], v[178:181], v[210:213], v[64:67]
	s_setprio 0
	s_barrier
; #define PG8_STAGE(bufoff, gbase, voff) do { _Pragma("unroll") for (int _i = 0; _i < 2; ++_i) \
;         __builtin_amdgcn_global_load_lds((const unsigned*)((const char*)(gbase) + (voff)[_i]), (LAS unsigned*)(lds + (bufoff) + ldsw + _i * 8192), 16, 0, 0); } while (0)
; #define PG8_LDA(dst, b, h) do { _Pragma("unroll") for (int m = 0; m < 4; ++m) _Pragma("unroll") for (int k = 0; k < 2; ++k) dst[m][k] = *(const LAS bf16x8*)(lds + PG8_SA(b, h) + aoff + m * 2048 + k * KOFF); } while (0)
; #define PG8_LDB(dst, b, h) do { _Pragma("unroll") for (int n = 0; n < 2; ++n) _Pragma("unroll") for (int k = 0; k < 2; ++k) dst[n][k] = *(const LAS bf16x8*)(lds + PG8_SB(b, h) + boff + n * 2048 + k * KOFF); } while (0)
; #define PG8_WAIT_V(n) asm volatile("s_waitcnt vmcnt(" #n ")" ::: "memory")
; #define PG8_WAIT_L(n) asm volatile("s_waitcnt lgkmcnt(" #n ")" ::: "memory")
; #define PG8_BAR __builtin_amdgcn_s_barrier()
; #define PG8_SCHED __builtin_amdgcn_sched_barrier(0)
; template <class Epi, bool ALIGN_EPI = true, bool FP8 = false>
; __device__ __forceinline__ void gemm_phase(LAS unsigned char* lds, const Gemm g, const StaticOrder& S, const Epi& E, const int wid) {
;     ...
;             PG8_WAIT_V(8); PG8_WAIT_L(0); PG8_BAR; PG8_MMA(1, 0, At, B0); PG8_MMA(1, 1, At, B1); PG8_BAR; PG8_SCHED;
;             PG8_LDB(B0, 1, 0); PG8_LDB(B1, 1, 1); PG8_SCHED; PG8_LDA(At, 1, 0); PG8_STAGE(PG8_SA(0, 1), a2 + hstep, voffA);
;             PG8_WAIT_V(8); PG8_WAIT_L(0); PG8_BAR; PG8_MMA(0, 0, At, B0); PG8_MMA(0, 1, At, B1); PG8_BAR; PG8_SCHED;
;             PG8_LDA(At, 1, 1); PG8_STAGE(PG8_SB(1, 0), b3, voffB); PG8_STAGE(PG8_SB(1, 1), b3 + hstep, voffB); PG8_STAGE(PG8_SA(1, 0), a3, voffA);
;             PG8_WAIT_V(8); PG8_WAIT_L(0); PG8_BAR; PG8_MMA(1, 0, At, B0); PG8_MMA(1, 1, At, B1); PG8_BAR; PG8_SCHED;
;         }
	s_add_i32 s36, s54, s48
	v_lshl_add_u64 v[214:215], v[214:215], 0, s[16:17]
	s_mov_b32 m0, s36
	ds_read_b128 v[182:185], v153 offset:49152
	ds_read_b128 v[186:189], v153 offset:50176
	ds_read_b128 v[190:193], v153 offset:51200
	ds_read_b128 v[194:197], v153 offset:52224
	ds_read_b128 v[198:201], v153 offset:53248
	ds_read_b128 v[202:205], v153 offset:54272
	ds_read_b128 v[206:209], v153 offset:55296
	ds_read_b128 v[210:213], v153 offset:56320
	global_load_lds_dwordx4 v[214:215], off
	s_add_i32 m0, s36, 0x2000
	s_add_u32 s34, s34, 0x80080
	v_lshl_add_u64 v[214:215], v[216:217], 0, s[16:17]
	s_addc_u32 s35, s35, 0
	s_add_i32 s36, s64, s48
	global_load_lds_dwordx4 v[214:215], off
	v_lshl_add_u64 v[214:215], s[34:35], 0, v[132:133]
	s_mov_b32 m0, s36
	s_nop 0
	global_load_lds_dwordx4 v[214:215], off
	v_lshl_add_u64 v[214:215], s[34:35], 0, v[128:129]
	s_add_i32 m0, s36, 0x2000
	s_nop 0
	global_load_lds_dwordx4 v[214:215], off
	v_lshl_add_u64 v[214:215], v[218:219], 0, s[16:17]
	s_mov_b32 m0, s83
	s_nop 0
	global_load_lds_dwordx4 v[214:215], off
	v_lshl_add_u64 v[214:215], v[220:221], 0, s[16:17]
	s_mov_b32 m0, s84
	s_nop 0
	global_load_lds_dwordx4 v[214:215], off
	s_waitcnt vmcnt(8)
	s_waitcnt lgkmcnt(0)
	s_barrier
	s_setprio 1
	s_waitcnt lgkmcnt(0)
	v_mfma_f32_16x16x32_bf16 v[60:63], v[146:149], v[182:185], v[60:63]
	v_mfma_f32_16x16x32_bf16 v[56:59], v[158:161], v[182:185], v[56:59]
	v_mfma_f32_16x16x32_bf16 v[44:47], v[146:149], v[190:193], v[44:47]
	v_mfma_f32_16x16x32_bf16 v[40:43], v[158:161], v[190:193], v[40:43]
	v_mfma_f32_16x16x32_bf16 v[28:31], v[146:149], v[198:201], v[28:31]
	v_mfma_f32_16x16x32_bf16 v[24:27], v[158:161], v[198:201], v[24:27]
	v_mfma_f32_16x16x32_bf16 v[12:15], v[146:149], v[206:209], v[12:15]
	v_mfma_f32_16x16x32_bf16 v[8:11], v[158:161], v[206:209], v[8:11]
	v_mfma_f32_16x16x32_bf16 v[60:63], v[154:157], v[186:189], v[60:63]
	v_mfma_f32_16x16x32_bf16 v[56:59], v[162:165], v[186:189], v[56:59]
	v_mfma_f32_16x16x32_bf16 v[44:47], v[154:157], v[194:197], v[44:47]
	v_mfma_f32_16x16x32_bf16 v[40:43], v[162:165], v[194:197], v[40:43]
	v_mfma_f32_16x16x32_bf16 v[28:31], v[154:157], v[202:205], v[28:31]
	v_mfma_f32_16x16x32_bf16 v[24:27], v[162:165], v[202:205], v[24:27]
	v_mfma_f32_16x16x32_bf16 v[12:15], v[154:157], v[210:213], v[12:15]
	v_mfma_f32_16x16x32_bf16 v[8:11], v[162:165], v[210:213], v[8:11]
	s_setprio 0
	s_setprio 1
	v_mfma_f32_16x16x32_bf16 v[52:55], v[166:169], v[182:185], v[52:55]
	v_mfma_f32_16x16x32_bf16 v[48:51], v[174:177], v[182:185], v[48:51]
	v_mfma_f32_16x16x32_bf16 v[36:39], v[166:169], v[190:193], v[36:39]
	v_mfma_f32_16x16x32_bf16 v[32:35], v[174:177], v[190:193], v[32:35]
	v_mfma_f32_16x16x32_bf16 v[20:23], v[166:169], v[198:201], v[20:23]
	v_mfma_f32_16x16x32_bf16 v[16:19], v[174:177], v[198:201], v[16:19]
	v_mfma_f32_16x16x32_bf16 v[4:7], v[166:169], v[206:209], v[4:7]
	v_mfma_f32_16x16x32_bf16 v[0:3], v[174:177], v[206:209], v[0:3]
	v_mfma_f32_16x16x32_bf16 v[52:55], v[170:173], v[186:189], v[52:55]
	v_mfma_f32_16x16x32_bf16 v[48:51], v[178:181], v[186:189], v[48:51]
	v_mfma_f32_16x16x32_bf16 v[36:39], v[170:173], v[194:197], v[36:39]
	v_mfma_f32_16x16x32_bf16 v[32:35], v[178:181], v[194:197], v[32:35]
	v_mfma_f32_16x16x32_bf16 v[20:23], v[170:173], v[202:205], v[20:23]
	v_mfma_f32_16x16x32_bf16 v[16:19], v[178:181], v[202:205], v[16:19]
	v_mfma_f32_16x16x32_bf16 v[4:7], v[170:173], v[210:213], v[4:7]
	v_mfma_f32_16x16x32_bf16 v[0:3], v[178:181], v[210:213], v[0:3]
	s_setprio 0
	s_barrier
	s_add_u32 s30, s30, 0x100
	s_addc_u32 s31, s31, 0
	s_add_u32 s42, s42, 0x100
	s_addc_u32 s43, s43, 0
	s_cmp_ge_u32 s52, s9
	s_mov_b32 s34, s52
	s_cbranch_scc0 .LBB0_506
	s_and_b64 vcc, exec, s[12:13]
	s_cbranch_vccz .LBB0_509

; #define PG8_STAGE(bufoff, gbase, voff) do { _Pragma("unroll") for (int _i = 0; _i < 2; ++_i) \
;         __builtin_amdgcn_global_load_lds((const unsigned*)((const char*)(gbase) + (voff)[_i]), (LAS unsigned*)(lds + (bufoff) + ldsw + _i * 8192), 16, 0, 0); } while (0)
; #define PG8_LDA(dst, b, h) do { _Pragma("unroll") for (int m = 0; m < 4; ++m) _Pragma("unroll") for (int k = 0; k < 2; ++k) dst[m][k] = *(const LAS bf16x8*)(lds + PG8_SA(b, h) + aoff + m * 2048 + k * KOFF); } while (0)
; #define PG8_LDB(dst, b, h) do { _Pragma("unroll") for (int n = 0; n < 2; ++n) _Pragma("unroll") for (int k = 0; k < 2; ++k) dst[n][k] = *(const LAS bf16x8*)(lds + PG8_SB(b, h) + boff + n * 2048 + k * KOFF); } while (0)
; #define PG8_WAIT_V(n) asm volatile("s_waitcnt vmcnt(" #n ")" ::: "memory")
; #define PG8_WAIT_L(n) asm volatile("s_waitcnt lgkmcnt(" #n ")" ::: "memory")
; template <class Epi, bool ALIGN_EPI = true, bool FP8 = false>
; __device__ __forceinline__ void gemm_phase(LAS unsigned char* lds, const Gemm g, const StaticOrder& S, const Epi& E, const int wid) {
;     ...
;             const char* a1 = cA + (size_t)(t + 1) * kstep;
;             const char* a2 = last ? nA : cA + (size_t)(t + 2) * kstep; const char* b2 = last ? nB : cB + (size_t)(t + 2) * kstep;
;             const char* a3 = a2 + kstep; const char* b3 = b2 + kstep;
;             PG8_LDB(B0, 0, 0); PG8_LDB(B1, 0, 1); PG8_SCHED; PG8_LDA(At, 0, 0); PG8_STAGE(PG8_SA(1, 1), a1 + hstep, voffA);
;             PG8_WAIT_V(8); PG8_WAIT_L(0); PG8_BAR; PG8_MMA(0, 0, At, B0); PG8_MMA(0, 1, At, B1); PG8_BAR; PG8_SCHED;
;             PG8_LDA(At, 0, 1); PG8_STAGE(PG8_SB(0, 0), b2, voffB); PG8_STAGE(PG8_SB(0, 1), b2 + hstep, voffB); PG8_STAGE(PG8_SA(0, 0), a2, voffA);
;             PG8_WAIT_V(8); PG8_WAIT_L(0); PG8_BAR; PG8_MMA(1, 0, At, B0); PG8_MMA(1, 1, At, B1); PG8_BAR; PG8_SCHED;
;             PG8_LDB(B0, 1, 0); PG8_LDB(B1, 1, 1); PG8_SCHED; PG8_LDA(At, 1, 0); PG8_STAGE(PG8_SA(0, 1), a2 + hstep, voffA);
;             PG8_WAIT_V(8); PG8_WAIT_L(0); PG8_BAR; PG8_MMA(0, 0, At, B0); PG8_MMA(0, 1, At, B1); PG8_BAR; PG8_SCHED;
;             PG8_LDA(At, 1, 1); PG8_STAGE(PG8_SB(1, 0), b3, voffB); PG8_STAGE(PG8_SB(1, 1), b3 + hstep, voffB); PG8_STAGE(PG8_SA(1, 0), a3, voffA);
;             PG8_WAIT_V(8); PG8_WAIT_L(0); PG8_BAR; PG8_MMA(1, 0, At, B0); PG8_MMA(1, 1, At, B1); PG8_BAR; PG8_SCHED;
.LBB0_572:
	ds_read_b128 v[152:155], v190
	ds_read_b128 v[156:159], v190 offset:1024
	ds_read_b128 v[144:147], v190 offset:2048
	ds_read_b128 v[148:151], v190 offset:3072
	ds_read_b128 v[136:139], v191
	ds_read_b128 v[140:143], v191 offset:1024
	ds_read_b128 v[128:131], v191 offset:2048
	ds_read_b128 v[132:135], v191 offset:3072
	s_add_i32 s3, s34, 2
	s_add_u32 s35, s30, 0xfffc0080
	s_addc_u32 s36, s31, -1
	s_cmp_eq_u32 s86, s34
	s_cselect_b32 s34, s85, s87
	s_cselect_b32 s37, s21, s36
	s_cselect_b32 s36, s23, s35
	s_cselect_b32 s35, s84, s88
	v_lshl_add_u64 v[220:221], s[30:31], 0, v[170:171]
	s_add_i32 m0, s27, 0xc000
	ds_read_b128 v[178:181], v192
	ds_read_b128 v[182:185], v192 offset:1024
	ds_read_b128 v[196:199], v192 offset:2048
	ds_read_b128 v[200:203], v192 offset:3072
	ds_read_b128 v[204:207], v192 offset:4096
	ds_read_b128 v[208:211], v192 offset:5120
	ds_read_b128 v[212:215], v192 offset:6144
	ds_read_b128 v[216:219], v192 offset:7168
	global_load_lds_dwordx4 v[220:221], off
	v_lshl_add_u64 v[220:221], s[30:31], 0, v[172:173]
	s_add_i32 m0, s27, 0xe000
	s_nop 0
	global_load_lds_dwordx4 v[220:221], off
	s_waitcnt vmcnt(8)
	s_waitcnt lgkmcnt(0)
	s_barrier
	s_setprio 1
	s_waitcnt lgkmcnt(0)
	v_mfma_f32_16x16x128_f8f6f4 v[120:123], v[152:159], v[178:185], v[120:123]
	v_mfma_f32_16x16x128_f8f6f4 v[124:127], v[144:151], v[178:185], v[124:127]
	v_mfma_f32_16x16x128_f8f6f4 v[112:115], v[152:159], v[196:203], v[112:115]
	v_mfma_f32_16x16x128_f8f6f4 v[116:119], v[144:151], v[196:203], v[116:119]
	v_mfma_f32_16x16x128_f8f6f4 v[104:107], v[152:159], v[204:211], v[104:107]
	v_mfma_f32_16x16x128_f8f6f4 v[108:111], v[144:151], v[204:211], v[108:111]
	v_mfma_f32_16x16x128_f8f6f4 v[88:91], v[152:159], v[212:219], v[88:91]
	v_mfma_f32_16x16x128_f8f6f4 v[92:95], v[144:151], v[212:219], v[92:95]
	s_setprio 0
	s_setprio 1
	v_mfma_f32_16x16x128_f8f6f4 v[96:99], v[136:143], v[178:185], v[96:99]
	v_mfma_f32_16x16x128_f8f6f4 v[100:103], v[128:135], v[178:185], v[100:103]
	v_mfma_f32_16x16x128_f8f6f4 v[80:83], v[136:143], v[196:203], v[80:83]
	v_mfma_f32_16x16x128_f8f6f4 v[84:87], v[128:135], v[196:203], v[84:87]
	v_mfma_f32_16x16x128_f8f6f4 v[72:75], v[136:143], v[204:211], v[72:75]
	v_mfma_f32_16x16x128_f8f6f4 v[76:79], v[128:135], v[204:211], v[76:79]
	v_mfma_f32_16x16x128_f8f6f4 v[64:67], v[136:143], v[212:219], v[64:67]
	v_mfma_f32_16x16x128_f8f6f4 v[68:71], v[128:135], v[212:219], v[68:71]
	s_setprio 0
	s_barrier
	s_add_i32 s42, s75, s48
	v_lshl_add_u64 v[178:179], s[34:35], 0, v[164:165]
	s_mov_b32 m0, s42
	ds_read_b128 v[196:199], v192 offset:16384
	ds_read_b128 v[200:203], v192 offset:17408
	ds_read_b128 v[204:207], v192 offset:18432
	ds_read_b128 v[208:211], v192 offset:19456
	ds_read_b128 v[212:215], v192 offset:20480
	ds_read_b128 v[216:219], v192 offset:21504
	ds_read_b128 v[220:223], v192 offset:22528
	ds_read_b128 v[224:227], v192 offset:23552
	global_load_lds_dwordx4 v[178:179], off
	s_add_i32 m0, s42, 0x2000
	s_add_u32 s42, s34, 0x40000
	v_lshl_add_u64 v[180:181], s[34:35], 0, v[160:161]
	s_addc_u32 s43, s35, 0
	s_add_i32 s52, s76, s48
	global_load_lds_dwordx4 v[180:181], off
	v_lshl_add_u64 v[182:183], s[42:43], 0, v[164:165]
	s_mov_b32 m0, s52
	v_lshl_add_u64 v[184:185], s[36:37], 0, v[162:163]
	global_load_lds_dwordx4 v[182:183], off
	v_lshl_add_u64 v[182:183], s[42:43], 0, v[160:161]
	s_add_i32 m0, s52, 0x2000
	s_nop 0
	global_load_lds_dwordx4 v[182:183], off
	v_lshl_add_u64 v[182:183], s[36:37], 0, v[166:167]
	s_mov_b32 m0, s27
	s_nop 0
	global_load_lds_dwordx4 v[182:183], off
	s_mov_b32 m0, s55
	s_nop 0
	global_load_lds_dwordx4 v[184:185], off
	s_waitcnt vmcnt(8)
	s_waitcnt lgkmcnt(0)
	s_barrier
	s_setprio 1
	s_waitcnt lgkmcnt(0)
	v_mfma_f32_16x16x128_f8f6f4 v[56:59], v[152:159], v[196:203], v[56:59]
	v_mfma_f32_16x16x128_f8f6f4 v[60:63], v[144:151], v[196:203], v[60:63]
	v_mfma_f32_16x16x128_f8f6f4 v[48:51], v[152:159], v[204:211], v[48:51]
	v_mfma_f32_16x16x128_f8f6f4 v[52:55], v[144:151], v[204:211], v[52:55]
	v_mfma_f32_16x16x128_f8f6f4 v[40:43], v[152:159], v[212:219], v[40:43]
	v_mfma_f32_16x16x128_f8f6f4 v[44:47], v[144:151], v[212:219], v[44:47]
	v_mfma_f32_16x16x128_f8f6f4 v[228:231], v[152:159], v[220:227], v[24:27]
	v_mfma_f32_16x16x128_f8f6f4 v[232:235], v[144:151], v[220:227], v[28:31]
	s_setprio 0
	s_setprio 1
	v_mfma_f32_16x16x128_f8f6f4 v[236:239], v[136:143], v[196:203], v[32:35]
	v_mfma_f32_16x16x128_f8f6f4 v[240:243], v[128:135], v[196:203], v[36:39]
	v_mfma_f32_16x16x128_f8f6f4 v[244:247], v[136:143], v[204:211], v[16:19]
	v_mfma_f32_16x16x128_f8f6f4 v[204:207], v[128:135], v[204:211], v[20:23]
	v_mfma_f32_16x16x128_f8f6f4 v[208:211], v[136:143], v[212:219], v[8:11]
	v_mfma_f32_16x16x128_f8f6f4 v[212:215], v[128:135], v[212:219], v[12:15]
	v_mfma_f32_16x16x128_f8f6f4 v[216:219], v[136:143], v[220:227], v[0:3]
	v_mfma_f32_16x16x128_f8f6f4 v[220:223], v[128:135], v[220:227], v[4:7]
	s_setprio 0
	s_barrier
	s_add_i32 s42, 0, 0x18000
	s_add_i32 s43, 0, 0x1c000
	s_nop 0
	v_add_u32_e32 v12, s42, v187
	v_add_u32_e32 v16, s43, v187
	ds_read_b128 v[0:3], v12
	ds_read_b128 v[4:7], v12 offset:1024
	ds_read_b128 v[8:11], v12 offset:2048
	ds_read_b128 v[12:15], v12 offset:3072
	ds_read_b128 v[128:131], v16
	ds_read_b128 v[132:135], v16 offset:1024
	ds_read_b128 v[136:139], v16 offset:2048
	ds_read_b128 v[140:143], v16 offset:3072
	s_add_u32 s36, s36, 0x40000
	s_addc_u32 s37, s37, 0
	s_mov_b32 m0, s64
	v_lshl_add_u64 v[152:153], s[36:37], 0, v[166:167]
	ds_read_b128 v[16:19], v192 offset:32768
	ds_read_b128 v[20:23], v192 offset:33792
	ds_read_b128 v[24:27], v192 offset:34816
	ds_read_b128 v[28:31], v192 offset:35840
	ds_read_b128 v[32:35], v192 offset:36864
	ds_read_b128 v[36:39], v192 offset:37888
	ds_read_b128 v[144:147], v192 offset:38912
	ds_read_b128 v[148:151], v192 offset:39936
	global_load_lds_dwordx4 v[152:153], off
	v_lshl_add_u64 v[152:153], s[36:37], 0, v[162:163]
	s_mov_b32 m0, s65
	s_nop 0
	global_load_lds_dwordx4 v[152:153], off
	s_waitcnt vmcnt(8)
	s_waitcnt lgkmcnt(0)
	s_barrier
; #define PG8_STAGE(bufoff, gbase, voff) do { _Pragma("unroll") for (int _i = 0; _i < 2; ++_i) \
;         __builtin_amdgcn_global_load_lds((const unsigned*)((const char*)(gbase) + (voff)[_i]), (LAS unsigned*)(lds + (bufoff) + ldsw + _i * 8192), 16, 0, 0); } while (0)
; #define PG8_LDA(dst, b, h) do { _Pragma("unroll") for (int m = 0; m < 4; ++m) _Pragma("unroll") for (int k = 0; k < 2; ++k) dst[m][k] = *(const LAS bf16x8*)(lds + PG8_SA(b, h) + aoff + m * 2048 + k * KOFF); } while (0)
; #define PG8_LDB(dst, b, h) do { _Pragma("unroll") for (int n = 0; n < 2; ++n) _Pragma("unroll") for (int k = 0; k < 2; ++k) dst[n][k] = *(const LAS bf16x8*)(lds + PG8_SB(b, h) + boff + n * 2048 + k * KOFF); } while (0)
; #define PG8_WAIT_V(n) asm volatile("s_waitcnt vmcnt(" #n ")" ::: "memory")
; #define PG8_WAIT_L(n) asm volatile("s_waitcnt lgkmcnt(" #n ")" ::: "memory")
; template <class Epi, bool ALIGN_EPI = true, bool FP8 = false>
; __device__ __forceinline__ void gemm_phase(LAS unsigned char* lds, const Gemm g, const StaticOrder& S, const Epi& E, const int wid) {
;     ...
;             const char* a1 = cA + (size_t)(t + 1) * kstep;
;             const char* a2 = last ? nA : cA + (size_t)(t + 2) * kstep; const char* b2 = last ? nB : cB + (size_t)(t + 2) * kstep;
;             const char* a3 = a2 + kstep; const char* b3 = b2 + kstep;
;             PG8_LDB(B0, 0, 0); PG8_LDB(B1, 0, 1); PG8_SCHED; PG8_LDA(At, 0, 0); PG8_STAGE(PG8_SA(1, 1), a1 + hstep, voffA);
;             PG8_WAIT_V(8); PG8_WAIT_L(0); PG8_BAR; PG8_MMA(0, 0, At, B0); PG8_MMA(0, 1, At, B1); PG8_BAR; PG8_SCHED;
;             PG8_LDA(At, 0, 1); PG8_STAGE(PG8_SB(0, 0), b2, voffB); PG8_STAGE(PG8_SB(0, 1), b2 + hstep, voffB); PG8_STAGE(PG8_SA(0, 0), a2, voffA);
;             PG8_WAIT_V(8); PG8_WAIT_L(0); PG8_BAR; PG8_MMA(1, 0, At, B0); PG8_MMA(1, 1, At, B1); PG8_BAR; PG8_SCHED;
;             PG8_LDB(B0, 1, 0); PG8_LDB(B1, 1, 1); PG8_SCHED; PG8_LDA(At, 1, 0); PG8_STAGE(PG8_SA(0, 1), a2 + hstep, voffA);
;             PG8_WAIT_V(8); PG8_WAIT_L(0); PG8_BAR; PG8_MMA(0, 0, At, B0); PG8_MMA(0, 1, At, B1); PG8_BAR; PG8_SCHED;
;             PG8_LDA(At, 1, 1); PG8_STAGE(PG8_SB(1, 0), b3, voffB); PG8_STAGE(PG8_SB(1, 1), b3 + hstep, voffB); PG8_STAGE(PG8_SA(1, 0), a3, voffA);
;             PG8_WAIT_V(8); PG8_WAIT_L(0); PG8_BAR; PG8_MMA(1, 0, At, B0); PG8_MMA(1, 1, At, B1); PG8_BAR; PG8_SCHED;
;         }
	s_setprio 1
	s_waitcnt lgkmcnt(0)
	v_mfma_f32_16x16x128_f8f6f4 v[120:123], v[0:7], v[16:23], v[120:123]
	v_mfma_f32_16x16x128_f8f6f4 v[124:127], v[8:15], v[16:23], v[124:127]
	v_mfma_f32_16x16x128_f8f6f4 v[112:115], v[0:7], v[24:31], v[112:115]
	v_mfma_f32_16x16x128_f8f6f4 v[116:119], v[8:15], v[24:31], v[116:119]
	v_mfma_f32_16x16x128_f8f6f4 v[104:107], v[0:7], v[32:39], v[104:107]
	v_mfma_f32_16x16x128_f8f6f4 v[108:111], v[8:15], v[32:39], v[108:111]
	v_mfma_f32_16x16x128_f8f6f4 v[88:91], v[0:7], v[144:151], v[88:91]
	v_mfma_f32_16x16x128_f8f6f4 v[92:95], v[8:15], v[144:151], v[92:95]
	s_setprio 0
	s_setprio 1
	v_mfma_f32_16x16x128_f8f6f4 v[96:99], v[128:135], v[16:23], v[96:99]
	v_mfma_f32_16x16x128_f8f6f4 v[100:103], v[136:143], v[16:23], v[100:103]
	v_mfma_f32_16x16x128_f8f6f4 v[80:83], v[128:135], v[24:31], v[80:83]
	v_mfma_f32_16x16x128_f8f6f4 v[84:87], v[136:143], v[24:31], v[84:87]
	v_mfma_f32_16x16x128_f8f6f4 v[72:75], v[128:135], v[32:39], v[72:75]
	v_mfma_f32_16x16x128_f8f6f4 v[76:79], v[136:143], v[32:39], v[76:79]
	v_mfma_f32_16x16x128_f8f6f4 v[64:67], v[128:135], v[144:151], v[64:67]
	v_mfma_f32_16x16x128_f8f6f4 v[68:71], v[136:143], v[144:151], v[68:71]
	s_setprio 0
	s_barrier
	s_add_i32 s36, s42, s48
	v_lshl_add_u64 v[24:25], v[178:179], 0, s[8:9]
	s_mov_b32 m0, s36
	ds_read_b128 v[16:19], v192 offset:49152
	ds_read_b128 v[20:23], v192 offset:50176
	ds_read_b128 v[144:147], v192 offset:51200
	ds_read_b128 v[148:151], v192 offset:52224
	ds_read_b128 v[152:155], v192 offset:53248
	ds_read_b128 v[156:159], v192 offset:54272
	ds_read_b128 v[196:199], v192 offset:55296
	ds_read_b128 v[200:203], v192 offset:56320
	global_load_lds_dwordx4 v[24:25], off
	s_add_i32 m0, s36, 0x2000
	s_add_u32 s34, s34, 0x40080
	v_lshl_add_u64 v[24:25], v[180:181], 0, s[8:9]
	s_addc_u32 s35, s35, 0
	s_add_i32 s36, s43, s48
	global_load_lds_dwordx4 v[24:25], off
	v_lshl_add_u64 v[24:25], s[34:35], 0, v[164:165]
	s_mov_b32 m0, s36
	s_nop 0
	global_load_lds_dwordx4 v[24:25], off
	v_lshl_add_u64 v[24:25], s[34:35], 0, v[160:161]
	s_add_i32 m0, s36, 0x2000
	s_nop 0
	global_load_lds_dwordx4 v[24:25], off
	v_lshl_add_u64 v[24:25], v[182:183], 0, s[8:9]
	s_mov_b32 m0, s70
	s_nop 0
	global_load_lds_dwordx4 v[24:25], off
	v_lshl_add_u64 v[24:25], v[184:185], 0, s[8:9]
	s_mov_b32 m0, s71
	s_nop 0
	global_load_lds_dwordx4 v[24:25], off
	s_waitcnt vmcnt(8)
	s_waitcnt lgkmcnt(0)
	s_barrier
	s_setprio 1
	s_waitcnt lgkmcnt(0)
	v_mfma_f32_16x16x128_f8f6f4 v[56:59], v[0:7], v[16:23], v[56:59]
	v_mfma_f32_16x16x128_f8f6f4 v[60:63], v[8:15], v[16:23], v[60:63]
	v_mfma_f32_16x16x128_f8f6f4 v[48:51], v[0:7], v[144:151], v[48:51]
	v_mfma_f32_16x16x128_f8f6f4 v[52:55], v[8:15], v[144:151], v[52:55]
	v_mfma_f32_16x16x128_f8f6f4 v[40:43], v[0:7], v[152:159], v[40:43]
	v_mfma_f32_16x16x128_f8f6f4 v[44:47], v[8:15], v[152:159], v[44:47]
	v_mfma_f32_16x16x128_f8f6f4 v[24:27], v[0:7], v[196:203], v[228:231]
	v_mfma_f32_16x16x128_f8f6f4 v[28:31], v[8:15], v[196:203], v[232:235]
	s_setprio 0
	s_setprio 1
	v_mfma_f32_16x16x128_f8f6f4 v[32:35], v[128:135], v[16:23], v[236:239]
	v_mfma_f32_16x16x128_f8f6f4 v[36:39], v[136:143], v[16:23], v[240:243]
	v_mfma_f32_16x16x128_f8f6f4 v[16:19], v[128:135], v[144:151], v[244:247]
	v_mfma_f32_16x16x128_f8f6f4 v[20:23], v[136:143], v[144:151], v[204:207]
	v_mfma_f32_16x16x128_f8f6f4 v[8:11], v[128:135], v[152:159], v[208:211]
	v_mfma_f32_16x16x128_f8f6f4 v[12:15], v[136:143], v[152:159], v[212:215]
	v_mfma_f32_16x16x128_f8f6f4 v[0:3], v[128:135], v[196:203], v[216:219]
	v_mfma_f32_16x16x128_f8f6f4 v[4:7], v[136:143], v[196:203], v[220:223]
	s_setprio 0
	s_barrier
	s_add_u32 s30, s30, 0x100
	s_addc_u32 s31, s31, 0
	s_add_u32 s87, s87, 0x100
	s_addc_u32 s88, s88, 0
	s_cmp_ge_u32 s3, s83
	s_mov_b32 s34, s3
	s_cbranch_scc0 .LBB0_572
;     __device__ __forceinline__ void operator()(const Acc& acc, const Unit& u, int wr, int wc, int fr, int fq) const {
;     ...
;                         const f32x4 v0 = acc[ai][bj][m][0] * QS, v1 = acc[ai][bj][m][1] * QS;
; template <class Epi, bool ALIGN_EPI = true, bool FP8 = false>
; __device__ __forceinline__ void gemm_phase(LAS unsigned char* lds, const Gemm g, const StaticOrder& S, const Epi& E, const int wid) {
;     ...
;         if constexpr (FP8) {
; #pragma unroll
;             for (int a = 0; a < 2; ++a)
; #pragma unroll
;                 for (int b = 0; b < 2; ++b)
; #pragma unroll
;                     for (int m = 0; m < 4; ++m) { const f32x8 c_ = acc8[a][b][m]; acc[a][b][m][0] = __builtin_shufflevector(c_, c_, 0, 1, 2, 3); acc[a][b][m][1] = __builtin_shufflevector(c_, c_, 4, 5, 6, 7); }
	v_pk_mul_f32 v[122:123], v[122:123], s[14:15] op_sel_hi:[1,0]
	v_pk_mul_f32 v[128:129], v[120:121], s[14:15] op_sel_hi:[1,0]
	v_pk_mul_f32 v[120:121], v[126:127], s[14:15] op_sel_hi:[1,0]
	v_pk_mul_f32 v[124:125], v[124:125], s[14:15] op_sel_hi:[1,0]
	v_pk_mul_f32 v[132:133], v[98:99], s[14:15] op_sel_hi:[1,0]
	v_pk_mul_f32 v[136:137], v[96:97], s[14:15] op_sel_hi:[1,0]
	v_pk_mul_f32 v[130:131], v[102:103], s[14:15] op_sel_hi:[1,0]
	v_pk_mul_f32 v[134:135], v[100:101], s[14:15] op_sel_hi:[1,0]
	v_pk_mul_f32 v[100:101], v[114:115], s[14:15] op_sel_hi:[1,0]
	v_pk_mul_f32 v[112:113], v[112:113], s[14:15] op_sel_hi:[1,0]
	v_pk_mul_f32 v[96:97], v[118:119], s[14:15] op_sel_hi:[1,0]
	v_pk_mul_f32 v[102:103], v[116:117], s[14:15] op_sel_hi:[1,0]
	v_pk_mul_f32 v[116:117], v[82:83], s[14:15] op_sel_hi:[1,0]
	v_pk_mul_f32 v[126:127], v[80:81], s[14:15] op_sel_hi:[1,0]
	v_pk_mul_f32 v[114:115], v[86:87], s[14:15] op_sel_hi:[1,0]
	v_pk_mul_f32 v[118:119], v[84:85], s[14:15] op_sel_hi:[1,0]
	v_pk_mul_f32 v[82:83], v[106:107], s[14:15] op_sel_hi:[1,0]
	v_pk_mul_f32 v[86:87], v[104:105], s[14:15] op_sel_hi:[1,0]
	v_pk_mul_f32 v[80:81], v[110:111], s[14:15] op_sel_hi:[1,0]
	v_pk_mul_f32 v[84:85], v[108:109], s[14:15] op_sel_hi:[1,0]
	v_pk_mul_f32 v[104:105], v[74:75], s[14:15] op_sel_hi:[1,0]
	v_pk_mul_f32 v[108:109], v[72:73], s[14:15] op_sel_hi:[1,0]
	v_pk_mul_f32 v[98:99], v[78:79], s[14:15] op_sel_hi:[1,0]
	v_pk_mul_f32 v[106:107], v[76:77], s[14:15] op_sel_hi:[1,0]
	v_pk_mul_f32 v[74:75], v[90:91], s[14:15] op_sel_hi:[1,0]
	v_pk_mul_f32 v[78:79], v[88:89], s[14:15] op_sel_hi:[1,0]
	v_pk_mul_f32 v[72:73], v[94:95], s[14:15] op_sel_hi:[1,0]
	v_pk_mul_f32 v[76:77], v[92:93], s[14:15] op_sel_hi:[1,0]
	v_pk_mul_f32 v[66:67], v[66:67], s[14:15] op_sel_hi:[1,0]
	v_pk_mul_f32 v[88:89], v[64:65], s[14:15] op_sel_hi:[1,0]
	v_pk_mul_f32 v[64:65], v[70:71], s[14:15] op_sel_hi:[1,0]
	v_pk_mul_f32 v[68:69], v[68:69], s[14:15] op_sel_hi:[1,0]
	v_pk_mul_f32 v[58:59], v[58:59], s[14:15] op_sel_hi:[1,0]
	v_pk_mul_f32 v[70:71], v[56:57], s[14:15] op_sel_hi:[1,0]
	v_pk_mul_f32 v[56:57], v[62:63], s[14:15] op_sel_hi:[1,0]
	v_pk_mul_f32 v[60:61], v[60:61], s[14:15] op_sel_hi:[1,0]
	v_pk_mul_f32 v[92:93], v[34:35], s[14:15] op_sel_hi:[1,0]
	v_pk_mul_f32 v[110:111], v[32:33], s[14:15] op_sel_hi:[1,0]
	v_pk_mul_f32 v[90:91], v[38:39], s[14:15] op_sel_hi:[1,0]
	v_pk_mul_f32 v[94:95], v[36:37], s[14:15] op_sel_hi:[1,0]
	v_pk_mul_f32 v[36:37], v[50:51], s[14:15] op_sel_hi:[1,0]
	v_pk_mul_f32 v[48:49], v[48:49], s[14:15] op_sel_hi:[1,0]
	v_pk_mul_f32 v[32:33], v[54:55], s[14:15] op_sel_hi:[1,0]
	v_pk_mul_f32 v[38:39], v[52:53], s[14:15] op_sel_hi:[1,0]
	v_pk_mul_f32 v[52:53], v[18:19], s[14:15] op_sel_hi:[1,0]
	v_pk_mul_f32 v[62:63], v[16:17], s[14:15] op_sel_hi:[1,0]
	v_pk_mul_f32 v[50:51], v[22:23], s[14:15] op_sel_hi:[1,0]
	v_pk_mul_f32 v[54:55], v[20:21], s[14:15] op_sel_hi:[1,0]
	v_pk_mul_f32 v[18:19], v[42:43], s[14:15] op_sel_hi:[1,0]
	v_pk_mul_f32 v[22:23], v[40:41], s[14:15] op_sel_hi:[1,0]
	v_pk_mul_f32 v[16:17], v[46:47], s[14:15] op_sel_hi:[1,0]
	v_pk_mul_f32 v[20:21], v[44:45], s[14:15] op_sel_hi:[1,0]
	v_pk_mul_f32 v[40:41], v[10:11], s[14:15] op_sel_hi:[1,0]
	v_pk_mul_f32 v[44:45], v[8:9], s[14:15] op_sel_hi:[1,0]
	v_pk_mul_f32 v[34:35], v[14:15], s[14:15] op_sel_hi:[1,0]
	v_pk_mul_f32 v[42:43], v[12:13], s[14:15] op_sel_hi:[1,0]
	v_pk_mul_f32 v[10:11], v[26:27], s[14:15] op_sel_hi:[1,0]
	v_pk_mul_f32 v[14:15], v[24:25], s[14:15] op_sel_hi:[1,0]
	v_pk_mul_f32 v[8:9], v[30:31], s[14:15] op_sel_hi:[1,0]
	v_pk_mul_f32 v[12:13], v[28:29], s[14:15] op_sel_hi:[1,0]
	v_pk_mul_f32 v[2:3], v[2:3], s[14:15] op_sel_hi:[1,0]
	v_pk_mul_f32 v[24:25], v[0:1], s[14:15] op_sel_hi:[1,0]
	v_pk_mul_f32 v[0:1], v[6:7], s[14:15] op_sel_hi:[1,0]
	v_pk_mul_f32 v[4:5], v[4:5], s[14:15] op_sel_hi:[1,0]
	s_and_b64 vcc, exec, s[12:13]
	s_cbranch_vccz .LBB0_575

; #define PG8_STAGE(bufoff, gbase, voff) do { _Pragma("unroll") for (int _i = 0; _i < 2; ++_i) \
;         __builtin_amdgcn_global_load_lds((const unsigned*)((const char*)(gbase) + (voff)[_i]), (LAS unsigned*)(lds + (bufoff) + ldsw + _i * 8192), 16, 0, 0); } while (0)
; #define PG8_LDA(dst, b, h) do { _Pragma("unroll") for (int m = 0; m < 4; ++m) _Pragma("unroll") for (int k = 0; k < 2; ++k) dst[m][k] = *(const LAS bf16x8*)(lds + PG8_SA(b, h) + aoff + m * 2048 + k * KOFF); } while (0)
; #define PG8_LDB(dst, b, h) do { _Pragma("unroll") for (int n = 0; n < 2; ++n) _Pragma("unroll") for (int k = 0; k < 2; ++k) dst[n][k] = *(const LAS bf16x8*)(lds + PG8_SB(b, h) + boff + n * 2048 + k * KOFF); } while (0)
; #define PG8_WAIT_V(n) asm volatile("s_waitcnt vmcnt(" #n ")" ::: "memory")
; #define PG8_WAIT_L(n) asm volatile("s_waitcnt lgkmcnt(" #n ")" ::: "memory")
; template <class Epi, bool ALIGN_EPI = true, bool FP8 = false>
; __device__ __forceinline__ void gemm_phase(LAS unsigned char* lds, const Gemm g, const StaticOrder& S, const Epi& E, const int wid) {
;     ...
;             const char* a1 = cA + (size_t)(t + 1) * kstep;
;             const char* a2 = last ? nA : cA + (size_t)(t + 2) * kstep; const char* b2 = last ? nB : cB + (size_t)(t + 2) * kstep;
;             const char* a3 = a2 + kstep; const char* b3 = b2 + kstep;
;             PG8_LDB(B0, 0, 0); PG8_LDB(B1, 0, 1); PG8_SCHED; PG8_LDA(At, 0, 0); PG8_STAGE(PG8_SA(1, 1), a1 + hstep, voffA);
;             PG8_WAIT_V(8); PG8_WAIT_L(0); PG8_BAR; PG8_MMA(0, 0, At, B0); PG8_MMA(0, 1, At, B1); PG8_BAR; PG8_SCHED;
;             PG8_LDA(At, 0, 1); PG8_STAGE(PG8_SB(0, 0), b2, voffB); PG8_STAGE(PG8_SB(0, 1), b2 + hstep, voffB); PG8_STAGE(PG8_SA(0, 0), a2, voffA);
;             PG8_WAIT_V(8); PG8_WAIT_L(0); PG8_BAR; PG8_MMA(1, 0, At, B0); PG8_MMA(1, 1, At, B1); PG8_BAR; PG8_SCHED;
;             PG8_LDB(B0, 1, 0); PG8_LDB(B1, 1, 1); PG8_SCHED; PG8_LDA(At, 1, 0); PG8_STAGE(PG8_SA(0, 1), a2 + hstep, voffA);
;             PG8_WAIT_V(8); PG8_WAIT_L(0); PG8_BAR; PG8_MMA(0, 0, At, B0); PG8_MMA(0, 1, At, B1); PG8_BAR; PG8_SCHED;
;             PG8_LDA(At, 1, 1); PG8_STAGE(PG8_SB(1, 0), b3, voffB); PG8_STAGE(PG8_SB(1, 1), b3 + hstep, voffB); PG8_STAGE(PG8_SA(1, 0), a3, voffA);
;             PG8_WAIT_V(8); PG8_WAIT_L(0); PG8_BAR; PG8_MMA(1, 0, At, B0); PG8_MMA(1, 1, At, B1); PG8_BAR; PG8_SCHED;
.LBB0_2058:
	v_add_u32_e32 v128, s83, v192
	v_add_u32_e32 v132, s84, v192
	ds_read_b128 v[152:155], v128
	ds_read_b128 v[156:159], v128 offset:1024
	ds_read_b128 v[144:147], v128 offset:2048
	ds_read_b128 v[148:151], v128 offset:3072
	ds_read_b128 v[136:139], v132
	ds_read_b128 v[140:143], v132 offset:1024
	ds_read_b128 v[128:131], v132 offset:2048
	ds_read_b128 v[132:135], v132 offset:3072
	s_add_i32 s3, s42, 2
	s_add_u32 s43, s64, 0xfffe0080
	s_addc_u32 s52, s65, -1
	s_cmp_eq_u32 s35, s42
	s_cselect_b32 s69, s11, s52
	s_cselect_b32 s68, s16, s43
	s_cselect_b32 s67, s29, s90
	s_cselect_b32 s66, s31, s89
	v_lshl_add_u64 v[188:189], s[64:65], 0, v[174:175]
	s_add_i32 m0, s72, 0xc000
	ds_read_b128 v[180:183], v193
	ds_read_b128 v[184:187], v193 offset:1024
	ds_read_b128 v[196:199], v193 offset:2048
	ds_read_b128 v[200:203], v193 offset:3072
	ds_read_b128 v[204:207], v193 offset:4096
	ds_read_b128 v[208:211], v193 offset:5120
	ds_read_b128 v[212:215], v193 offset:6144
	ds_read_b128 v[216:219], v193 offset:7168
	global_load_lds_dwordx4 v[188:189], off
	v_lshl_add_u64 v[188:189], s[64:65], 0, v[176:177]
	s_add_i32 m0, s72, 0xe000
	s_nop 0
	global_load_lds_dwordx4 v[188:189], off
	s_waitcnt vmcnt(8)
	s_waitcnt lgkmcnt(0)
	s_barrier
	s_setprio 1
	s_waitcnt lgkmcnt(0)
	v_mfma_f32_16x16x128_f8f6f4 v[120:123], v[152:159], v[180:187], v[120:123]
	v_mfma_f32_16x16x128_f8f6f4 v[124:127], v[144:151], v[180:187], v[124:127]
	v_mfma_f32_16x16x128_f8f6f4 v[112:115], v[152:159], v[196:203], v[112:115]
	v_mfma_f32_16x16x128_f8f6f4 v[116:119], v[144:151], v[196:203], v[116:119]
	v_mfma_f32_16x16x128_f8f6f4 v[104:107], v[152:159], v[204:211], v[104:107]
	v_mfma_f32_16x16x128_f8f6f4 v[108:111], v[144:151], v[204:211], v[108:111]
	v_mfma_f32_16x16x128_f8f6f4 v[96:99], v[152:159], v[212:219], v[96:99]
	v_mfma_f32_16x16x128_f8f6f4 v[100:103], v[144:151], v[212:219], v[100:103]
	s_setprio 0
	s_setprio 1
	v_mfma_f32_16x16x128_f8f6f4 v[88:91], v[136:143], v[180:187], v[88:91]
	v_mfma_f32_16x16x128_f8f6f4 v[92:95], v[128:135], v[180:187], v[92:95]
	v_mfma_f32_16x16x128_f8f6f4 v[80:83], v[136:143], v[196:203], v[80:83]
	v_mfma_f32_16x16x128_f8f6f4 v[84:87], v[128:135], v[196:203], v[84:87]
	v_mfma_f32_16x16x128_f8f6f4 v[72:75], v[136:143], v[204:211], v[72:75]
	v_mfma_f32_16x16x128_f8f6f4 v[76:79], v[128:135], v[204:211], v[76:79]
	v_mfma_f32_16x16x128_f8f6f4 v[64:67], v[136:143], v[212:219], v[64:67]
	v_mfma_f32_16x16x128_f8f6f4 v[68:71], v[128:135], v[212:219], v[68:71]
	s_setprio 0
	s_barrier
	s_add_i32 s42, s83, s71
	v_lshl_add_u64 v[180:181], s[66:67], 0, v[162:163]
	s_mov_b32 m0, s42
	ds_read_b128 v[196:199], v193 offset:16384
	ds_read_b128 v[200:203], v193 offset:17408
	ds_read_b128 v[204:207], v193 offset:18432
	ds_read_b128 v[208:211], v193 offset:19456
	ds_read_b128 v[212:215], v193 offset:20480
	ds_read_b128 v[216:219], v193 offset:21504
	ds_read_b128 v[220:223], v193 offset:22528
	ds_read_b128 v[224:227], v193 offset:23552
	global_load_lds_dwordx4 v[180:181], off
	s_add_i32 m0, s42, 0x2000
	s_add_u32 s42, s66, 0x20000
	v_lshl_add_u64 v[182:183], s[66:67], 0, v[166:167]
	s_addc_u32 s43, s67, 0
	s_add_i32 s52, s84, s71
	global_load_lds_dwordx4 v[182:183], off
	v_lshl_add_u64 v[184:185], s[42:43], 0, v[162:163]
	s_mov_b32 m0, s52
	v_lshl_add_u64 v[186:187], s[68:69], 0, v[164:165]
	global_load_lds_dwordx4 v[184:185], off
	v_lshl_add_u64 v[184:185], s[42:43], 0, v[166:167]
	s_add_i32 m0, s52, 0x2000
	s_nop 0
	global_load_lds_dwordx4 v[184:185], off
	v_lshl_add_u64 v[184:185], s[68:69], 0, v[160:161]
	s_mov_b32 m0, s72
	s_nop 0
	global_load_lds_dwordx4 v[184:185], off
	s_mov_b32 m0, s73
	s_nop 0
	global_load_lds_dwordx4 v[186:187], off
	s_waitcnt vmcnt(8)
	s_waitcnt lgkmcnt(0)
	s_barrier
	s_setprio 1
	s_waitcnt lgkmcnt(0)
	v_mfma_f32_16x16x128_f8f6f4 v[56:59], v[152:159], v[196:203], v[56:59]
	v_mfma_f32_16x16x128_f8f6f4 v[60:63], v[144:151], v[196:203], v[60:63]
	v_mfma_f32_16x16x128_f8f6f4 v[48:51], v[152:159], v[204:211], v[48:51]
	v_mfma_f32_16x16x128_f8f6f4 v[52:55], v[144:151], v[204:211], v[52:55]
	v_mfma_f32_16x16x128_f8f6f4 v[40:43], v[152:159], v[212:219], v[40:43]
	v_mfma_f32_16x16x128_f8f6f4 v[44:47], v[144:151], v[212:219], v[44:47]
	v_mfma_f32_16x16x128_f8f6f4 v[188:191], v[152:159], v[220:227], v[32:35]
	v_mfma_f32_16x16x128_f8f6f4 v[228:231], v[144:151], v[220:227], v[36:39]
	s_setprio 0
	s_setprio 1
	v_mfma_f32_16x16x128_f8f6f4 v[232:235], v[136:143], v[196:203], v[24:27]
	v_mfma_f32_16x16x128_f8f6f4 v[236:239], v[128:135], v[196:203], v[28:31]
	v_mfma_f32_16x16x128_f8f6f4 v[240:243], v[136:143], v[204:211], v[16:19]
	v_mfma_f32_16x16x128_f8f6f4 v[204:207], v[128:135], v[204:211], v[20:23]
	v_mfma_f32_16x16x128_f8f6f4 v[208:211], v[136:143], v[212:219], v[8:11]
	v_mfma_f32_16x16x128_f8f6f4 v[212:215], v[128:135], v[212:219], v[12:15]
	v_mfma_f32_16x16x128_f8f6f4 v[216:219], v[136:143], v[220:227], v[0:3]
	v_mfma_f32_16x16x128_f8f6f4 v[220:223], v[128:135], v[220:227], v[4:7]
	s_setprio 0
	s_barrier
; #define PG8_STAGE(bufoff, gbase, voff) do { _Pragma("unroll") for (int _i = 0; _i < 2; ++_i) \
;         __builtin_amdgcn_global_load_lds((const unsigned*)((const char*)(gbase) + (voff)[_i]), (LAS unsigned*)(lds + (bufoff) + ldsw + _i * 8192), 16, 0, 0); } while (0)
; #define PG8_LDA(dst, b, h) do { _Pragma("unroll") for (int m = 0; m < 4; ++m) _Pragma("unroll") for (int k = 0; k < 2; ++k) dst[m][k] = *(const LAS bf16x8*)(lds + PG8_SA(b, h) + aoff + m * 2048 + k * KOFF); } while (0)
; #define PG8_LDB(dst, b, h) do { _Pragma("unroll") for (int n = 0; n < 2; ++n) _Pragma("unroll") for (int k = 0; k < 2; ++k) dst[n][k] = *(const LAS bf16x8*)(lds + PG8_SB(b, h) + boff + n * 2048 + k * KOFF); } while (0)
; #define PG8_WAIT_V(n) asm volatile("s_waitcnt vmcnt(" #n ")" ::: "memory")
; #define PG8_WAIT_L(n) asm volatile("s_waitcnt lgkmcnt(" #n ")" ::: "memory")
; #define PG8_BAR __builtin_amdgcn_s_barrier()
; #define PG8_SCHED __builtin_amdgcn_sched_barrier(0)
; template <class Epi, bool ALIGN_EPI = true, bool FP8 = false>
; __device__ __forceinline__ void gemm_phase(LAS unsigned char* lds, const Gemm g, const StaticOrder& S, const Epi& E, const int wid) {
;     ...
;             PG8_WAIT_V(8); PG8_WAIT_L(0); PG8_BAR; PG8_MMA(1, 0, At, B0); PG8_MMA(1, 1, At, B1); PG8_BAR; PG8_SCHED;
;             PG8_LDB(B0, 1, 0); PG8_LDB(B1, 1, 1); PG8_SCHED; PG8_LDA(At, 1, 0); PG8_STAGE(PG8_SA(0, 1), a2 + hstep, voffA);
;             PG8_WAIT_V(8); PG8_WAIT_L(0); PG8_BAR; PG8_MMA(0, 0, At, B0); PG8_MMA(0, 1, At, B1); PG8_BAR; PG8_SCHED;
;             PG8_LDA(At, 1, 1); PG8_STAGE(PG8_SB(1, 0), b3, voffB); PG8_STAGE(PG8_SB(1, 1), b3 + hstep, voffB); PG8_STAGE(PG8_SA(1, 0), a3, voffA);
;             PG8_WAIT_V(8); PG8_WAIT_L(0); PG8_BAR; PG8_MMA(1, 0, At, B0); PG8_MMA(1, 1, At, B1); PG8_BAR; PG8_SCHED;
;         }
;         if constexpr (ALIGN_EPI) { if (wr == 0) PG8_BAR; }
	s_add_i32 s52, 0, 0x18000
	s_add_i32 s54, 0, 0x1c000
	s_nop 0
	v_add_u32_e32 v12, s52, v192
	v_add_u32_e32 v16, s54, v192
	ds_read_b128 v[0:3], v12
	ds_read_b128 v[4:7], v12 offset:1024
	ds_read_b128 v[8:11], v12 offset:2048
	ds_read_b128 v[12:15], v12 offset:3072
	ds_read_b128 v[128:131], v16
	ds_read_b128 v[132:135], v16 offset:1024
	ds_read_b128 v[136:139], v16 offset:2048
	ds_read_b128 v[140:143], v16 offset:3072
	s_add_u32 s42, s68, 0x20000
	s_addc_u32 s43, s69, 0
	s_mov_b32 m0, s74
	v_lshl_add_u64 v[152:153], s[42:43], 0, v[160:161]
	ds_read_b128 v[16:19], v193 offset:32768
	ds_read_b128 v[20:23], v193 offset:33792
	ds_read_b128 v[24:27], v193 offset:34816
	ds_read_b128 v[28:31], v193 offset:35840
	ds_read_b128 v[32:35], v193 offset:36864
	ds_read_b128 v[36:39], v193 offset:37888
	ds_read_b128 v[144:147], v193 offset:38912
	ds_read_b128 v[148:151], v193 offset:39936
	global_load_lds_dwordx4 v[152:153], off
	v_lshl_add_u64 v[152:153], s[42:43], 0, v[164:165]
	s_mov_b32 m0, s75
	s_nop 0
	global_load_lds_dwordx4 v[152:153], off
	s_waitcnt vmcnt(8)
	s_waitcnt lgkmcnt(0)
	s_barrier
	s_setprio 1
	s_waitcnt lgkmcnt(0)
	v_mfma_f32_16x16x128_f8f6f4 v[120:123], v[0:7], v[16:23], v[120:123]
	v_mfma_f32_16x16x128_f8f6f4 v[124:127], v[8:15], v[16:23], v[124:127]
	v_mfma_f32_16x16x128_f8f6f4 v[112:115], v[0:7], v[24:31], v[112:115]
	v_mfma_f32_16x16x128_f8f6f4 v[116:119], v[8:15], v[24:31], v[116:119]
	v_mfma_f32_16x16x128_f8f6f4 v[104:107], v[0:7], v[32:39], v[104:107]
	v_mfma_f32_16x16x128_f8f6f4 v[108:111], v[8:15], v[32:39], v[108:111]
	v_mfma_f32_16x16x128_f8f6f4 v[96:99], v[0:7], v[144:151], v[96:99]
	v_mfma_f32_16x16x128_f8f6f4 v[100:103], v[8:15], v[144:151], v[100:103]
	s_setprio 0
	s_setprio 1
	v_mfma_f32_16x16x128_f8f6f4 v[88:91], v[128:135], v[16:23], v[88:91]
	v_mfma_f32_16x16x128_f8f6f4 v[92:95], v[136:143], v[16:23], v[92:95]
	v_mfma_f32_16x16x128_f8f6f4 v[80:83], v[128:135], v[24:31], v[80:83]
	v_mfma_f32_16x16x128_f8f6f4 v[84:87], v[136:143], v[24:31], v[84:87]
	v_mfma_f32_16x16x128_f8f6f4 v[72:75], v[128:135], v[32:39], v[72:75]
	v_mfma_f32_16x16x128_f8f6f4 v[76:79], v[136:143], v[32:39], v[76:79]
	v_mfma_f32_16x16x128_f8f6f4 v[64:67], v[128:135], v[144:151], v[64:67]
	v_mfma_f32_16x16x128_f8f6f4 v[68:71], v[136:143], v[144:151], v[68:71]
	s_setprio 0
	s_barrier
	s_add_i32 s42, s52, s71
	v_lshl_add_u64 v[24:25], v[180:181], 0, s[20:21]
	s_mov_b32 m0, s42
	ds_read_b128 v[16:19], v193 offset:49152
	ds_read_b128 v[20:23], v193 offset:50176
	ds_read_b128 v[144:147], v193 offset:51200
	ds_read_b128 v[148:151], v193 offset:52224
	ds_read_b128 v[152:155], v193 offset:53248
	ds_read_b128 v[156:159], v193 offset:54272
	ds_read_b128 v[196:199], v193 offset:55296
	ds_read_b128 v[200:203], v193 offset:56320
	global_load_lds_dwordx4 v[24:25], off
	s_add_i32 m0, s42, 0x2000
	s_add_u32 s42, s66, 0x20080
	v_lshl_add_u64 v[24:25], v[182:183], 0, s[20:21]
	s_addc_u32 s43, s67, 0
	s_add_i32 s52, s54, s71
	global_load_lds_dwordx4 v[24:25], off
	v_lshl_add_u64 v[24:25], s[42:43], 0, v[162:163]
	s_mov_b32 m0, s52
	s_nop 0
	global_load_lds_dwordx4 v[24:25], off
	v_lshl_add_u64 v[24:25], s[42:43], 0, v[166:167]
	s_add_i32 m0, s52, 0x2000
	s_nop 0
	global_load_lds_dwordx4 v[24:25], off
	v_lshl_add_u64 v[24:25], v[184:185], 0, s[20:21]
	s_mov_b32 m0, s80
	s_nop 0
	global_load_lds_dwordx4 v[24:25], off
	v_lshl_add_u64 v[24:25], v[186:187], 0, s[20:21]
	s_mov_b32 m0, s81
	s_nop 0
	global_load_lds_dwordx4 v[24:25], off
	s_waitcnt vmcnt(8)
	s_waitcnt lgkmcnt(0)
	s_barrier
	s_setprio 1
	s_waitcnt lgkmcnt(0)
	v_mfma_f32_16x16x128_f8f6f4 v[56:59], v[0:7], v[16:23], v[56:59]
	v_mfma_f32_16x16x128_f8f6f4 v[60:63], v[8:15], v[16:23], v[60:63]
	v_mfma_f32_16x16x128_f8f6f4 v[48:51], v[0:7], v[144:151], v[48:51]
	v_mfma_f32_16x16x128_f8f6f4 v[52:55], v[8:15], v[144:151], v[52:55]
	v_mfma_f32_16x16x128_f8f6f4 v[40:43], v[0:7], v[152:159], v[40:43]
	v_mfma_f32_16x16x128_f8f6f4 v[44:47], v[8:15], v[152:159], v[44:47]
	v_mfma_f32_16x16x128_f8f6f4 v[32:35], v[0:7], v[196:203], v[188:191]
	v_mfma_f32_16x16x128_f8f6f4 v[36:39], v[8:15], v[196:203], v[228:231]
	s_setprio 0
	s_setprio 1
	v_mfma_f32_16x16x128_f8f6f4 v[24:27], v[128:135], v[16:23], v[232:235]
	v_mfma_f32_16x16x128_f8f6f4 v[28:31], v[136:143], v[16:23], v[236:239]
	v_mfma_f32_16x16x128_f8f6f4 v[16:19], v[128:135], v[144:151], v[240:243]
	v_mfma_f32_16x16x128_f8f6f4 v[20:23], v[136:143], v[144:151], v[204:207]
	v_mfma_f32_16x16x128_f8f6f4 v[8:11], v[128:135], v[152:159], v[208:211]
	v_mfma_f32_16x16x128_f8f6f4 v[12:15], v[136:143], v[152:159], v[212:215]
	v_mfma_f32_16x16x128_f8f6f4 v[0:3], v[128:135], v[196:203], v[216:219]
	v_mfma_f32_16x16x128_f8f6f4 v[4:7], v[136:143], v[196:203], v[220:223]
	s_setprio 0
	s_barrier
	s_add_u32 s64, s64, 0x100
	s_addc_u32 s65, s65, 0
	s_add_u32 s89, s89, 0x100
	s_addc_u32 s90, s90, 0
	s_cmp_ge_u32 s3, s9
	s_mov_b32 s42, s3
	s_cbranch_scc0 .LBB0_2058
	s_and_b64 vcc, exec, s[22:23]
	s_cbranch_vccz .LBB0_2061
	s_barrier

; #define PG8_STAGE(bufoff, gbase, voff) do { _Pragma("unroll") for (int _i = 0; _i < 2; ++_i) \
;         __builtin_amdgcn_global_load_lds((const unsigned*)((const char*)(gbase) + (voff)[_i]), (LAS unsigned*)(lds + (bufoff) + ldsw + _i * 8192), 16, 0, 0); } while (0)
; #define PG8_LDA(dst, b, h) do { _Pragma("unroll") for (int m = 0; m < 4; ++m) _Pragma("unroll") for (int k = 0; k < 2; ++k) dst[m][k] = *(const LAS bf16x8*)(lds + PG8_SA(b, h) + aoff + m * 2048 + k * KOFF); } while (0)
; #define PG8_LDB(dst, b, h) do { _Pragma("unroll") for (int n = 0; n < 2; ++n) _Pragma("unroll") for (int k = 0; k < 2; ++k) dst[n][k] = *(const LAS bf16x8*)(lds + PG8_SB(b, h) + boff + n * 2048 + k * KOFF); } while (0)
; #define PG8_WAIT_V(n) asm volatile("s_waitcnt vmcnt(" #n ")" ::: "memory")
; #define PG8_WAIT_L(n) asm volatile("s_waitcnt lgkmcnt(" #n ")" ::: "memory")
; template <class Epi, bool ALIGN_EPI = true, bool FP8 = false>
; __device__ __forceinline__ void gemm_phase(LAS unsigned char* lds, const Gemm g, const StaticOrder& S, const Epi& E, const int wid) {
;     ...
;             const char* a1 = cA + (size_t)(t + 1) * kstep;
;             const char* a2 = last ? nA : cA + (size_t)(t + 2) * kstep; const char* b2 = last ? nB : cB + (size_t)(t + 2) * kstep;
;             const char* a3 = a2 + kstep; const char* b3 = b2 + kstep;
;             PG8_LDB(B0, 0, 0); PG8_LDB(B1, 0, 1); PG8_SCHED; PG8_LDA(At, 0, 0); PG8_STAGE(PG8_SA(1, 1), a1 + hstep, voffA);
;             PG8_WAIT_V(8); PG8_WAIT_L(0); PG8_BAR; PG8_MMA(0, 0, At, B0); PG8_MMA(0, 1, At, B1); PG8_BAR; PG8_SCHED;
;             PG8_LDA(At, 0, 1); PG8_STAGE(PG8_SB(0, 0), b2, voffB); PG8_STAGE(PG8_SB(0, 1), b2 + hstep, voffB); PG8_STAGE(PG8_SA(0, 0), a2, voffA);
;             PG8_WAIT_V(8); PG8_WAIT_L(0); PG8_BAR; PG8_MMA(1, 0, At, B0); PG8_MMA(1, 1, At, B1); PG8_BAR; PG8_SCHED;
;             PG8_LDB(B0, 1, 0); PG8_LDB(B1, 1, 1); PG8_SCHED; PG8_LDA(At, 1, 0); PG8_STAGE(PG8_SA(0, 1), a2 + hstep, voffA);
;             PG8_WAIT_V(8); PG8_WAIT_L(0); PG8_BAR; PG8_MMA(0, 0, At, B0); PG8_MMA(0, 1, At, B1); PG8_BAR; PG8_SCHED;
;             PG8_LDA(At, 1, 1); PG8_STAGE(PG8_SB(1, 0), b3, voffB); PG8_STAGE(PG8_SB(1, 1), b3 + hstep, voffB); PG8_STAGE(PG8_SA(1, 0), a3, voffA);
;             PG8_WAIT_V(8); PG8_WAIT_L(0); PG8_BAR; PG8_MMA(1, 0, At, B0); PG8_MMA(1, 1, At, B1); PG8_BAR; PG8_SCHED;
.LBB0_2290:
	ds_read_b128 v[152:155], v218
	ds_read_b128 v[156:159], v218 offset:1024
	ds_read_b128 v[144:147], v218 offset:2048
	ds_read_b128 v[148:151], v218 offset:3072
	ds_read_b128 v[136:139], v219
	ds_read_b128 v[140:143], v219 offset:1024
	ds_read_b128 v[128:131], v219 offset:2048
	ds_read_b128 v[132:135], v219 offset:3072
	s_add_i32 s3, s38, 2
	s_add_u32 s36, s34, 0xfffc0080
	s_addc_u32 s37, s35, -1
	s_cmp_eq_u32 s88, s38
	s_cselect_b32 s38, s31, s36
	s_cselect_b32 s39, s21, s37
	s_cselect_b32 s37, s19, s90
	s_cselect_b32 s36, s87, s89
	v_lshl_add_u64 v[212:213], s[34:35], 0, v[198:199]
	s_add_i32 m0, s27, 0xc000
	ds_read_b128 v[160:163], v220
	ds_read_b128 v[164:167], v220 offset:1024
	ds_read_b128 v[168:171], v220 offset:2048
	ds_read_b128 v[172:175], v220 offset:3072
	ds_read_b128 v[176:179], v220 offset:4096
	ds_read_b128 v[180:183], v220 offset:5120
	ds_read_b128 v[204:207], v220 offset:6144
	ds_read_b128 v[208:211], v220 offset:7168
	global_load_lds_dwordx4 v[212:213], off
	v_lshl_add_u64 v[212:213], s[34:35], 0, v[200:201]
	s_add_i32 m0, s27, 0xe000
	s_nop 0
	global_load_lds_dwordx4 v[212:213], off
	s_waitcnt vmcnt(8)
	s_waitcnt lgkmcnt(0)
	s_barrier
	s_setprio 1
	s_waitcnt lgkmcnt(0)
	v_mfma_f32_16x16x128_f8f6f4 v[120:123], v[152:159], v[160:167], v[120:123]
	v_mfma_f32_16x16x128_f8f6f4 v[124:127], v[144:151], v[160:167], v[124:127]
	v_mfma_f32_16x16x128_f8f6f4 v[104:107], v[152:159], v[168:175], v[104:107]
	v_mfma_f32_16x16x128_f8f6f4 v[108:111], v[144:151], v[168:175], v[108:111]
	v_mfma_f32_16x16x128_f8f6f4 v[96:99], v[152:159], v[176:183], v[96:99]
	v_mfma_f32_16x16x128_f8f6f4 v[100:103], v[144:151], v[176:183], v[100:103]
	v_mfma_f32_16x16x128_f8f6f4 v[80:83], v[152:159], v[204:211], v[80:83]
	v_mfma_f32_16x16x128_f8f6f4 v[84:87], v[144:151], v[204:211], v[84:87]
	s_setprio 0
	s_setprio 1
	v_mfma_f32_16x16x128_f8f6f4 v[112:115], v[136:143], v[160:167], v[112:115]
	v_mfma_f32_16x16x128_f8f6f4 v[116:119], v[128:135], v[160:167], v[116:119]
	v_mfma_f32_16x16x128_f8f6f4 v[88:91], v[136:143], v[168:175], v[88:91]
	v_mfma_f32_16x16x128_f8f6f4 v[92:95], v[128:135], v[168:175], v[92:95]
	v_mfma_f32_16x16x128_f8f6f4 v[72:75], v[136:143], v[176:183], v[72:75]
	v_mfma_f32_16x16x128_f8f6f4 v[76:79], v[128:135], v[176:183], v[76:79]
	v_mfma_f32_16x16x128_f8f6f4 v[64:67], v[136:143], v[204:211], v[64:67]
	v_mfma_f32_16x16x128_f8f6f4 v[68:71], v[128:135], v[204:211], v[68:71]
	s_setprio 0
	s_barrier
	s_add_i32 s42, s75, s53
	v_lshl_add_u64 v[160:161], s[36:37], 0, v[188:189]
	s_mov_b32 m0, s42
	ds_read_b128 v[168:171], v220 offset:16384
	ds_read_b128 v[172:175], v220 offset:17408
	ds_read_b128 v[176:179], v220 offset:18432
	ds_read_b128 v[180:183], v220 offset:19456
	ds_read_b128 v[204:207], v220 offset:20480
	ds_read_b128 v[208:211], v220 offset:21504
	ds_read_b128 v[222:225], v220 offset:22528
	ds_read_b128 v[226:229], v220 offset:23552
	global_load_lds_dwordx4 v[160:161], off
	s_add_i32 m0, s42, 0x2000
	s_add_u32 s42, s36, 0x40000
	v_lshl_add_u64 v[162:163], s[36:37], 0, v[184:185]
	s_addc_u32 s43, s37, 0
	s_add_i32 s52, s76, s53
	global_load_lds_dwordx4 v[162:163], off
	v_lshl_add_u64 v[164:165], s[42:43], 0, v[188:189]
	s_mov_b32 m0, s52
	v_lshl_add_u64 v[166:167], s[38:39], 0, v[186:187]
	global_load_lds_dwordx4 v[164:165], off
	v_lshl_add_u64 v[164:165], s[42:43], 0, v[184:185]
	s_add_i32 m0, s52, 0x2000
	s_nop 0
	global_load_lds_dwordx4 v[164:165], off
	v_lshl_add_u64 v[164:165], s[38:39], 0, v[190:191]
	s_mov_b32 m0, s27
	s_nop 0
	global_load_lds_dwordx4 v[164:165], off
	s_mov_b32 m0, s55
	s_nop 0
	global_load_lds_dwordx4 v[166:167], off
	s_waitcnt vmcnt(8)
	s_waitcnt lgkmcnt(0)
	s_barrier
	s_setprio 1
	s_waitcnt lgkmcnt(0)
	v_mfma_f32_16x16x128_f8f6f4 v[56:59], v[152:159], v[168:175], v[56:59]
	v_mfma_f32_16x16x128_f8f6f4 v[60:63], v[144:151], v[168:175], v[60:63]
	v_mfma_f32_16x16x128_f8f6f4 v[48:51], v[152:159], v[176:183], v[48:51]
	v_mfma_f32_16x16x128_f8f6f4 v[52:55], v[144:151], v[176:183], v[52:55]
	v_mfma_f32_16x16x128_f8f6f4 v[32:35], v[152:159], v[204:211], v[32:35]
	v_mfma_f32_16x16x128_f8f6f4 v[212:215], v[144:151], v[204:211], v[36:39]
	v_mfma_f32_16x16x128_f8f6f4 v[230:233], v[152:159], v[222:229], v[16:19]
	v_mfma_f32_16x16x128_f8f6f4 v[234:237], v[144:151], v[222:229], v[20:23]
	s_setprio 0
	s_setprio 1
	v_mfma_f32_16x16x128_f8f6f4 v[44:47], v[128:135], v[168:175], v[44:47]
	v_mfma_f32_16x16x128_f8f6f4 v[238:241], v[136:143], v[168:175], v[40:43]
	v_mfma_f32_16x16x128_f8f6f4 v[242:245], v[136:143], v[176:183], v[24:27]
	v_mfma_f32_16x16x128_f8f6f4 v[176:179], v[128:135], v[176:183], v[28:31]
	v_mfma_f32_16x16x128_f8f6f4 v[180:183], v[136:143], v[204:211], v[8:11]
	v_mfma_f32_16x16x128_f8f6f4 v[204:207], v[128:135], v[204:211], v[12:15]
	v_mfma_f32_16x16x128_f8f6f4 v[208:211], v[136:143], v[222:229], v[0:3]
	v_mfma_f32_16x16x128_f8f6f4 v[222:225], v[128:135], v[222:229], v[4:7]
	s_setprio 0
	s_barrier
	s_add_i32 s42, 0, 0x18000
	s_add_i32 s43, 0, 0x1c000
	s_nop 0
	v_add_u32_e32 v12, s42, v217
	v_add_u32_e32 v16, s43, v217
	ds_read_b128 v[0:3], v12
	ds_read_b128 v[4:7], v12 offset:1024
	ds_read_b128 v[8:11], v12 offset:2048
	ds_read_b128 v[12:15], v12 offset:3072
	ds_read_b128 v[128:131], v16
	ds_read_b128 v[132:135], v16 offset:1024
	ds_read_b128 v[136:139], v16 offset:2048
	ds_read_b128 v[140:143], v16 offset:3072
	s_add_u32 s38, s38, 0x40000
	s_addc_u32 s39, s39, 0
	s_mov_b32 m0, s64
	v_lshl_add_u64 v[152:153], s[38:39], 0, v[190:191]
	ds_read_b128 v[16:19], v220 offset:32768
	ds_read_b128 v[20:23], v220 offset:33792
	ds_read_b128 v[24:27], v220 offset:34816
	ds_read_b128 v[28:31], v220 offset:35840
	ds_read_b128 v[36:39], v220 offset:36864
	ds_read_b128 v[40:43], v220 offset:37888
	ds_read_b128 v[144:147], v220 offset:38912
	ds_read_b128 v[148:151], v220 offset:39936
	global_load_lds_dwordx4 v[152:153], off
	v_lshl_add_u64 v[152:153], s[38:39], 0, v[186:187]
	s_mov_b32 m0, s65
	s_nop 0
	global_load_lds_dwordx4 v[152:153], off
	s_waitcnt vmcnt(8)
	s_waitcnt lgkmcnt(0)
	s_barrier
; #define GAS __attribute__((address_space(1)))
; #define PG8_STAGE(bufoff, gbase, voff) do { _Pragma("unroll") for (int _i = 0; _i < 2; ++_i) \
;         __builtin_amdgcn_global_load_lds((const unsigned*)((const char*)(gbase) + (voff)[_i]), (LAS unsigned*)(lds + (bufoff) + ldsw + _i * 8192), 16, 0, 0); } while (0)
; #define PG8_BAR __builtin_amdgcn_s_barrier()
;     __device__ __forceinline__ void operator()(const Acc& acc, const Unit& u, int wr, int wc, int fr, int fq) const {
;     ...
;         if (u.part) {
;             const int ks = u.part - 1, rs0 = u.pm * 256 - MP;
;             char* sl_ = uni_ptr((char*)(slab + ((size_t)ks * MS + rs0) * DM + u.pn * 256));
;             asm volatile("" : "+s"(sl_));
;             GAS char* sl = (GAS char*)sl_;
;             const unsigned lo4 = (unsigned)((wr * 64 + fr) * DM + wc * 32 + 8 * fq) * 4u;
; #pragma unroll
;             for (int ai = 0; ai < 2; ++ai)
; #pragma unroll
;                 for (int m = 0; m < 4; ++m) {
;                     const int gi = NB_P + ((rs0 + ai * HALF + wr * 64) >> 5) + (m >> 1);
;                     const float* grow = gate + (size_t)gi * NADA + col0;
; #pragma unroll
;                     for (int bj = 0; bj < 2; ++bj)
; #pragma unroll
;                         for (int n = 0; n < 2; ++n) { const int co = bj * HALF + n * 4;
;                             *(GAS f32x4*)(sl + (unsigned)((ai * HALF + m * 16) * DM + co) * 4u + lo4) = *(const f32x4*)(grow + co) * acc[ai][bj][m][n] * (SRC_F32 ? 1.0f / (WOUT_SCALE * M_SCALE) : 1.0f / WDN_SCALE); }
;                 }
; template <class Epi, bool ALIGN_EPI = true, bool FP8 = false>
; __device__ __forceinline__ void gemm_phase(LAS unsigned char* lds, const Gemm g, const StaticOrder& S, const Epi& E, const int wid) {
;     ...
;             PG8_WAIT_V(8); PG8_WAIT_L(0); PG8_BAR; PG8_MMA(1, 0, At, B0); PG8_MMA(1, 1, At, B1); PG8_BAR; PG8_SCHED;
;             PG8_LDB(B0, 1, 0); PG8_LDB(B1, 1, 1); PG8_SCHED; PG8_LDA(At, 1, 0); PG8_STAGE(PG8_SA(0, 1), a2 + hstep, voffA);
;             PG8_WAIT_V(8); PG8_WAIT_L(0); PG8_BAR; PG8_MMA(0, 0, At, B0); PG8_MMA(0, 1, At, B1); PG8_BAR; PG8_SCHED;
;             PG8_LDA(At, 1, 1); PG8_STAGE(PG8_SB(1, 0), b3, voffB); PG8_STAGE(PG8_SB(1, 1), b3 + hstep, voffB); PG8_STAGE(PG8_SA(1, 0), a3, voffA);
;             PG8_WAIT_V(8); PG8_WAIT_L(0); PG8_BAR; PG8_MMA(1, 0, At, B0); PG8_MMA(1, 1, At, B1); PG8_BAR; PG8_SCHED;
;         }
	s_setprio 1
	s_waitcnt lgkmcnt(0)
	v_mfma_f32_16x16x128_f8f6f4 v[120:123], v[0:7], v[16:23], v[120:123]
	v_mfma_f32_16x16x128_f8f6f4 v[124:127], v[8:15], v[16:23], v[124:127]
	v_mfma_f32_16x16x128_f8f6f4 v[104:107], v[0:7], v[24:31], v[104:107]
	v_mfma_f32_16x16x128_f8f6f4 v[108:111], v[8:15], v[24:31], v[108:111]
	v_mfma_f32_16x16x128_f8f6f4 v[96:99], v[0:7], v[36:43], v[96:99]
	v_mfma_f32_16x16x128_f8f6f4 v[100:103], v[8:15], v[36:43], v[100:103]
	v_mfma_f32_16x16x128_f8f6f4 v[80:83], v[0:7], v[144:151], v[80:83]
	v_mfma_f32_16x16x128_f8f6f4 v[84:87], v[8:15], v[144:151], v[84:87]
	s_setprio 0
	s_setprio 1
	v_mfma_f32_16x16x128_f8f6f4 v[112:115], v[128:135], v[16:23], v[112:115]
	v_mfma_f32_16x16x128_f8f6f4 v[116:119], v[136:143], v[16:23], v[116:119]
	v_mfma_f32_16x16x128_f8f6f4 v[88:91], v[128:135], v[24:31], v[88:91]
	v_mfma_f32_16x16x128_f8f6f4 v[92:95], v[136:143], v[24:31], v[92:95]
	v_mfma_f32_16x16x128_f8f6f4 v[72:75], v[128:135], v[36:43], v[72:75]
	v_mfma_f32_16x16x128_f8f6f4 v[76:79], v[136:143], v[36:43], v[76:79]
	v_mfma_f32_16x16x128_f8f6f4 v[64:67], v[128:135], v[144:151], v[64:67]
	v_mfma_f32_16x16x128_f8f6f4 v[68:71], v[136:143], v[144:151], v[68:71]
	s_setprio 0
	s_barrier
	s_add_i32 s38, s42, s53
	v_lshl_add_u64 v[16:17], v[160:161], 0, s[14:15]
	s_mov_b32 m0, s38
	ds_read_b128 v[24:27], v220 offset:49152
	ds_read_b128 v[28:31], v220 offset:50176
	ds_read_b128 v[144:147], v220 offset:51200
	ds_read_b128 v[148:151], v220 offset:52224
	ds_read_b128 v[152:155], v220 offset:53248
	ds_read_b128 v[156:159], v220 offset:54272
	ds_read_b128 v[168:171], v220 offset:55296
	ds_read_b128 v[172:175], v220 offset:56320
	global_load_lds_dwordx4 v[16:17], off
	s_add_i32 m0, s38, 0x2000
	s_add_u32 s36, s36, 0x40080
	v_lshl_add_u64 v[16:17], v[162:163], 0, s[14:15]
	s_addc_u32 s37, s37, 0
	s_add_i32 s38, s43, s53
	global_load_lds_dwordx4 v[16:17], off
	v_lshl_add_u64 v[16:17], s[36:37], 0, v[188:189]
	s_mov_b32 m0, s38
	s_nop 0
	global_load_lds_dwordx4 v[16:17], off
	v_lshl_add_u64 v[16:17], s[36:37], 0, v[184:185]
	s_add_i32 m0, s38, 0x2000
	s_nop 0
	global_load_lds_dwordx4 v[16:17], off
	v_lshl_add_u64 v[16:17], v[164:165], 0, s[14:15]
	s_mov_b32 m0, s71
	s_nop 0
	global_load_lds_dwordx4 v[16:17], off
	v_lshl_add_u64 v[16:17], v[166:167], 0, s[14:15]
	s_mov_b32 m0, s72
	s_nop 0
	global_load_lds_dwordx4 v[16:17], off
	s_waitcnt vmcnt(8)
	s_waitcnt lgkmcnt(0)
	s_barrier
	s_setprio 1
	s_waitcnt lgkmcnt(0)
	v_mfma_f32_16x16x128_f8f6f4 v[56:59], v[0:7], v[24:31], v[56:59]
	v_mfma_f32_16x16x128_f8f6f4 v[60:63], v[8:15], v[24:31], v[60:63]
	v_mfma_f32_16x16x128_f8f6f4 v[48:51], v[0:7], v[144:151], v[48:51]
	v_mfma_f32_16x16x128_f8f6f4 v[52:55], v[8:15], v[144:151], v[52:55]
	v_mfma_f32_16x16x128_f8f6f4 v[32:35], v[0:7], v[152:159], v[32:35]
	v_mfma_f32_16x16x128_f8f6f4 v[36:39], v[8:15], v[152:159], v[212:215]
	v_mfma_f32_16x16x128_f8f6f4 v[16:19], v[0:7], v[168:175], v[230:233]
	v_mfma_f32_16x16x128_f8f6f4 v[20:23], v[8:15], v[168:175], v[234:237]
	s_setprio 0
	s_setprio 1
	v_mfma_f32_16x16x128_f8f6f4 v[40:43], v[128:135], v[24:31], v[238:241]
	v_mfma_f32_16x16x128_f8f6f4 v[44:47], v[136:143], v[24:31], v[44:47]
	v_mfma_f32_16x16x128_f8f6f4 v[24:27], v[128:135], v[144:151], v[242:245]
	v_mfma_f32_16x16x128_f8f6f4 v[28:31], v[136:143], v[144:151], v[176:179]
	v_mfma_f32_16x16x128_f8f6f4 v[8:11], v[128:135], v[152:159], v[180:183]
	v_mfma_f32_16x16x128_f8f6f4 v[12:15], v[136:143], v[152:159], v[204:207]
	v_mfma_f32_16x16x128_f8f6f4 v[0:3], v[128:135], v[168:175], v[208:211]
	v_mfma_f32_16x16x128_f8f6f4 v[4:7], v[136:143], v[168:175], v[222:225]
	s_setprio 0
	s_barrier
	s_add_u32 s34, s34, 0x100
	s_addc_u32 s35, s35, 0
	s_add_u32 s89, s89, 0x100
	s_addc_u32 s90, s90, 0
	s_cmp_ge_u32 s3, s29
	s_mov_b32 s38, s3
	s_cbranch_scc0 .LBB0_2290
	s_and_b64 vcc, exec, s[12:13]
	s_cbranch_vccz .LBB0_2293
	s_barrier
.LBB0_2293:
	s_lshl_b32 s28, s28, 8
	s_or_b32 s3, s28, s69
	v_add_u32_e32 v128, s3, v216
	s_cmp_eq_u32 s30, 0
	v_ashrrev_i32_e32 v129, 31, v128
	s_cbranch_scc1 .LBB0_2299
	s_lshl_b32 s3, s26, 8
	s_add_i32 s34, s3, 0xffff8000
	s_ashr_i32 s31, s30, 31
	s_lshl_b64 s[30:31], s[30:31], 22
	s_ashr_i32 s35, s34, 31
	s_add_u32 s3, s62, s30
	s_addc_u32 s19, s63, s31
	s_lshl_b64 s[30:31], s[34:35], 13
	s_add_u32 s3, s3, s30
	s_addc_u32 s19, s19, s31
	s_ashr_i32 s29, s28, 31
	s_lshl_b64 s[30:31], s[28:29], 2
	s_add_u32 s3, s3, s30
	s_addc_u32 s19, s19, s31
	s_add_u32 s30, s3, 0xffc00000
	s_addc_u32 s31, s19, -1
	s_add_i32 s3, s34, s68
	s_ashr_i32 s19, s3, 5
	s_mul_i32 s21, s19, 0xc000
	s_add_i32 s29, s19, 8
	s_add_i32 s34, s21, 0x60000
	s_mul_hi_i32 s29, s29, 0xc000
	s_add_u32 s34, s66, s34
	s_addc_u32 s35, s67, s29
	v_lshlrev_b64 v[132:133], 2, v[128:129]
	v_lshl_add_u64 v[138:139], s[34:35], 0, v[132:133]
	v_lshl_add_u64 v[130:131], s[30:31], 0, v[192:193]
	global_load_dwordx4 v[146:149], v[138:139], off
	global_load_dwordx4 v[150:153], v[138:139], off offset:16
	global_load_dwordx4 v[154:157], v[138:139], off offset:512
	global_load_dwordx4 v[158:161], v[138:139], off offset:528
	s_add_i32 s29, s19, 9
	s_add_i32 s30, s21, 0x6c000
	s_mul_hi_i32 s29, s29, 0xc000
	s_add_u32 s30, s66, s30
	s_addc_u32 s31, s67, s29
	v_lshl_add_u64 v[138:139], s[30:31], 0, v[132:133]
	global_load_dwordx4 v[162:165], v[138:139], off
	global_load_dwordx4 v[166:169], v[138:139], off offset:16
	global_load_dwordx4 v[170:173], v[138:139], off offset:512
	global_load_dwordx4 v[174:177], v[138:139], off offset:528
	s_addk_i32 s3, 0x80
	s_ashr_i32 s19, s3, 5
	s_mul_i32 s21, s19, 0xc000
	s_add_i32 s29, s19, 8
	s_add_i32 s30, s21, 0x60000
	s_mul_hi_i32 s29, s29, 0xc000
	s_add_u32 s30, s66, s30
	s_addc_u32 s31, s67, s29
	v_lshl_add_u64 v[138:139], s[30:31], 0, v[132:133]
	global_load_dwordx4 v[178:181], v[138:139], off
	global_load_dwordx4 v[204:207], v[138:139], off offset:16
	global_load_dwordx4 v[208:211], v[138:139], off offset:512
	global_load_dwordx4 v[212:215], v[138:139], off offset:528
	s_add_i32 s29, s19, 9
	s_add_i32 s30, s21, 0x6c000
	s_mul_hi_i32 s29, s29, 0xc000
	s_add_u32 s30, s66, s30
	s_addc_u32 s31, s67, s29
	v_lshl_add_u64 v[138:139], s[30:31], 0, v[132:133]
	global_load_dwordx4 v[222:225], v[138:139], off
	global_load_dwordx4 v[226:229], v[138:139], off offset:16
	global_load_dwordx4 v[230:233], v[138:139], off offset:512
	global_load_dwordx4 v[234:237], v[138:139], off offset:528
	s_waitcnt vmcnt(0)
; #define GAS __attribute__((address_space(1)))
;     __device__ __forceinline__ void operator()(const Acc& acc, const Unit& u, int wr, int wc, int fr, int fq) const {
;     ...
;             const unsigned lo4 = (unsigned)((wr * 64 + fr) * DM + wc * 32 + 8 * fq) * 4u;
; #pragma unroll
;             for (int ai = 0; ai < 2; ++ai)
; #pragma unroll
;                 for (int m = 0; m < 4; ++m) {
;                     const int gi = NB_P + ((rs0 + ai * HALF + wr * 64) >> 5) + (m >> 1);
;                     const float* grow = gate + (size_t)gi * NADA + col0;
; #pragma unroll
;                     for (int bj = 0; bj < 2; ++bj)
; #pragma unroll
;                         for (int n = 0; n < 2; ++n) { const int co = bj * HALF + n * 4;
;                             *(GAS f32x4*)(sl + (unsigned)((ai * HALF + m * 16) * DM + co) * 4u + lo4) = *(const f32x4*)(grow + co) * acc[ai][bj][m][n] * (SRC_F32 ? 1.0f / (WOUT_SCALE * M_SCALE) : 1.0f / WDN_SCALE); }
;                 }
	v_pk_mul_f32 v[136:137], v[122:123], v[148:149]
	v_pk_mul_f32 v[134:135], v[120:121], v[146:147]
	v_pk_mul_f32 v[136:137], v[136:137], s[16:17] op_sel_hi:[1,0]
	v_pk_mul_f32 v[134:135], v[134:135], s[16:17] op_sel_hi:[1,0]
	global_store_dwordx4 v[130:131], v[134:137], off
	v_pk_mul_f32 v[144:145], v[126:127], v[152:153]
	v_pk_mul_f32 v[142:143], v[124:125], v[150:151]
	v_pk_mul_f32 v[144:145], v[144:145], s[16:17] op_sel_hi:[1,0]
	v_pk_mul_f32 v[142:143], v[142:143], s[16:17] op_sel_hi:[1,0]
	global_store_dwordx4 v[130:131], v[142:145], off offset:16
	v_pk_mul_f32 v[136:137], v[114:115], v[156:157]
	v_pk_mul_f32 v[134:135], v[112:113], v[154:155]
	v_pk_mul_f32 v[136:137], v[136:137], s[16:17] op_sel_hi:[1,0]
	v_pk_mul_f32 v[134:135], v[134:135], s[16:17] op_sel_hi:[1,0]
	global_store_dwordx4 v[130:131], v[134:137], off offset:512
	v_pk_mul_f32 v[144:145], v[118:119], v[160:161]
	v_pk_mul_f32 v[142:143], v[116:117], v[158:159]
	v_pk_mul_f32 v[144:145], v[144:145], s[16:17] op_sel_hi:[1,0]
	v_pk_mul_f32 v[142:143], v[142:143], s[16:17] op_sel_hi:[1,0]
	global_store_dwordx4 v[130:131], v[142:145], off offset:528
	v_add_co_u32_e32 v140, vcc, s78, v130
	s_nop 1
	v_addc_co_u32_e32 v141, vcc, 0, v131, vcc
	v_pk_mul_f32 v[136:137], v[106:107], v[148:149]
	v_pk_mul_f32 v[134:135], v[104:105], v[146:147]
	v_pk_mul_f32 v[136:137], v[136:137], s[16:17] op_sel_hi:[1,0]
	v_pk_mul_f32 v[134:135], v[134:135], s[16:17] op_sel_hi:[1,0]
	global_store_dwordx4 v[140:141], v[134:137], off
	v_pk_mul_f32 v[144:145], v[110:111], v[152:153]
	v_pk_mul_f32 v[142:143], v[108:109], v[150:151]
	v_pk_mul_f32 v[144:145], v[144:145], s[16:17] op_sel_hi:[1,0]
	v_pk_mul_f32 v[142:143], v[142:143], s[16:17] op_sel_hi:[1,0]
	global_store_dwordx4 v[140:141], v[142:145], off offset:16
	v_pk_mul_f32 v[136:137], v[90:91], v[156:157]
	v_pk_mul_f32 v[134:135], v[88:89], v[154:155]
	v_pk_mul_f32 v[136:137], v[136:137], s[16:17] op_sel_hi:[1,0]
	v_pk_mul_f32 v[134:135], v[134:135], s[16:17] op_sel_hi:[1,0]
	global_store_dwordx4 v[140:141], v[134:137], off offset:512
	v_pk_mul_f32 v[144:145], v[94:95], v[160:161]
	v_pk_mul_f32 v[142:143], v[92:93], v[158:159]
	v_pk_mul_f32 v[144:145], v[144:145], s[16:17] op_sel_hi:[1,0]
	v_pk_mul_f32 v[142:143], v[142:143], s[16:17] op_sel_hi:[1,0]
	global_store_dwordx4 v[140:141], v[142:145], off offset:528
	v_add_co_u32_e32 v140, vcc, s79, v130
	s_nop 1
	v_addc_co_u32_e32 v141, vcc, 0, v131, vcc
	v_pk_mul_f32 v[136:137], v[98:99], v[164:165]
	v_pk_mul_f32 v[134:135], v[96:97], v[162:163]
	v_pk_mul_f32 v[136:137], v[136:137], s[16:17] op_sel_hi:[1,0]
	v_pk_mul_f32 v[134:135], v[134:135], s[16:17] op_sel_hi:[1,0]
	global_store_dwordx4 v[140:141], v[134:137], off
	v_pk_mul_f32 v[144:145], v[102:103], v[168:169]
	v_pk_mul_f32 v[142:143], v[100:101], v[166:167]
	v_pk_mul_f32 v[144:145], v[144:145], s[16:17] op_sel_hi:[1,0]
	v_pk_mul_f32 v[142:143], v[142:143], s[16:17] op_sel_hi:[1,0]
	global_store_dwordx4 v[140:141], v[142:145], off offset:16
	v_pk_mul_f32 v[136:137], v[74:75], v[172:173]
	v_pk_mul_f32 v[134:135], v[72:73], v[170:171]
	v_pk_mul_f32 v[136:137], v[136:137], s[16:17] op_sel_hi:[1,0]
	v_pk_mul_f32 v[134:135], v[134:135], s[16:17] op_sel_hi:[1,0]
	global_store_dwordx4 v[140:141], v[134:137], off offset:512
	v_pk_mul_f32 v[144:145], v[78:79], v[176:177]
	v_pk_mul_f32 v[142:143], v[76:77], v[174:175]
	v_pk_mul_f32 v[144:145], v[144:145], s[16:17] op_sel_hi:[1,0]
	v_pk_mul_f32 v[142:143], v[142:143], s[16:17] op_sel_hi:[1,0]
	global_store_dwordx4 v[140:141], v[142:145], off offset:528
	v_add_co_u32_e32 v140, vcc, s77, v130
	s_nop 1
	v_addc_co_u32_e32 v141, vcc, 0, v131, vcc
	v_pk_mul_f32 v[136:137], v[82:83], v[164:165]
	v_pk_mul_f32 v[134:135], v[80:81], v[162:163]
	v_pk_mul_f32 v[136:137], v[136:137], s[16:17] op_sel_hi:[1,0]
	v_pk_mul_f32 v[134:135], v[134:135], s[16:17] op_sel_hi:[1,0]
	global_store_dwordx4 v[140:141], v[134:137], off
	v_pk_mul_f32 v[144:145], v[86:87], v[168:169]
	v_pk_mul_f32 v[142:143], v[84:85], v[166:167]
	v_pk_mul_f32 v[144:145], v[144:145], s[16:17] op_sel_hi:[1,0]
	v_pk_mul_f32 v[142:143], v[142:143], s[16:17] op_sel_hi:[1,0]
	global_store_dwordx4 v[140:141], v[142:145], off offset:16
	v_pk_mul_f32 v[136:137], v[66:67], v[172:173]
	v_pk_mul_f32 v[134:135], v[64:65], v[170:171]
	v_pk_mul_f32 v[136:137], v[136:137], s[16:17] op_sel_hi:[1,0]
	v_pk_mul_f32 v[134:135], v[134:135], s[16:17] op_sel_hi:[1,0]
	global_store_dwordx4 v[140:141], v[134:137], off offset:512
	v_pk_mul_f32 v[144:145], v[70:71], v[176:177]
	v_pk_mul_f32 v[142:143], v[68:69], v[174:175]
	v_pk_mul_f32 v[144:145], v[144:145], s[16:17] op_sel_hi:[1,0]
	v_pk_mul_f32 v[142:143], v[142:143], s[16:17] op_sel_hi:[1,0]
	global_store_dwordx4 v[140:141], v[142:145], off offset:528
	v_add_co_u32_e32 v140, vcc, s80, v130
; #define GAS __attribute__((address_space(1)))
;     __device__ __forceinline__ void operator()(const Acc& acc, const Unit& u, int wr, int wc, int fr, int fq) const {
;     ...
;             const unsigned lo4 = (unsigned)((wr * 64 + fr) * DM + wc * 32 + 8 * fq) * 4u;
; #pragma unroll
;             for (int ai = 0; ai < 2; ++ai)
; #pragma unroll
;                 for (int m = 0; m < 4; ++m) {
;                     const int gi = NB_P + ((rs0 + ai * HALF + wr * 64) >> 5) + (m >> 1);
;                     const float* grow = gate + (size_t)gi * NADA + col0;
; #pragma unroll
;                     for (int bj = 0; bj < 2; ++bj)
; #pragma unroll
;                         for (int n = 0; n < 2; ++n) { const int co = bj * HALF + n * 4;
;                             *(GAS f32x4*)(sl + (unsigned)((ai * HALF + m * 16) * DM + co) * 4u + lo4) = *(const f32x4*)(grow + co) * acc[ai][bj][m][n] * (SRC_F32 ? 1.0f / (WOUT_SCALE * M_SCALE) : 1.0f / WDN_SCALE); }
;                 }
	s_nop 1
	v_addc_co_u32_e32 v141, vcc, 0, v131, vcc
	v_pk_mul_f32 v[136:137], v[58:59], v[180:181]
	v_pk_mul_f32 v[134:135], v[56:57], v[178:179]
	v_pk_mul_f32 v[136:137], v[136:137], s[16:17] op_sel_hi:[1,0]
	v_pk_mul_f32 v[134:135], v[134:135], s[16:17] op_sel_hi:[1,0]
	global_store_dwordx4 v[140:141], v[134:137], off
	v_pk_mul_f32 v[144:145], v[62:63], v[206:207]
	v_pk_mul_f32 v[142:143], v[60:61], v[204:205]
	v_pk_mul_f32 v[144:145], v[144:145], s[16:17] op_sel_hi:[1,0]
	v_pk_mul_f32 v[142:143], v[142:143], s[16:17] op_sel_hi:[1,0]
	global_store_dwordx4 v[140:141], v[142:145], off offset:16
	v_pk_mul_f32 v[136:137], v[42:43], v[210:211]
	v_pk_mul_f32 v[134:135], v[40:41], v[208:209]
	v_pk_mul_f32 v[136:137], v[136:137], s[16:17] op_sel_hi:[1,0]
	v_pk_mul_f32 v[134:135], v[134:135], s[16:17] op_sel_hi:[1,0]
	global_store_dwordx4 v[140:141], v[134:137], off offset:512
	v_pk_mul_f32 v[144:145], v[46:47], v[214:215]
	v_pk_mul_f32 v[142:143], v[44:45], v[212:213]
	v_pk_mul_f32 v[144:145], v[144:145], s[16:17] op_sel_hi:[1,0]
	v_pk_mul_f32 v[142:143], v[142:143], s[16:17] op_sel_hi:[1,0]
	global_store_dwordx4 v[140:141], v[142:145], off offset:528
	v_add_co_u32_e32 v140, vcc, s81, v130
	s_nop 1
	v_addc_co_u32_e32 v141, vcc, 0, v131, vcc
	v_pk_mul_f32 v[136:137], v[50:51], v[180:181]
	v_pk_mul_f32 v[134:135], v[48:49], v[178:179]
	v_pk_mul_f32 v[136:137], v[136:137], s[16:17] op_sel_hi:[1,0]
	v_pk_mul_f32 v[134:135], v[134:135], s[16:17] op_sel_hi:[1,0]
	global_store_dwordx4 v[140:141], v[134:137], off
	v_pk_mul_f32 v[144:145], v[54:55], v[206:207]
	v_pk_mul_f32 v[142:143], v[52:53], v[204:205]
	v_pk_mul_f32 v[144:145], v[144:145], s[16:17] op_sel_hi:[1,0]
	v_pk_mul_f32 v[142:143], v[142:143], s[16:17] op_sel_hi:[1,0]
	global_store_dwordx4 v[140:141], v[142:145], off offset:16
	v_pk_mul_f32 v[136:137], v[26:27], v[210:211]
	v_pk_mul_f32 v[134:135], v[24:25], v[208:209]
	v_pk_mul_f32 v[136:137], v[136:137], s[16:17] op_sel_hi:[1,0]
	v_pk_mul_f32 v[134:135], v[134:135], s[16:17] op_sel_hi:[1,0]
	global_store_dwordx4 v[140:141], v[134:137], off offset:512
	v_pk_mul_f32 v[144:145], v[30:31], v[214:215]
	v_pk_mul_f32 v[142:143], v[28:29], v[212:213]
	v_pk_mul_f32 v[144:145], v[144:145], s[16:17] op_sel_hi:[1,0]
	v_pk_mul_f32 v[142:143], v[142:143], s[16:17] op_sel_hi:[1,0]
	global_store_dwordx4 v[140:141], v[142:145], off offset:528
	v_add_co_u32_e32 v140, vcc, s82, v130
	s_nop 1
	v_addc_co_u32_e32 v141, vcc, 0, v131, vcc
	v_pk_mul_f32 v[136:137], v[34:35], v[224:225]
	v_pk_mul_f32 v[134:135], v[32:33], v[222:223]
	v_pk_mul_f32 v[136:137], v[136:137], s[16:17] op_sel_hi:[1,0]
	v_pk_mul_f32 v[134:135], v[134:135], s[16:17] op_sel_hi:[1,0]
	global_store_dwordx4 v[140:141], v[134:137], off
	v_pk_mul_f32 v[144:145], v[38:39], v[228:229]
	v_pk_mul_f32 v[142:143], v[36:37], v[226:227]
	v_pk_mul_f32 v[144:145], v[144:145], s[16:17] op_sel_hi:[1,0]
	v_pk_mul_f32 v[142:143], v[142:143], s[16:17] op_sel_hi:[1,0]
	global_store_dwordx4 v[140:141], v[142:145], off offset:16
	v_pk_mul_f32 v[136:137], v[10:11], v[232:233]
	v_pk_mul_f32 v[134:135], v[8:9], v[230:231]
	v_pk_mul_f32 v[136:137], v[136:137], s[16:17] op_sel_hi:[1,0]
	v_pk_mul_f32 v[134:135], v[134:135], s[16:17] op_sel_hi:[1,0]
	global_store_dwordx4 v[140:141], v[134:137], off offset:512
	v_pk_mul_f32 v[144:145], v[14:15], v[236:237]
	v_pk_mul_f32 v[142:143], v[12:13], v[234:235]
	v_pk_mul_f32 v[144:145], v[144:145], s[16:17] op_sel_hi:[1,0]
	v_pk_mul_f32 v[142:143], v[142:143], s[16:17] op_sel_hi:[1,0]
	global_store_dwordx4 v[140:141], v[142:145], off offset:528
	v_add_co_u32_e32 v140, vcc, s83, v130
	s_nop 1
	v_addc_co_u32_e32 v141, vcc, 0, v131, vcc
	v_pk_mul_f32 v[136:137], v[18:19], v[224:225]
	v_pk_mul_f32 v[134:135], v[16:17], v[222:223]
	v_pk_mul_f32 v[136:137], v[136:137], s[16:17] op_sel_hi:[1,0]
	v_pk_mul_f32 v[134:135], v[134:135], s[16:17] op_sel_hi:[1,0]
	global_store_dwordx4 v[140:141], v[134:137], off
	v_pk_mul_f32 v[144:145], v[22:23], v[228:229]
	v_pk_mul_f32 v[142:143], v[20:21], v[226:227]
	v_pk_mul_f32 v[144:145], v[144:145], s[16:17] op_sel_hi:[1,0]
	v_pk_mul_f32 v[142:143], v[142:143], s[16:17] op_sel_hi:[1,0]
	global_store_dwordx4 v[140:141], v[142:145], off offset:16
	v_pk_mul_f32 v[136:137], v[2:3], v[232:233]
	v_pk_mul_f32 v[134:135], v[0:1], v[230:231]
	v_pk_mul_f32 v[136:137], v[136:137], s[16:17] op_sel_hi:[1,0]
	v_pk_mul_f32 v[134:135], v[134:135], s[16:17] op_sel_hi:[1,0]
	global_store_dwordx4 v[140:141], v[134:137], off offset:512
	v_pk_mul_f32 v[144:145], v[6:7], v[236:237]
	v_pk_mul_f32 v[142:143], v[4:5], v[234:235]
	v_pk_mul_f32 v[144:145], v[144:145], s[16:17] op_sel_hi:[1,0]
	v_pk_mul_f32 v[142:143], v[142:143], s[16:17] op_sel_hi:[1,0]
	global_store_dwordx4 v[140:141], v[142:145], off offset:528
	s_cbranch_execnz .LBB0_2296

; #define PG8_STAGE(bufoff, gbase, voff) do { _Pragma("unroll") for (int _i = 0; _i < 2; ++_i) \
;         __builtin_amdgcn_global_load_lds((const unsigned*)((const char*)(gbase) + (voff)[_i]), (LAS unsigned*)(lds + (bufoff) + ldsw + _i * 8192), 16, 0, 0); } while (0)
; #define PG8_LDA(dst, b, h) do { _Pragma("unroll") for (int m = 0; m < 4; ++m) _Pragma("unroll") for (int k = 0; k < 2; ++k) dst[m][k] = *(const LAS bf16x8*)(lds + PG8_SA(b, h) + aoff + m * 2048 + k * KOFF); } while (0)
; template <class Epi, bool ALIGN_EPI = true, bool FP8 = false>
; __device__ __forceinline__ void gemm_phase(LAS unsigned char* lds, const Gemm g, const StaticOrder& S, const Epi& E, const int wid) {
;     ...
;         for (int t = 0; t < nt; t += 2) {
;             const bool last = (t == nt - 2);
;             if constexpr (FP8) {
; #pragma unroll
;                 for (int a = 0; a < 2; ++a)
; #pragma unroll
;                     for (int b = 0; b < 2; ++b)
; #pragma unroll
;                         for (int m = 0; m < 4; ++m) asm volatile("" : "+v"(acc8[a][b][m]));
;             }
;             const char* a1 = cA + (size_t)(t + 1) * kstep;
;             const char* a2 = last ? nA : cA + (size_t)(t + 2) * kstep; const char* b2 = last ? nB : cB + (size_t)(t + 2) * kstep;
;             const char* a3 = a2 + kstep; const char* b3 = b2 + kstep;
;             PG8_LDB(B0, 0, 0); PG8_LDB(B1, 0, 1); PG8_SCHED; PG8_LDA(At, 0, 0); PG8_STAGE(PG8_SA(1, 1), a1 + hstep, voffA);
;             PG8_WAIT_V(8); PG8_WAIT_L(0); PG8_BAR; PG8_MMA(0, 0, At, B0); PG8_MMA(0, 1, At, B1); PG8_BAR; PG8_SCHED;
;             PG8_LDA(At, 0, 1); PG8_STAGE(PG8_SB(0, 0), b2, voffB); PG8_STAGE(PG8_SB(0, 1), b2 + hstep, voffB); PG8_STAGE(PG8_SA(0, 0), a2, voffA);
;             PG8_WAIT_V(8); PG8_WAIT_L(0); PG8_BAR; PG8_MMA(1, 0, At, B0); PG8_MMA(1, 1, At, B1); PG8_BAR; PG8_SCHED;
;             PG8_LDB(B0, 1, 0); PG8_LDB(B1, 1, 1); PG8_SCHED; PG8_LDA(At, 1, 0); PG8_STAGE(PG8_SA(0, 1), a2 + hstep, voffA);
;             PG8_WAIT_V(8); PG8_WAIT_L(0); PG8_BAR; PG8_MMA(0, 0, At, B0); PG8_MMA(0, 1, At, B1); PG8_BAR; PG8_SCHED;
;             PG8_LDA(At, 1, 1); PG8_STAGE(PG8_SB(1, 0), b3, voffB); PG8_STAGE(PG8_SB(1, 1), b3 + hstep, voffB); PG8_STAGE(PG8_SA(1, 0), a3, voffA);
;             PG8_WAIT_V(8); PG8_WAIT_L(0); PG8_BAR; PG8_MMA(1, 0, At, B0); PG8_MMA(1, 1, At, B1); PG8_BAR; PG8_SCHED;
.LBB0_2452:
	ds_read_b128 v[152:155], v148
	ds_read_b128 v[156:159], v148 offset:1024
	ds_read_b128 v[160:163], v148 offset:2048
	ds_read_b128 v[164:167], v148 offset:3072
	ds_read_b128 v[168:171], v149
	ds_read_b128 v[172:175], v149 offset:1024
	ds_read_b128 v[176:179], v149 offset:2048
	ds_read_b128 v[180:183], v149 offset:3072
	s_add_i32 s76, s30, 2
	s_add_u32 s31, s28, 0xfff80080
	s_addc_u32 s34, s29, -1
	s_cmp_eq_u32 s43, s30
	s_cselect_b32 s30, s42, s52
	s_cselect_b32 s35, s3, s34
	s_cselect_b32 s34, s17, s31
	s_cselect_b32 s31, s19, s75
	v_lshl_add_u64 v[144:145], s[28:29], 0, v[138:139]
	s_add_i32 m0, s25, 0xc000
	ds_read_b128 v[184:187], v150
	ds_read_b128 v[188:191], v150 offset:1024
	ds_read_b128 v[192:195], v150 offset:2048
	ds_read_b128 v[196:199], v150 offset:3072
	ds_read_b128 v[200:203], v150 offset:4096
	ds_read_b128 v[204:207], v150 offset:5120
	ds_read_b128 v[208:211], v150 offset:6144
	ds_read_b128 v[212:215], v150 offset:7168
	global_load_lds_dwordx4 v[144:145], off
	v_lshl_add_u64 v[144:145], s[28:29], 0, v[140:141]
	s_add_i32 m0, s25, 0xe000
	s_nop 0
	global_load_lds_dwordx4 v[144:145], off
	s_waitcnt vmcnt(8)
	s_waitcnt lgkmcnt(0)
	s_barrier
	s_setprio 1
	s_waitcnt lgkmcnt(0)
	v_mfma_f32_16x16x32_bf16 v[124:127], v[152:155], v[184:187], v[124:127]
	v_mfma_f32_16x16x32_bf16 v[116:119], v[160:163], v[184:187], v[116:119]
	v_mfma_f32_16x16x32_bf16 v[108:111], v[152:155], v[192:195], v[108:111]
	v_mfma_f32_16x16x32_bf16 v[100:103], v[160:163], v[192:195], v[100:103]
	v_mfma_f32_16x16x32_bf16 v[92:95], v[152:155], v[200:203], v[92:95]
	v_mfma_f32_16x16x32_bf16 v[84:87], v[160:163], v[200:203], v[84:87]
	v_mfma_f32_16x16x32_bf16 v[76:79], v[152:155], v[208:211], v[76:79]
	v_mfma_f32_16x16x32_bf16 v[68:71], v[160:163], v[208:211], v[68:71]
	v_mfma_f32_16x16x32_bf16 v[124:127], v[156:159], v[188:191], v[124:127]
	v_mfma_f32_16x16x32_bf16 v[116:119], v[164:167], v[188:191], v[116:119]
	v_mfma_f32_16x16x32_bf16 v[108:111], v[156:159], v[196:199], v[108:111]
	v_mfma_f32_16x16x32_bf16 v[100:103], v[164:167], v[196:199], v[100:103]
	v_mfma_f32_16x16x32_bf16 v[92:95], v[156:159], v[204:207], v[92:95]
	v_mfma_f32_16x16x32_bf16 v[84:87], v[164:167], v[204:207], v[84:87]
	v_mfma_f32_16x16x32_bf16 v[76:79], v[156:159], v[212:215], v[76:79]
	v_mfma_f32_16x16x32_bf16 v[68:71], v[164:167], v[212:215], v[68:71]
	s_setprio 0
	s_setprio 1
	v_mfma_f32_16x16x32_bf16 v[120:123], v[168:171], v[184:187], v[120:123]
	v_mfma_f32_16x16x32_bf16 v[112:115], v[176:179], v[184:187], v[112:115]
	v_mfma_f32_16x16x32_bf16 v[104:107], v[168:171], v[192:195], v[104:107]
	v_mfma_f32_16x16x32_bf16 v[96:99], v[176:179], v[192:195], v[96:99]
	v_mfma_f32_16x16x32_bf16 v[88:91], v[168:171], v[200:203], v[88:91]
	v_mfma_f32_16x16x32_bf16 v[80:83], v[176:179], v[200:203], v[80:83]
	v_mfma_f32_16x16x32_bf16 v[72:75], v[168:171], v[208:211], v[72:75]
	v_mfma_f32_16x16x32_bf16 v[64:67], v[176:179], v[208:211], v[64:67]
	v_mfma_f32_16x16x32_bf16 v[120:123], v[172:175], v[188:191], v[120:123]
	v_mfma_f32_16x16x32_bf16 v[112:115], v[180:183], v[188:191], v[112:115]
	v_mfma_f32_16x16x32_bf16 v[104:107], v[172:175], v[196:199], v[104:107]
	v_mfma_f32_16x16x32_bf16 v[96:99], v[180:183], v[196:199], v[96:99]
	v_mfma_f32_16x16x32_bf16 v[88:91], v[172:175], v[204:207], v[88:91]
	v_mfma_f32_16x16x32_bf16 v[80:83], v[180:183], v[204:207], v[80:83]
	v_mfma_f32_16x16x32_bf16 v[72:75], v[172:175], v[212:215], v[72:75]
	v_mfma_f32_16x16x32_bf16 v[64:67], v[180:183], v[212:215], v[64:67]
	s_setprio 0
	s_barrier
	s_add_i32 s77, s65, s38
	v_lshl_add_u64 v[144:145], s[30:31], 0, v[132:133]
	s_mov_b32 m0, s77
	ds_read_b128 v[184:187], v150 offset:16384
	ds_read_b128 v[188:191], v150 offset:17408
	ds_read_b128 v[192:195], v150 offset:18432
	ds_read_b128 v[196:199], v150 offset:19456
	ds_read_b128 v[200:203], v150 offset:20480
	ds_read_b128 v[204:207], v150 offset:21504
	ds_read_b128 v[208:211], v150 offset:22528
	ds_read_b128 v[212:215], v150 offset:23552
	global_load_lds_dwordx4 v[144:145], off
	s_add_i32 m0, s77, 0x2000
	s_add_u32 s78, s30, 0x80000
	v_lshl_add_u64 v[216:217], s[30:31], 0, v[128:129]
	s_addc_u32 s79, s31, 0
	s_add_i32 s77, s66, s38
	global_load_lds_dwordx4 v[216:217], off
	v_lshl_add_u64 v[218:219], s[78:79], 0, v[132:133]
	s_mov_b32 m0, s77
	v_lshl_add_u64 v[220:221], s[34:35], 0, v[130:131]
	global_load_lds_dwordx4 v[218:219], off
	v_lshl_add_u64 v[218:219], s[78:79], 0, v[128:129]
	s_add_i32 m0, s77, 0x2000
	s_nop 0
	global_load_lds_dwordx4 v[218:219], off
	v_lshl_add_u64 v[218:219], s[34:35], 0, v[134:135]
	s_mov_b32 m0, s25
	s_nop 0
	global_load_lds_dwordx4 v[218:219], off
	s_mov_b32 m0, s27
	s_nop 0
	global_load_lds_dwordx4 v[220:221], off
	s_waitcnt vmcnt(8)
	s_waitcnt lgkmcnt(0)
	s_barrier
; #define PG8_STAGE(bufoff, gbase, voff) do { _Pragma("unroll") for (int _i = 0; _i < 2; ++_i) \
;         __builtin_amdgcn_global_load_lds((const unsigned*)((const char*)(gbase) + (voff)[_i]), (LAS unsigned*)(lds + (bufoff) + ldsw + _i * 8192), 16, 0, 0); } while (0)
; #define PG8_LDA(dst, b, h) do { _Pragma("unroll") for (int m = 0; m < 4; ++m) _Pragma("unroll") for (int k = 0; k < 2; ++k) dst[m][k] = *(const LAS bf16x8*)(lds + PG8_SA(b, h) + aoff + m * 2048 + k * KOFF); } while (0)
; #define PG8_LDB(dst, b, h) do { _Pragma("unroll") for (int n = 0; n < 2; ++n) _Pragma("unroll") for (int k = 0; k < 2; ++k) dst[n][k] = *(const LAS bf16x8*)(lds + PG8_SB(b, h) + boff + n * 2048 + k * KOFF); } while (0)
; #define PG8_WAIT_V(n) asm volatile("s_waitcnt vmcnt(" #n ")" ::: "memory")
; #define PG8_WAIT_L(n) asm volatile("s_waitcnt lgkmcnt(" #n ")" ::: "memory")
; template <class Epi, bool ALIGN_EPI = true, bool FP8 = false>
; __device__ __forceinline__ void gemm_phase(LAS unsigned char* lds, const Gemm g, const StaticOrder& S, const Epi& E, const int wid) {
;     ...
;             const char* a1 = cA + (size_t)(t + 1) * kstep;
;             const char* a2 = last ? nA : cA + (size_t)(t + 2) * kstep; const char* b2 = last ? nB : cB + (size_t)(t + 2) * kstep;
;             const char* a3 = a2 + kstep; const char* b3 = b2 + kstep;
;             PG8_LDB(B0, 0, 0); PG8_LDB(B1, 0, 1); PG8_SCHED; PG8_LDA(At, 0, 0); PG8_STAGE(PG8_SA(1, 1), a1 + hstep, voffA);
;             PG8_WAIT_V(8); PG8_WAIT_L(0); PG8_BAR; PG8_MMA(0, 0, At, B0); PG8_MMA(0, 1, At, B1); PG8_BAR; PG8_SCHED;
;             PG8_LDA(At, 0, 1); PG8_STAGE(PG8_SB(0, 0), b2, voffB); PG8_STAGE(PG8_SB(0, 1), b2 + hstep, voffB); PG8_STAGE(PG8_SA(0, 0), a2, voffA);
;             PG8_WAIT_V(8); PG8_WAIT_L(0); PG8_BAR; PG8_MMA(1, 0, At, B0); PG8_MMA(1, 1, At, B1); PG8_BAR; PG8_SCHED;
;             PG8_LDB(B0, 1, 0); PG8_LDB(B1, 1, 1); PG8_SCHED; PG8_LDA(At, 1, 0); PG8_STAGE(PG8_SA(0, 1), a2 + hstep, voffA);
;             PG8_WAIT_V(8); PG8_WAIT_L(0); PG8_BAR; PG8_MMA(0, 0, At, B0); PG8_MMA(0, 1, At, B1); PG8_BAR; PG8_SCHED;
;             PG8_LDA(At, 1, 1); PG8_STAGE(PG8_SB(1, 0), b3, voffB); PG8_STAGE(PG8_SB(1, 1), b3 + hstep, voffB); PG8_STAGE(PG8_SA(1, 0), a3, voffA);
;             PG8_WAIT_V(8); PG8_WAIT_L(0); PG8_BAR; PG8_MMA(1, 0, At, B0); PG8_MMA(1, 1, At, B1); PG8_BAR; PG8_SCHED;
	s_setprio 1
	s_waitcnt lgkmcnt(0)
	v_mfma_f32_16x16x32_bf16 v[60:63], v[152:155], v[184:187], v[60:63]
	v_mfma_f32_16x16x32_bf16 v[52:55], v[160:163], v[184:187], v[52:55]
	v_mfma_f32_16x16x32_bf16 v[44:47], v[152:155], v[192:195], v[44:47]
	v_mfma_f32_16x16x32_bf16 v[36:39], v[160:163], v[192:195], v[36:39]
	v_mfma_f32_16x16x32_bf16 v[28:31], v[152:155], v[200:203], v[28:31]
	v_mfma_f32_16x16x32_bf16 v[20:23], v[160:163], v[200:203], v[20:23]
	v_mfma_f32_16x16x32_bf16 v[12:15], v[152:155], v[208:211], v[12:15]
	v_mfma_f32_16x16x32_bf16 v[4:7], v[160:163], v[208:211], v[4:7]
	v_mfma_f32_16x16x32_bf16 v[60:63], v[156:159], v[188:191], v[60:63]
	v_mfma_f32_16x16x32_bf16 v[52:55], v[164:167], v[188:191], v[52:55]
	v_mfma_f32_16x16x32_bf16 v[44:47], v[156:159], v[196:199], v[44:47]
	v_mfma_f32_16x16x32_bf16 v[36:39], v[164:167], v[196:199], v[36:39]
	v_mfma_f32_16x16x32_bf16 v[28:31], v[156:159], v[204:207], v[28:31]
	v_mfma_f32_16x16x32_bf16 v[20:23], v[164:167], v[204:207], v[20:23]
	v_mfma_f32_16x16x32_bf16 v[12:15], v[156:159], v[212:215], v[12:15]
	v_mfma_f32_16x16x32_bf16 v[4:7], v[164:167], v[212:215], v[4:7]
	s_setprio 0
	s_setprio 1
	v_mfma_f32_16x16x32_bf16 v[56:59], v[168:171], v[184:187], v[56:59]
	v_mfma_f32_16x16x32_bf16 v[48:51], v[176:179], v[184:187], v[48:51]
	v_mfma_f32_16x16x32_bf16 v[40:43], v[168:171], v[192:195], v[40:43]
	v_mfma_f32_16x16x32_bf16 v[32:35], v[176:179], v[192:195], v[32:35]
	v_mfma_f32_16x16x32_bf16 v[24:27], v[168:171], v[200:203], v[24:27]
	v_mfma_f32_16x16x32_bf16 v[16:19], v[176:179], v[200:203], v[16:19]
	v_mfma_f32_16x16x32_bf16 v[8:11], v[168:171], v[208:211], v[8:11]
	v_mfma_f32_16x16x32_bf16 v[0:3], v[176:179], v[208:211], v[0:3]
	v_mfma_f32_16x16x32_bf16 v[56:59], v[172:175], v[188:191], v[56:59]
	v_mfma_f32_16x16x32_bf16 v[48:51], v[180:183], v[188:191], v[48:51]
	v_mfma_f32_16x16x32_bf16 v[40:43], v[172:175], v[196:199], v[40:43]
	v_mfma_f32_16x16x32_bf16 v[32:35], v[180:183], v[196:199], v[32:35]
	v_mfma_f32_16x16x32_bf16 v[24:27], v[172:175], v[204:207], v[24:27]
	v_mfma_f32_16x16x32_bf16 v[16:19], v[180:183], v[204:207], v[16:19]
	v_mfma_f32_16x16x32_bf16 v[8:11], v[172:175], v[212:215], v[8:11]
	v_mfma_f32_16x16x32_bf16 v[0:3], v[180:183], v[212:215], v[0:3]
	s_setprio 0
	s_barrier
	s_add_i32 s77, 0, 0x18000
	s_add_i32 s78, 0, 0x1c000
	v_add_u32_e32 v164, s77, v147
	v_add_u32_e32 v180, s78, v147
	ds_read_b128 v[152:155], v164
	ds_read_b128 v[156:159], v164 offset:1024
	ds_read_b128 v[160:163], v164 offset:2048
	ds_read_b128 v[164:167], v164 offset:3072
	ds_read_b128 v[168:171], v180
	ds_read_b128 v[172:175], v180 offset:1024
	ds_read_b128 v[176:179], v180 offset:2048
	ds_read_b128 v[180:183], v180 offset:3072
	s_add_u32 s34, s34, 0x80000
	s_addc_u32 s35, s35, 0
	s_mov_b32 m0, s39
	v_lshl_add_u64 v[222:223], s[34:35], 0, v[134:135]
	ds_read_b128 v[184:187], v150 offset:32768
	ds_read_b128 v[188:191], v150 offset:33792
	ds_read_b128 v[192:195], v150 offset:34816
	ds_read_b128 v[196:199], v150 offset:35840
	ds_read_b128 v[200:203], v150 offset:36864
	ds_read_b128 v[204:207], v150 offset:37888
	ds_read_b128 v[208:211], v150 offset:38912
	ds_read_b128 v[212:215], v150 offset:39936
	global_load_lds_dwordx4 v[222:223], off
	v_lshl_add_u64 v[222:223], s[34:35], 0, v[130:131]
	s_mov_b32 m0, s48
	s_nop 0
	global_load_lds_dwordx4 v[222:223], off
	s_waitcnt vmcnt(8)
	s_waitcnt lgkmcnt(0)
	s_barrier
	s_setprio 1
	s_waitcnt lgkmcnt(0)
	v_mfma_f32_16x16x32_bf16 v[124:127], v[152:155], v[184:187], v[124:127]
	v_mfma_f32_16x16x32_bf16 v[116:119], v[160:163], v[184:187], v[116:119]
	v_mfma_f32_16x16x32_bf16 v[108:111], v[152:155], v[192:195], v[108:111]
	v_mfma_f32_16x16x32_bf16 v[100:103], v[160:163], v[192:195], v[100:103]
	v_mfma_f32_16x16x32_bf16 v[92:95], v[152:155], v[200:203], v[92:95]
	v_mfma_f32_16x16x32_bf16 v[84:87], v[160:163], v[200:203], v[84:87]
	v_mfma_f32_16x16x32_bf16 v[76:79], v[152:155], v[208:211], v[76:79]
	v_mfma_f32_16x16x32_bf16 v[68:71], v[160:163], v[208:211], v[68:71]
	v_mfma_f32_16x16x32_bf16 v[124:127], v[156:159], v[188:191], v[124:127]
	v_mfma_f32_16x16x32_bf16 v[116:119], v[164:167], v[188:191], v[116:119]
	v_mfma_f32_16x16x32_bf16 v[108:111], v[156:159], v[196:199], v[108:111]
	v_mfma_f32_16x16x32_bf16 v[100:103], v[164:167], v[196:199], v[100:103]
	v_mfma_f32_16x16x32_bf16 v[92:95], v[156:159], v[204:207], v[92:95]
	v_mfma_f32_16x16x32_bf16 v[84:87], v[164:167], v[204:207], v[84:87]
	v_mfma_f32_16x16x32_bf16 v[76:79], v[156:159], v[212:215], v[76:79]
	v_mfma_f32_16x16x32_bf16 v[68:71], v[164:167], v[212:215], v[68:71]
	s_setprio 0
	s_setprio 1
	v_mfma_f32_16x16x32_bf16 v[120:123], v[168:171], v[184:187], v[120:123]
	v_mfma_f32_16x16x32_bf16 v[112:115], v[176:179], v[184:187], v[112:115]
	v_mfma_f32_16x16x32_bf16 v[104:107], v[168:171], v[192:195], v[104:107]
	v_mfma_f32_16x16x32_bf16 v[96:99], v[176:179], v[192:195], v[96:99]
	v_mfma_f32_16x16x32_bf16 v[88:91], v[168:171], v[200:203], v[88:91]
	v_mfma_f32_16x16x32_bf16 v[80:83], v[176:179], v[200:203], v[80:83]
	v_mfma_f32_16x16x32_bf16 v[72:75], v[168:171], v[208:211], v[72:75]
	v_mfma_f32_16x16x32_bf16 v[64:67], v[176:179], v[208:211], v[64:67]
	v_mfma_f32_16x16x32_bf16 v[120:123], v[172:175], v[188:191], v[120:123]
	v_mfma_f32_16x16x32_bf16 v[112:115], v[180:183], v[188:191], v[112:115]
	v_mfma_f32_16x16x32_bf16 v[104:107], v[172:175], v[196:199], v[104:107]
	v_mfma_f32_16x16x32_bf16 v[96:99], v[180:183], v[196:199], v[96:99]
	v_mfma_f32_16x16x32_bf16 v[88:91], v[172:175], v[204:207], v[88:91]
	v_mfma_f32_16x16x32_bf16 v[80:83], v[180:183], v[204:207], v[80:83]
	v_mfma_f32_16x16x32_bf16 v[72:75], v[172:175], v[212:215], v[72:75]
	v_mfma_f32_16x16x32_bf16 v[64:67], v[180:183], v[212:215], v[64:67]
	s_setprio 0
	s_barrier
; #define PG8_STAGE(bufoff, gbase, voff) do { _Pragma("unroll") for (int _i = 0; _i < 2; ++_i) \
;         __builtin_amdgcn_global_load_lds((const unsigned*)((const char*)(gbase) + (voff)[_i]), (LAS unsigned*)(lds + (bufoff) + ldsw + _i * 8192), 16, 0, 0); } while (0)
; #define PG8_LDA(dst, b, h) do { _Pragma("unroll") for (int m = 0; m < 4; ++m) _Pragma("unroll") for (int k = 0; k < 2; ++k) dst[m][k] = *(const LAS bf16x8*)(lds + PG8_SA(b, h) + aoff + m * 2048 + k * KOFF); } while (0)
; #define PG8_LDB(dst, b, h) do { _Pragma("unroll") for (int n = 0; n < 2; ++n) _Pragma("unroll") for (int k = 0; k < 2; ++k) dst[n][k] = *(const LAS bf16x8*)(lds + PG8_SB(b, h) + boff + n * 2048 + k * KOFF); } while (0)
; #define PG8_WAIT_V(n) asm volatile("s_waitcnt vmcnt(" #n ")" ::: "memory")
; #define PG8_WAIT_L(n) asm volatile("s_waitcnt lgkmcnt(" #n ")" ::: "memory")
; #define PG8_BAR __builtin_amdgcn_s_barrier()
; #define PG8_SCHED __builtin_amdgcn_sched_barrier(0)
; template <class Epi, bool ALIGN_EPI = true, bool FP8 = false>
; __device__ __forceinline__ void gemm_phase(LAS unsigned char* lds, const Gemm g, const StaticOrder& S, const Epi& E, const int wid) {
;     ...
;             PG8_WAIT_V(8); PG8_WAIT_L(0); PG8_BAR; PG8_MMA(1, 0, At, B0); PG8_MMA(1, 1, At, B1); PG8_BAR; PG8_SCHED;
;             PG8_LDB(B0, 1, 0); PG8_LDB(B1, 1, 1); PG8_SCHED; PG8_LDA(At, 1, 0); PG8_STAGE(PG8_SA(0, 1), a2 + hstep, voffA);
;             PG8_WAIT_V(8); PG8_WAIT_L(0); PG8_BAR; PG8_MMA(0, 0, At, B0); PG8_MMA(0, 1, At, B1); PG8_BAR; PG8_SCHED;
;             PG8_LDA(At, 1, 1); PG8_STAGE(PG8_SB(1, 0), b3, voffB); PG8_STAGE(PG8_SB(1, 1), b3 + hstep, voffB); PG8_STAGE(PG8_SA(1, 0), a3, voffA);
;             PG8_WAIT_V(8); PG8_WAIT_L(0); PG8_BAR; PG8_MMA(1, 0, At, B0); PG8_MMA(1, 1, At, B1); PG8_BAR; PG8_SCHED;
;         }
	s_add_i32 s34, s77, s38
	v_lshl_add_u64 v[144:145], v[144:145], 0, s[14:15]
	s_mov_b32 m0, s34
	ds_read_b128 v[184:187], v150 offset:49152
	ds_read_b128 v[188:191], v150 offset:50176
	ds_read_b128 v[192:195], v150 offset:51200
	ds_read_b128 v[196:199], v150 offset:52224
	ds_read_b128 v[200:203], v150 offset:53248
	ds_read_b128 v[204:207], v150 offset:54272
	ds_read_b128 v[208:211], v150 offset:55296
	ds_read_b128 v[212:215], v150 offset:56320
	global_load_lds_dwordx4 v[144:145], off
	s_add_i32 m0, s34, 0x2000
	s_add_u32 s30, s30, 0x80080
	v_lshl_add_u64 v[144:145], v[216:217], 0, s[14:15]
	s_addc_u32 s31, s31, 0
	s_add_i32 s34, s78, s38
	global_load_lds_dwordx4 v[144:145], off
	v_lshl_add_u64 v[144:145], s[30:31], 0, v[132:133]
	s_mov_b32 m0, s34
	s_nop 0
	global_load_lds_dwordx4 v[144:145], off
	v_lshl_add_u64 v[144:145], s[30:31], 0, v[128:129]
	s_add_i32 m0, s34, 0x2000
	s_nop 0
	global_load_lds_dwordx4 v[144:145], off
	v_lshl_add_u64 v[144:145], v[218:219], 0, s[14:15]
	s_mov_b32 m0, s53
	s_nop 0
	global_load_lds_dwordx4 v[144:145], off
	v_lshl_add_u64 v[144:145], v[220:221], 0, s[14:15]
	s_mov_b32 m0, s55
	s_nop 0
	global_load_lds_dwordx4 v[144:145], off
	s_waitcnt vmcnt(8)
	s_waitcnt lgkmcnt(0)
	s_barrier
	s_setprio 1
	s_waitcnt lgkmcnt(0)
	v_mfma_f32_16x16x32_bf16 v[60:63], v[152:155], v[184:187], v[60:63]
	v_mfma_f32_16x16x32_bf16 v[52:55], v[160:163], v[184:187], v[52:55]
	v_mfma_f32_16x16x32_bf16 v[44:47], v[152:155], v[192:195], v[44:47]
	v_mfma_f32_16x16x32_bf16 v[36:39], v[160:163], v[192:195], v[36:39]
	v_mfma_f32_16x16x32_bf16 v[28:31], v[152:155], v[200:203], v[28:31]
	v_mfma_f32_16x16x32_bf16 v[20:23], v[160:163], v[200:203], v[20:23]
	v_mfma_f32_16x16x32_bf16 v[12:15], v[152:155], v[208:211], v[12:15]
	v_mfma_f32_16x16x32_bf16 v[4:7], v[160:163], v[208:211], v[4:7]
	v_mfma_f32_16x16x32_bf16 v[60:63], v[156:159], v[188:191], v[60:63]
	v_mfma_f32_16x16x32_bf16 v[52:55], v[164:167], v[188:191], v[52:55]
	v_mfma_f32_16x16x32_bf16 v[44:47], v[156:159], v[196:199], v[44:47]
	v_mfma_f32_16x16x32_bf16 v[36:39], v[164:167], v[196:199], v[36:39]
	v_mfma_f32_16x16x32_bf16 v[28:31], v[156:159], v[204:207], v[28:31]
	v_mfma_f32_16x16x32_bf16 v[20:23], v[164:167], v[204:207], v[20:23]
	v_mfma_f32_16x16x32_bf16 v[12:15], v[156:159], v[212:215], v[12:15]
	v_mfma_f32_16x16x32_bf16 v[4:7], v[164:167], v[212:215], v[4:7]
	s_setprio 0
	s_setprio 1
	v_mfma_f32_16x16x32_bf16 v[56:59], v[168:171], v[184:187], v[56:59]
	v_mfma_f32_16x16x32_bf16 v[48:51], v[176:179], v[184:187], v[48:51]
	v_mfma_f32_16x16x32_bf16 v[40:43], v[168:171], v[192:195], v[40:43]
	v_mfma_f32_16x16x32_bf16 v[32:35], v[176:179], v[192:195], v[32:35]
	v_mfma_f32_16x16x32_bf16 v[24:27], v[168:171], v[200:203], v[24:27]
	v_mfma_f32_16x16x32_bf16 v[16:19], v[176:179], v[200:203], v[16:19]
	v_mfma_f32_16x16x32_bf16 v[8:11], v[168:171], v[208:211], v[8:11]
	v_mfma_f32_16x16x32_bf16 v[0:3], v[176:179], v[208:211], v[0:3]
	v_mfma_f32_16x16x32_bf16 v[56:59], v[172:175], v[188:191], v[56:59]
	v_mfma_f32_16x16x32_bf16 v[48:51], v[180:183], v[188:191], v[48:51]
	v_mfma_f32_16x16x32_bf16 v[40:43], v[172:175], v[196:199], v[40:43]
	v_mfma_f32_16x16x32_bf16 v[32:35], v[180:183], v[196:199], v[32:35]
	v_mfma_f32_16x16x32_bf16 v[24:27], v[172:175], v[204:207], v[24:27]
	v_mfma_f32_16x16x32_bf16 v[16:19], v[180:183], v[204:207], v[16:19]
	v_mfma_f32_16x16x32_bf16 v[8:11], v[172:175], v[212:215], v[8:11]
	v_mfma_f32_16x16x32_bf16 v[0:3], v[180:183], v[212:215], v[0:3]
	s_setprio 0
	s_barrier
	s_add_u32 s28, s28, 0x100
	s_addc_u32 s29, s29, 0
	s_add_u32 s52, s52, 0x100
	s_addc_u32 s75, s75, 0
	s_cmp_ge_u32 s76, s54
	s_mov_b32 s30, s76
	s_cbranch_scc0 .LBB0_2452
	s_and_b64 vcc, exec, s[12:13]
	s_cbranch_vccz .LBB0_2455

; #define PG8_STAGE(bufoff, gbase, voff) do { _Pragma("unroll") for (int _i = 0; _i < 2; ++_i) \
;         __builtin_amdgcn_global_load_lds((const unsigned*)((const char*)(gbase) + (voff)[_i]), (LAS unsigned*)(lds + (bufoff) + ldsw + _i * 8192), 16, 0, 0); } while (0)
; #define PG8_LDA(dst, b, h) do { _Pragma("unroll") for (int m = 0; m < 4; ++m) _Pragma("unroll") for (int k = 0; k < 2; ++k) dst[m][k] = *(const LAS bf16x8*)(lds + PG8_SA(b, h) + aoff + m * 2048 + k * KOFF); } while (0)
; #define PG8_LDB(dst, b, h) do { _Pragma("unroll") for (int n = 0; n < 2; ++n) _Pragma("unroll") for (int k = 0; k < 2; ++k) dst[n][k] = *(const LAS bf16x8*)(lds + PG8_SB(b, h) + boff + n * 2048 + k * KOFF); } while (0)
; #define PG8_WAIT_V(n) asm volatile("s_waitcnt vmcnt(" #n ")" ::: "memory")
; #define PG8_WAIT_L(n) asm volatile("s_waitcnt lgkmcnt(" #n ")" ::: "memory")
; template <class Epi, bool ALIGN_EPI = true, bool FP8 = false>
; __device__ __forceinline__ void gemm_phase(LAS unsigned char* lds, const Gemm g, const StaticOrder& S, const Epi& E, const int wid) {
;     ...
;             const char* a1 = cA + (size_t)(t + 1) * kstep;
;             const char* a2 = last ? nA : cA + (size_t)(t + 2) * kstep; const char* b2 = last ? nB : cB + (size_t)(t + 2) * kstep;
;             const char* a3 = a2 + kstep; const char* b3 = b2 + kstep;
;             PG8_LDB(B0, 0, 0); PG8_LDB(B1, 0, 1); PG8_SCHED; PG8_LDA(At, 0, 0); PG8_STAGE(PG8_SA(1, 1), a1 + hstep, voffA);
;             PG8_WAIT_V(8); PG8_WAIT_L(0); PG8_BAR; PG8_MMA(0, 0, At, B0); PG8_MMA(0, 1, At, B1); PG8_BAR; PG8_SCHED;
;             PG8_LDA(At, 0, 1); PG8_STAGE(PG8_SB(0, 0), b2, voffB); PG8_STAGE(PG8_SB(0, 1), b2 + hstep, voffB); PG8_STAGE(PG8_SA(0, 0), a2, voffA);
;             PG8_WAIT_V(8); PG8_WAIT_L(0); PG8_BAR; PG8_MMA(1, 0, At, B0); PG8_MMA(1, 1, At, B1); PG8_BAR; PG8_SCHED;
;             PG8_LDB(B0, 1, 0); PG8_LDB(B1, 1, 1); PG8_SCHED; PG8_LDA(At, 1, 0); PG8_STAGE(PG8_SA(0, 1), a2 + hstep, voffA);
;             PG8_WAIT_V(8); PG8_WAIT_L(0); PG8_BAR; PG8_MMA(0, 0, At, B0); PG8_MMA(0, 1, At, B1); PG8_BAR; PG8_SCHED;
;             PG8_LDA(At, 1, 1); PG8_STAGE(PG8_SB(1, 0), b3, voffB); PG8_STAGE(PG8_SB(1, 1), b3 + hstep, voffB); PG8_STAGE(PG8_SA(1, 0), a3, voffA);
;             PG8_WAIT_V(8); PG8_WAIT_L(0); PG8_BAR; PG8_MMA(1, 0, At, B0); PG8_MMA(1, 1, At, B1); PG8_BAR; PG8_SCHED;
.LBB0_2536:
	ds_read_b128 v[152:155], v188
	ds_read_b128 v[156:159], v188 offset:1024
	ds_read_b128 v[144:147], v188 offset:2048
	ds_read_b128 v[148:151], v188 offset:3072
	ds_read_b128 v[136:139], v189
	ds_read_b128 v[140:143], v189 offset:1024
	ds_read_b128 v[128:131], v189 offset:2048
	ds_read_b128 v[132:135], v189 offset:3072
	s_add_i32 s42, s26, 2
	s_add_u32 s27, s24, 0xfff50080
	s_addc_u32 s28, s25, -1
	s_cmp_eq_u32 s81, s26
	s_cselect_b32 s26, s20, s82
	s_cselect_b32 s29, s7, s28
	s_cselect_b32 s28, s6, s27
	s_cselect_b32 s27, s21, s83
	v_lshl_add_u64 v[216:217], s[24:25], 0, v[172:173]
	s_add_i32 m0, s34, 0xc000
	ds_read_b128 v[178:181], v190
	ds_read_b128 v[182:185], v190 offset:1024
	ds_read_b128 v[192:195], v190 offset:2048
	ds_read_b128 v[196:199], v190 offset:3072
	ds_read_b128 v[200:203], v190 offset:4096
	ds_read_b128 v[204:207], v190 offset:5120
	ds_read_b128 v[208:211], v190 offset:6144
	ds_read_b128 v[212:215], v190 offset:7168
	global_load_lds_dwordx4 v[216:217], off
	v_lshl_add_u64 v[216:217], s[24:25], 0, v[174:175]
	s_add_i32 m0, s34, 0xe000
	s_nop 0
	global_load_lds_dwordx4 v[216:217], off
	s_waitcnt vmcnt(8)
	s_waitcnt lgkmcnt(0)
	s_barrier
	s_setprio 1
	s_waitcnt lgkmcnt(0)
	v_mfma_f32_16x16x128_f8f6f4 v[120:123], v[152:159], v[178:185], v[120:123]
	v_mfma_f32_16x16x128_f8f6f4 v[124:127], v[144:151], v[178:185], v[124:127]
	v_mfma_f32_16x16x128_f8f6f4 v[112:115], v[152:159], v[192:199], v[112:115]
	v_mfma_f32_16x16x128_f8f6f4 v[116:119], v[144:151], v[192:199], v[116:119]
	v_mfma_f32_16x16x128_f8f6f4 v[96:99], v[152:159], v[200:207], v[96:99]
	v_mfma_f32_16x16x128_f8f6f4 v[100:103], v[144:151], v[200:207], v[100:103]
	v_mfma_f32_16x16x128_f8f6f4 v[80:83], v[152:159], v[208:215], v[80:83]
	v_mfma_f32_16x16x128_f8f6f4 v[84:87], v[144:151], v[208:215], v[84:87]
	s_setprio 0
	s_setprio 1
	v_mfma_f32_16x16x128_f8f6f4 v[104:107], v[136:143], v[178:185], v[104:107]
	v_mfma_f32_16x16x128_f8f6f4 v[108:111], v[128:135], v[178:185], v[108:111]
	v_mfma_f32_16x16x128_f8f6f4 v[88:91], v[136:143], v[192:199], v[88:91]
	v_mfma_f32_16x16x128_f8f6f4 v[92:95], v[128:135], v[192:199], v[92:95]
	v_mfma_f32_16x16x128_f8f6f4 v[72:75], v[136:143], v[200:207], v[72:75]
	v_mfma_f32_16x16x128_f8f6f4 v[76:79], v[128:135], v[200:207], v[76:79]
	v_mfma_f32_16x16x128_f8f6f4 v[64:67], v[136:143], v[208:215], v[64:67]
	v_mfma_f32_16x16x128_f8f6f4 v[68:71], v[128:135], v[208:215], v[68:71]
	s_setprio 0
	s_barrier
	s_add_i32 s43, s64, s31
	v_lshl_add_u64 v[178:179], s[26:27], 0, v[162:163]
	s_mov_b32 m0, s43
	ds_read_b128 v[192:195], v190 offset:16384
	ds_read_b128 v[196:199], v190 offset:17408
	ds_read_b128 v[200:203], v190 offset:18432
	ds_read_b128 v[204:207], v190 offset:19456
	ds_read_b128 v[208:211], v190 offset:20480
	ds_read_b128 v[212:215], v190 offset:21504
	ds_read_b128 v[216:219], v190 offset:22528
	ds_read_b128 v[220:223], v190 offset:23552
	global_load_lds_dwordx4 v[178:179], off
	s_add_i32 m0, s43, 0x2000
	s_add_u32 s84, s26, 0xb0000
	v_lshl_add_u64 v[180:181], s[26:27], 0, v[166:167]
	s_addc_u32 s85, s27, 0
	s_add_i32 s43, s65, s31
	global_load_lds_dwordx4 v[180:181], off
	v_lshl_add_u64 v[182:183], s[84:85], 0, v[162:163]
	s_mov_b32 m0, s43
	v_lshl_add_u64 v[184:185], s[28:29], 0, v[164:165]
	global_load_lds_dwordx4 v[182:183], off
	v_lshl_add_u64 v[182:183], s[84:85], 0, v[166:167]
	s_add_i32 m0, s43, 0x2000
	s_nop 0
	global_load_lds_dwordx4 v[182:183], off
	v_lshl_add_u64 v[182:183], s[28:29], 0, v[160:161]
	s_mov_b32 m0, s34
	s_nop 0
	global_load_lds_dwordx4 v[182:183], off
	s_mov_b32 m0, s35
	s_nop 0
	global_load_lds_dwordx4 v[184:185], off
	s_waitcnt vmcnt(8)
	s_waitcnt lgkmcnt(0)
	s_barrier
	s_setprio 1
	s_waitcnt lgkmcnt(0)
	v_mfma_f32_16x16x128_f8f6f4 v[56:59], v[152:159], v[192:199], v[56:59]
	v_mfma_f32_16x16x128_f8f6f4 v[60:63], v[144:151], v[192:199], v[60:63]
	v_mfma_f32_16x16x128_f8f6f4 v[48:51], v[152:159], v[200:207], v[48:51]
	v_mfma_f32_16x16x128_f8f6f4 v[52:55], v[144:151], v[200:207], v[52:55]
	v_mfma_f32_16x16x128_f8f6f4 v[32:35], v[152:159], v[208:215], v[32:35]
	v_mfma_f32_16x16x128_f8f6f4 v[224:227], v[144:151], v[208:215], v[36:39]
	v_mfma_f32_16x16x128_f8f6f4 v[228:231], v[152:159], v[216:223], v[16:19]
	v_mfma_f32_16x16x128_f8f6f4 v[232:235], v[144:151], v[216:223], v[20:23]
	s_setprio 0
	s_setprio 1
	v_mfma_f32_16x16x128_f8f6f4 v[44:47], v[128:135], v[192:199], v[44:47]
	v_mfma_f32_16x16x128_f8f6f4 v[236:239], v[136:143], v[192:199], v[40:43]
	v_mfma_f32_16x16x128_f8f6f4 v[240:243], v[136:143], v[200:207], v[24:27]
	v_mfma_f32_16x16x128_f8f6f4 v[200:203], v[128:135], v[200:207], v[28:31]
	v_mfma_f32_16x16x128_f8f6f4 v[204:207], v[136:143], v[208:215], v[8:11]
	v_mfma_f32_16x16x128_f8f6f4 v[208:211], v[128:135], v[208:215], v[12:15]
	v_mfma_f32_16x16x128_f8f6f4 v[212:215], v[136:143], v[216:223], v[0:3]
	v_mfma_f32_16x16x128_f8f6f4 v[216:219], v[128:135], v[216:223], v[4:7]
	s_setprio 0
	s_barrier
	s_add_i32 s43, 0, 0x18000
	s_add_i32 s54, 0, 0x1c000
	s_nop 0
	v_add_u32_e32 v12, s43, v187
	v_add_u32_e32 v16, s54, v187
	ds_read_b128 v[0:3], v12
	ds_read_b128 v[4:7], v12 offset:1024
	ds_read_b128 v[8:11], v12 offset:2048
	ds_read_b128 v[12:15], v12 offset:3072
	ds_read_b128 v[128:131], v16
	ds_read_b128 v[132:135], v16 offset:1024
	ds_read_b128 v[136:139], v16 offset:2048
	ds_read_b128 v[140:143], v16 offset:3072
	s_add_u32 s28, s28, 0xb0000
	s_addc_u32 s29, s29, 0
	s_mov_b32 m0, s36
	v_lshl_add_u64 v[152:153], s[28:29], 0, v[160:161]
	ds_read_b128 v[16:19], v190 offset:32768
	ds_read_b128 v[20:23], v190 offset:33792
	ds_read_b128 v[24:27], v190 offset:34816
	ds_read_b128 v[28:31], v190 offset:35840
	ds_read_b128 v[36:39], v190 offset:36864
	ds_read_b128 v[40:43], v190 offset:37888
	ds_read_b128 v[144:147], v190 offset:38912
	ds_read_b128 v[148:151], v190 offset:39936
	global_load_lds_dwordx4 v[152:153], off
	v_lshl_add_u64 v[152:153], s[28:29], 0, v[164:165]
	s_mov_b32 m0, s37
	s_nop 0
	global_load_lds_dwordx4 v[152:153], off
	s_waitcnt vmcnt(8)
	s_waitcnt lgkmcnt(0)
	s_barrier
; #define GAS __attribute__((address_space(1)))
; #define PG8_STAGE(bufoff, gbase, voff) do { _Pragma("unroll") for (int _i = 0; _i < 2; ++_i) \
;         __builtin_amdgcn_global_load_lds((const unsigned*)((const char*)(gbase) + (voff)[_i]), (LAS unsigned*)(lds + (bufoff) + ldsw + _i * 8192), 16, 0, 0); } while (0)
; #define PG8_LDA(dst, b, h) do { _Pragma("unroll") for (int m = 0; m < 4; ++m) _Pragma("unroll") for (int k = 0; k < 2; ++k) dst[m][k] = *(const LAS bf16x8*)(lds + PG8_SA(b, h) + aoff + m * 2048 + k * KOFF); } while (0)
;     __device__ __forceinline__ void operator()(const Acc& acc, const Unit& u, int wr, int wc, int fr, int fq) const {
;     ...
;         if (u.part) {
;             const int ks = u.part - 1, rs0 = u.pm * 256 - MP;
;             char* sl_ = uni_ptr((char*)(slab + ((size_t)ks * MS + rs0) * DM + u.pn * 256));
;             asm volatile("" : "+s"(sl_));
;             GAS char* sl = (GAS char*)sl_;
;             const unsigned lo4 = (unsigned)((wr * 64 + fr) * DM + wc * 32 + 8 * fq) * 4u;
; #pragma unroll
;             for (int ai = 0; ai < 2; ++ai)
; #pragma unroll
;                 for (int m = 0; m < 4; ++m) {
;                     const int gi = NB_P + ((rs0 + ai * HALF + wr * 64) >> 5) + (m >> 1);
;                     const float* grow = gate + (size_t)gi * NADA + col0;
; #pragma unroll
;                     for (int bj = 0; bj < 2; ++bj)
; #pragma unroll
;                         for (int n = 0; n < 2; ++n) { const int co = bj * HALF + n * 4;
;                             *(GAS f32x4*)(sl + (unsigned)((ai * HALF + m * 16) * DM + co) * 4u + lo4) = *(const f32x4*)(grow + co) * acc[ai][bj][m][n] * (SRC_F32 ? 1.0f / (WOUT_SCALE * M_SCALE) : 1.0f / WDN_SCALE); }
; template <class Epi, bool ALIGN_EPI = true, bool FP8 = false>
; __device__ __forceinline__ void gemm_phase(LAS unsigned char* lds, const Gemm g, const StaticOrder& S, const Epi& E, const int wid) {
;     ...
;             PG8_WAIT_V(8); PG8_WAIT_L(0); PG8_BAR; PG8_MMA(0, 0, At, B0); PG8_MMA(0, 1, At, B1); PG8_BAR; PG8_SCHED;
;             PG8_LDA(At, 1, 1); PG8_STAGE(PG8_SB(1, 0), b3, voffB); PG8_STAGE(PG8_SB(1, 1), b3 + hstep, voffB); PG8_STAGE(PG8_SA(1, 0), a3, voffA);
;             PG8_WAIT_V(8); PG8_WAIT_L(0); PG8_BAR; PG8_MMA(1, 0, At, B0); PG8_MMA(1, 1, At, B1); PG8_BAR; PG8_SCHED;
;         }
;         if constexpr (ALIGN_EPI) { if (wr == 0) PG8_BAR; }
	s_setprio 1
	s_waitcnt lgkmcnt(0)
	v_mfma_f32_16x16x128_f8f6f4 v[120:123], v[0:7], v[16:23], v[120:123]
	v_mfma_f32_16x16x128_f8f6f4 v[124:127], v[8:15], v[16:23], v[124:127]
	v_mfma_f32_16x16x128_f8f6f4 v[112:115], v[0:7], v[24:31], v[112:115]
	v_mfma_f32_16x16x128_f8f6f4 v[116:119], v[8:15], v[24:31], v[116:119]
	v_mfma_f32_16x16x128_f8f6f4 v[96:99], v[0:7], v[36:43], v[96:99]
	v_mfma_f32_16x16x128_f8f6f4 v[100:103], v[8:15], v[36:43], v[100:103]
	v_mfma_f32_16x16x128_f8f6f4 v[80:83], v[0:7], v[144:151], v[80:83]
	v_mfma_f32_16x16x128_f8f6f4 v[84:87], v[8:15], v[144:151], v[84:87]
	s_setprio 0
	s_setprio 1
	v_mfma_f32_16x16x128_f8f6f4 v[104:107], v[128:135], v[16:23], v[104:107]
	v_mfma_f32_16x16x128_f8f6f4 v[108:111], v[136:143], v[16:23], v[108:111]
	v_mfma_f32_16x16x128_f8f6f4 v[88:91], v[128:135], v[24:31], v[88:91]
	v_mfma_f32_16x16x128_f8f6f4 v[92:95], v[136:143], v[24:31], v[92:95]
	v_mfma_f32_16x16x128_f8f6f4 v[72:75], v[128:135], v[36:43], v[72:75]
	v_mfma_f32_16x16x128_f8f6f4 v[76:79], v[136:143], v[36:43], v[76:79]
	v_mfma_f32_16x16x128_f8f6f4 v[64:67], v[128:135], v[144:151], v[64:67]
	v_mfma_f32_16x16x128_f8f6f4 v[68:71], v[136:143], v[144:151], v[68:71]
	s_setprio 0
	s_barrier
	s_add_i32 s28, s43, s31
	v_lshl_add_u64 v[16:17], v[178:179], 0, s[14:15]
	s_mov_b32 m0, s28
	ds_read_b128 v[24:27], v190 offset:49152
	ds_read_b128 v[28:31], v190 offset:50176
	ds_read_b128 v[144:147], v190 offset:51200
	ds_read_b128 v[148:151], v190 offset:52224
	ds_read_b128 v[152:155], v190 offset:53248
	ds_read_b128 v[156:159], v190 offset:54272
	ds_read_b128 v[192:195], v190 offset:55296
	ds_read_b128 v[196:199], v190 offset:56320
	global_load_lds_dwordx4 v[16:17], off
	s_add_i32 m0, s28, 0x2000
	s_add_u32 s26, s26, 0xb0080
	v_lshl_add_u64 v[16:17], v[180:181], 0, s[14:15]
	s_addc_u32 s27, s27, 0
	s_add_i32 s28, s54, s31
	global_load_lds_dwordx4 v[16:17], off
	v_lshl_add_u64 v[16:17], s[26:27], 0, v[162:163]
	s_mov_b32 m0, s28
	s_nop 0
	global_load_lds_dwordx4 v[16:17], off
	v_lshl_add_u64 v[16:17], s[26:27], 0, v[166:167]
	s_add_i32 m0, s28, 0x2000
	s_nop 0
	global_load_lds_dwordx4 v[16:17], off
	v_lshl_add_u64 v[16:17], v[182:183], 0, s[14:15]
	s_mov_b32 m0, s52
	s_nop 0
	global_load_lds_dwordx4 v[16:17], off
	v_lshl_add_u64 v[16:17], v[184:185], 0, s[14:15]
	s_mov_b32 m0, s53
	s_nop 0
	global_load_lds_dwordx4 v[16:17], off
	s_waitcnt vmcnt(8)
	s_waitcnt lgkmcnt(0)
	s_barrier
	s_setprio 1
	s_waitcnt lgkmcnt(0)
	v_mfma_f32_16x16x128_f8f6f4 v[56:59], v[0:7], v[24:31], v[56:59]
	v_mfma_f32_16x16x128_f8f6f4 v[60:63], v[8:15], v[24:31], v[60:63]
	v_mfma_f32_16x16x128_f8f6f4 v[48:51], v[0:7], v[144:151], v[48:51]
	v_mfma_f32_16x16x128_f8f6f4 v[52:55], v[8:15], v[144:151], v[52:55]
	v_mfma_f32_16x16x128_f8f6f4 v[32:35], v[0:7], v[152:159], v[32:35]
	v_mfma_f32_16x16x128_f8f6f4 v[36:39], v[8:15], v[152:159], v[224:227]
	v_mfma_f32_16x16x128_f8f6f4 v[16:19], v[0:7], v[192:199], v[228:231]
	v_mfma_f32_16x16x128_f8f6f4 v[20:23], v[8:15], v[192:199], v[232:235]
	s_setprio 0
	s_setprio 1
	v_mfma_f32_16x16x128_f8f6f4 v[40:43], v[128:135], v[24:31], v[236:239]
	v_mfma_f32_16x16x128_f8f6f4 v[44:47], v[136:143], v[24:31], v[44:47]
	v_mfma_f32_16x16x128_f8f6f4 v[24:27], v[128:135], v[144:151], v[240:243]
	v_mfma_f32_16x16x128_f8f6f4 v[28:31], v[136:143], v[144:151], v[200:203]
	v_mfma_f32_16x16x128_f8f6f4 v[8:11], v[128:135], v[152:159], v[204:207]
	v_mfma_f32_16x16x128_f8f6f4 v[12:15], v[136:143], v[152:159], v[208:211]
	v_mfma_f32_16x16x128_f8f6f4 v[0:3], v[128:135], v[192:199], v[212:215]
	v_mfma_f32_16x16x128_f8f6f4 v[4:7], v[136:143], v[192:199], v[216:219]
	s_setprio 0
	s_barrier
	s_add_u32 s24, s24, 0x100
	s_addc_u32 s25, s25, 0
	s_add_u32 s82, s82, 0x100
	s_addc_u32 s83, s83, 0
	s_cmp_ge_u32 s42, s80
	s_mov_b32 s26, s42
	s_cbranch_scc0 .LBB0_2536
	s_and_b64 vcc, exec, s[16:17]
	s_cbranch_vccz .LBB0_2539
	s_barrier
.LBB0_2539:
	s_lshl_b32 s24, s23, 8
	s_or_b32 s23, s24, s51
	v_add_u32_e32 v128, s23, v186
	s_cmp_eq_u32 s22, 0
	v_ashrrev_i32_e32 v129, 31, v128
	s_cbranch_scc1 .LBB0_2545
	s_lshl_b32 s23, s79, 8
	s_add_i32 s26, s23, 0xffff8000
	s_ashr_i32 s23, s22, 31
	s_lshl_b64 s[22:23], s[22:23], 22
	s_ashr_i32 s27, s26, 31
	s_add_u32 s25, s58, s22
	s_addc_u32 s28, s59, s23
	s_lshl_b64 s[22:23], s[26:27], 13
	s_add_u32 s27, s25, s22
	s_addc_u32 s28, s28, s23
	s_ashr_i32 s25, s24, 31
	s_lshl_b64 s[22:23], s[24:25], 2
	s_add_u32 s22, s27, s22
	s_addc_u32 s23, s28, s23
	s_add_u32 s28, s22, 0xffc00000
	s_addc_u32 s29, s23, -1
	s_add_i32 s22, s26, s50
	s_ashr_i32 s23, s22, 5
	s_mul_i32 s25, s23, 0xc000
	s_add_i32 s26, s23, 8
	s_mul_hi_i32 s27, s26, 0xc000
	s_add_i32 s26, s25, 0x60000
	s_add_u32 s26, s48, s26
	s_addc_u32 s27, s49, s27
	v_lshlrev_b64 v[132:133], 2, v[128:129]
	v_lshl_add_u64 v[138:139], s[26:27], 0, v[132:133]
	v_lshl_add_u64 v[130:131], s[28:29], 0, v[168:169]
	global_load_dwordx4 v[144:147], v[138:139], off
	global_load_dwordx4 v[148:151], v[138:139], off offset:16
	global_load_dwordx4 v[152:155], v[138:139], off offset:512
	global_load_dwordx4 v[156:159], v[138:139], off offset:528
	s_add_i32 s28, s23, 9
	s_add_i32 s26, s25, 0x6c000
	s_mul_hi_i32 s28, s28, 0xc000
	s_add_u32 s26, s48, s26
	s_addc_u32 s27, s49, s28
	v_lshl_add_u64 v[138:139], s[26:27], 0, v[132:133]
	global_load_dwordx4 v[178:181], v[138:139], off
	global_load_dwordx4 v[182:185], v[138:139], off offset:16
	global_load_dwordx4 v[192:195], v[138:139], off offset:512
	global_load_dwordx4 v[196:199], v[138:139], off offset:528
	s_addk_i32 s22, 0x80
	s_ashr_i32 s23, s22, 5
	s_mul_i32 s25, s23, 0xc000
	s_add_i32 s28, s23, 8
	s_add_i32 s26, s25, 0x60000
	s_mul_hi_i32 s28, s28, 0xc000
	s_add_u32 s26, s48, s26
	s_addc_u32 s27, s49, s28
	v_lshl_add_u64 v[138:139], s[26:27], 0, v[132:133]
	global_load_dwordx4 v[200:203], v[138:139], off
	global_load_dwordx4 v[204:207], v[138:139], off offset:16
	global_load_dwordx4 v[208:211], v[138:139], off offset:512
	global_load_dwordx4 v[212:215], v[138:139], off offset:528
	s_add_i32 s28, s23, 9
	s_add_i32 s26, s25, 0x6c000
	s_mul_hi_i32 s28, s28, 0xc000
	s_add_u32 s26, s48, s26
	s_addc_u32 s27, s49, s28
	v_lshl_add_u64 v[138:139], s[26:27], 0, v[132:133]
	global_load_dwordx4 v[216:219], v[138:139], off
	global_load_dwordx4 v[220:223], v[138:139], off offset:16
	global_load_dwordx4 v[224:227], v[138:139], off offset:512
	global_load_dwordx4 v[228:231], v[138:139], off offset:528
	s_waitcnt vmcnt(0)
; #define GAS __attribute__((address_space(1)))
;     __device__ __forceinline__ void operator()(const Acc& acc, const Unit& u, int wr, int wc, int fr, int fq) const {
;     ...
;             for (int ai = 0; ai < 2; ++ai)
; #pragma unroll
;                 for (int m = 0; m < 4; ++m) {
;                     const int gi = NB_P + ((rs0 + ai * HALF + wr * 64) >> 5) + (m >> 1);
;                     const float* grow = gate + (size_t)gi * NADA + col0;
; #pragma unroll
;                     for (int bj = 0; bj < 2; ++bj)
; #pragma unroll
;                         for (int n = 0; n < 2; ++n) { const int co = bj * HALF + n * 4;
;                             *(GAS f32x4*)(sl + (unsigned)((ai * HALF + m * 16) * DM + co) * 4u + lo4) = *(const f32x4*)(grow + co) * acc[ai][bj][m][n] * (SRC_F32 ? 1.0f / (WOUT_SCALE * M_SCALE) : 1.0f / WDN_SCALE); }
	v_pk_mul_f32 v[136:137], v[122:123], v[146:147]
	v_pk_mul_f32 v[134:135], v[120:121], v[144:145]
	v_pk_mul_f32 v[136:137], v[136:137], s[18:19] op_sel_hi:[1,0]
	v_pk_mul_f32 v[134:135], v[134:135], s[18:19] op_sel_hi:[1,0]
	global_store_dwordx4 v[130:131], v[134:137], off
	v_pk_mul_f32 v[234:235], v[126:127], v[150:151]
	v_pk_mul_f32 v[232:233], v[124:125], v[148:149]
	v_pk_mul_f32 v[234:235], v[234:235], s[18:19] op_sel_hi:[1,0]
	v_pk_mul_f32 v[232:233], v[232:233], s[18:19] op_sel_hi:[1,0]
	global_store_dwordx4 v[130:131], v[232:235], off offset:16
	v_pk_mul_f32 v[136:137], v[106:107], v[154:155]
	v_pk_mul_f32 v[134:135], v[104:105], v[152:153]
	v_pk_mul_f32 v[136:137], v[136:137], s[18:19] op_sel_hi:[1,0]
	v_pk_mul_f32 v[134:135], v[134:135], s[18:19] op_sel_hi:[1,0]
	global_store_dwordx4 v[130:131], v[134:137], off offset:512
	v_pk_mul_f32 v[234:235], v[110:111], v[158:159]
	v_pk_mul_f32 v[232:233], v[108:109], v[156:157]
	v_pk_mul_f32 v[234:235], v[234:235], s[18:19] op_sel_hi:[1,0]
	v_pk_mul_f32 v[232:233], v[232:233], s[18:19] op_sel_hi:[1,0]
	global_store_dwordx4 v[130:131], v[232:235], off offset:528
	v_add_co_u32_e32 v140, vcc, s67, v130
	s_nop 1
	v_addc_co_u32_e32 v141, vcc, 0, v131, vcc
	v_pk_mul_f32 v[136:137], v[114:115], v[146:147]
	v_pk_mul_f32 v[134:135], v[112:113], v[144:145]
	v_pk_mul_f32 v[136:137], v[136:137], s[18:19] op_sel_hi:[1,0]
	v_pk_mul_f32 v[134:135], v[134:135], s[18:19] op_sel_hi:[1,0]
	global_store_dwordx4 v[140:141], v[134:137], off
	v_pk_mul_f32 v[234:235], v[118:119], v[150:151]
	v_pk_mul_f32 v[232:233], v[116:117], v[148:149]
	v_pk_mul_f32 v[234:235], v[234:235], s[18:19] op_sel_hi:[1,0]
	v_pk_mul_f32 v[232:233], v[232:233], s[18:19] op_sel_hi:[1,0]
	global_store_dwordx4 v[140:141], v[232:235], off offset:16
	v_pk_mul_f32 v[136:137], v[90:91], v[154:155]
	v_pk_mul_f32 v[134:135], v[88:89], v[152:153]
	v_pk_mul_f32 v[136:137], v[136:137], s[18:19] op_sel_hi:[1,0]
	v_pk_mul_f32 v[134:135], v[134:135], s[18:19] op_sel_hi:[1,0]
	global_store_dwordx4 v[140:141], v[134:137], off offset:512
	v_pk_mul_f32 v[234:235], v[94:95], v[158:159]
	v_pk_mul_f32 v[232:233], v[92:93], v[156:157]
	v_pk_mul_f32 v[234:235], v[234:235], s[18:19] op_sel_hi:[1,0]
	v_pk_mul_f32 v[232:233], v[232:233], s[18:19] op_sel_hi:[1,0]
	global_store_dwordx4 v[140:141], v[232:235], off offset:528
	v_add_co_u32_e32 v140, vcc, s68, v130
	s_nop 1
	v_addc_co_u32_e32 v141, vcc, 0, v131, vcc
	v_pk_mul_f32 v[136:137], v[98:99], v[180:181]
	v_pk_mul_f32 v[134:135], v[96:97], v[178:179]
	v_pk_mul_f32 v[136:137], v[136:137], s[18:19] op_sel_hi:[1,0]
	v_pk_mul_f32 v[134:135], v[134:135], s[18:19] op_sel_hi:[1,0]
	global_store_dwordx4 v[140:141], v[134:137], off
	v_pk_mul_f32 v[234:235], v[102:103], v[184:185]
	v_pk_mul_f32 v[232:233], v[100:101], v[182:183]
	v_pk_mul_f32 v[234:235], v[234:235], s[18:19] op_sel_hi:[1,0]
	v_pk_mul_f32 v[232:233], v[232:233], s[18:19] op_sel_hi:[1,0]
	global_store_dwordx4 v[140:141], v[232:235], off offset:16
	v_pk_mul_f32 v[136:137], v[74:75], v[194:195]
	v_pk_mul_f32 v[134:135], v[72:73], v[192:193]
	v_pk_mul_f32 v[136:137], v[136:137], s[18:19] op_sel_hi:[1,0]
	v_pk_mul_f32 v[134:135], v[134:135], s[18:19] op_sel_hi:[1,0]
	global_store_dwordx4 v[140:141], v[134:137], off offset:512
	v_pk_mul_f32 v[234:235], v[78:79], v[198:199]
	v_pk_mul_f32 v[232:233], v[76:77], v[196:197]
	v_pk_mul_f32 v[234:235], v[234:235], s[18:19] op_sel_hi:[1,0]
	v_pk_mul_f32 v[232:233], v[232:233], s[18:19] op_sel_hi:[1,0]
	global_store_dwordx4 v[140:141], v[232:235], off offset:528
	v_add_co_u32_e32 v140, vcc, s66, v130
	s_nop 1
	v_addc_co_u32_e32 v141, vcc, 0, v131, vcc
	v_pk_mul_f32 v[136:137], v[82:83], v[180:181]
	v_pk_mul_f32 v[134:135], v[80:81], v[178:179]
	v_pk_mul_f32 v[136:137], v[136:137], s[18:19] op_sel_hi:[1,0]
	v_pk_mul_f32 v[134:135], v[134:135], s[18:19] op_sel_hi:[1,0]
	global_store_dwordx4 v[140:141], v[134:137], off
	v_pk_mul_f32 v[234:235], v[86:87], v[184:185]
	v_pk_mul_f32 v[232:233], v[84:85], v[182:183]
	v_pk_mul_f32 v[234:235], v[234:235], s[18:19] op_sel_hi:[1,0]
	v_pk_mul_f32 v[232:233], v[232:233], s[18:19] op_sel_hi:[1,0]
	global_store_dwordx4 v[140:141], v[232:235], off offset:16
	v_pk_mul_f32 v[136:137], v[66:67], v[194:195]
	v_pk_mul_f32 v[134:135], v[64:65], v[192:193]
	v_pk_mul_f32 v[136:137], v[136:137], s[18:19] op_sel_hi:[1,0]
	v_pk_mul_f32 v[134:135], v[134:135], s[18:19] op_sel_hi:[1,0]
	global_store_dwordx4 v[140:141], v[134:137], off offset:512
	v_pk_mul_f32 v[234:235], v[70:71], v[198:199]
	v_pk_mul_f32 v[232:233], v[68:69], v[196:197]
	v_pk_mul_f32 v[234:235], v[234:235], s[18:19] op_sel_hi:[1,0]
	v_pk_mul_f32 v[232:233], v[232:233], s[18:19] op_sel_hi:[1,0]
	global_store_dwordx4 v[140:141], v[232:235], off offset:528
	v_add_co_u32_e32 v140, vcc, s69, v130
; #define GAS __attribute__((address_space(1)))
;     __device__ __forceinline__ void operator()(const Acc& acc, const Unit& u, int wr, int wc, int fr, int fq) const {
;     ...
;             for (int ai = 0; ai < 2; ++ai)
; #pragma unroll
;                 for (int m = 0; m < 4; ++m) {
;                     const int gi = NB_P + ((rs0 + ai * HALF + wr * 64) >> 5) + (m >> 1);
;                     const float* grow = gate + (size_t)gi * NADA + col0;
; #pragma unroll
;                     for (int bj = 0; bj < 2; ++bj)
; #pragma unroll
;                         for (int n = 0; n < 2; ++n) { const int co = bj * HALF + n * 4;
;                             *(GAS f32x4*)(sl + (unsigned)((ai * HALF + m * 16) * DM + co) * 4u + lo4) = *(const f32x4*)(grow + co) * acc[ai][bj][m][n] * (SRC_F32 ? 1.0f / (WOUT_SCALE * M_SCALE) : 1.0f / WDN_SCALE); }
	s_nop 1
	v_addc_co_u32_e32 v141, vcc, 0, v131, vcc
	v_pk_mul_f32 v[136:137], v[58:59], v[202:203]
	v_pk_mul_f32 v[134:135], v[56:57], v[200:201]
	v_pk_mul_f32 v[136:137], v[136:137], s[18:19] op_sel_hi:[1,0]
	v_pk_mul_f32 v[134:135], v[134:135], s[18:19] op_sel_hi:[1,0]
	global_store_dwordx4 v[140:141], v[134:137], off
	v_pk_mul_f32 v[234:235], v[62:63], v[206:207]
	v_pk_mul_f32 v[232:233], v[60:61], v[204:205]
	v_pk_mul_f32 v[234:235], v[234:235], s[18:19] op_sel_hi:[1,0]
	v_pk_mul_f32 v[232:233], v[232:233], s[18:19] op_sel_hi:[1,0]
	global_store_dwordx4 v[140:141], v[232:235], off offset:16
	v_pk_mul_f32 v[136:137], v[42:43], v[210:211]
	v_pk_mul_f32 v[134:135], v[40:41], v[208:209]
	v_pk_mul_f32 v[136:137], v[136:137], s[18:19] op_sel_hi:[1,0]
	v_pk_mul_f32 v[134:135], v[134:135], s[18:19] op_sel_hi:[1,0]
	global_store_dwordx4 v[140:141], v[134:137], off offset:512
	v_pk_mul_f32 v[234:235], v[46:47], v[214:215]
	v_pk_mul_f32 v[232:233], v[44:45], v[212:213]
	v_pk_mul_f32 v[234:235], v[234:235], s[18:19] op_sel_hi:[1,0]
	v_pk_mul_f32 v[232:233], v[232:233], s[18:19] op_sel_hi:[1,0]
	global_store_dwordx4 v[140:141], v[232:235], off offset:528
	v_add_co_u32_e32 v140, vcc, s70, v130
	s_nop 1
	v_addc_co_u32_e32 v141, vcc, 0, v131, vcc
	v_pk_mul_f32 v[136:137], v[50:51], v[202:203]
	v_pk_mul_f32 v[134:135], v[48:49], v[200:201]
	v_pk_mul_f32 v[136:137], v[136:137], s[18:19] op_sel_hi:[1,0]
	v_pk_mul_f32 v[134:135], v[134:135], s[18:19] op_sel_hi:[1,0]
	global_store_dwordx4 v[140:141], v[134:137], off
	v_pk_mul_f32 v[234:235], v[54:55], v[206:207]
	v_pk_mul_f32 v[232:233], v[52:53], v[204:205]
	v_pk_mul_f32 v[234:235], v[234:235], s[18:19] op_sel_hi:[1,0]
	v_pk_mul_f32 v[232:233], v[232:233], s[18:19] op_sel_hi:[1,0]
	global_store_dwordx4 v[140:141], v[232:235], off offset:16
	v_pk_mul_f32 v[136:137], v[26:27], v[210:211]
	v_pk_mul_f32 v[134:135], v[24:25], v[208:209]
	v_pk_mul_f32 v[136:137], v[136:137], s[18:19] op_sel_hi:[1,0]
	v_pk_mul_f32 v[134:135], v[134:135], s[18:19] op_sel_hi:[1,0]
	global_store_dwordx4 v[140:141], v[134:137], off offset:512
	v_pk_mul_f32 v[234:235], v[30:31], v[214:215]
	v_pk_mul_f32 v[232:233], v[28:29], v[212:213]
	v_pk_mul_f32 v[234:235], v[234:235], s[18:19] op_sel_hi:[1,0]
	v_pk_mul_f32 v[232:233], v[232:233], s[18:19] op_sel_hi:[1,0]
	global_store_dwordx4 v[140:141], v[232:235], off offset:528
	v_add_co_u32_e32 v140, vcc, s71, v130
	s_nop 1
	v_addc_co_u32_e32 v141, vcc, 0, v131, vcc
	v_pk_mul_f32 v[136:137], v[34:35], v[218:219]
	v_pk_mul_f32 v[134:135], v[32:33], v[216:217]
	v_pk_mul_f32 v[136:137], v[136:137], s[18:19] op_sel_hi:[1,0]
	v_pk_mul_f32 v[134:135], v[134:135], s[18:19] op_sel_hi:[1,0]
	global_store_dwordx4 v[140:141], v[134:137], off
	v_pk_mul_f32 v[234:235], v[38:39], v[222:223]
	v_pk_mul_f32 v[232:233], v[36:37], v[220:221]
	v_pk_mul_f32 v[234:235], v[234:235], s[18:19] op_sel_hi:[1,0]
	v_pk_mul_f32 v[232:233], v[232:233], s[18:19] op_sel_hi:[1,0]
	global_store_dwordx4 v[140:141], v[232:235], off offset:16
	v_pk_mul_f32 v[136:137], v[10:11], v[226:227]
	v_pk_mul_f32 v[134:135], v[8:9], v[224:225]
	v_pk_mul_f32 v[136:137], v[136:137], s[18:19] op_sel_hi:[1,0]
	v_pk_mul_f32 v[134:135], v[134:135], s[18:19] op_sel_hi:[1,0]
	global_store_dwordx4 v[140:141], v[134:137], off offset:512
	v_pk_mul_f32 v[234:235], v[14:15], v[230:231]
	v_pk_mul_f32 v[232:233], v[12:13], v[228:229]
	v_pk_mul_f32 v[234:235], v[234:235], s[18:19] op_sel_hi:[1,0]
	v_pk_mul_f32 v[232:233], v[232:233], s[18:19] op_sel_hi:[1,0]
	global_store_dwordx4 v[140:141], v[232:235], off offset:528
	v_add_co_u32_e32 v140, vcc, s38, v130
	s_nop 1
	v_addc_co_u32_e32 v141, vcc, 0, v131, vcc
	v_pk_mul_f32 v[136:137], v[18:19], v[218:219]
	v_pk_mul_f32 v[134:135], v[16:17], v[216:217]
	v_pk_mul_f32 v[136:137], v[136:137], s[18:19] op_sel_hi:[1,0]
	v_pk_mul_f32 v[134:135], v[134:135], s[18:19] op_sel_hi:[1,0]
	global_store_dwordx4 v[140:141], v[134:137], off
	v_pk_mul_f32 v[234:235], v[22:23], v[222:223]
	v_pk_mul_f32 v[232:233], v[20:21], v[220:221]
	v_pk_mul_f32 v[234:235], v[234:235], s[18:19] op_sel_hi:[1,0]
	v_pk_mul_f32 v[232:233], v[232:233], s[18:19] op_sel_hi:[1,0]
	global_store_dwordx4 v[140:141], v[232:235], off offset:16
	v_pk_mul_f32 v[136:137], v[2:3], v[226:227]
	v_pk_mul_f32 v[134:135], v[0:1], v[224:225]
	v_pk_mul_f32 v[136:137], v[136:137], s[18:19] op_sel_hi:[1,0]
	v_pk_mul_f32 v[134:135], v[134:135], s[18:19] op_sel_hi:[1,0]
	global_store_dwordx4 v[140:141], v[134:137], off offset:512
	v_pk_mul_f32 v[234:235], v[6:7], v[230:231]
	v_pk_mul_f32 v[232:233], v[4:5], v[228:229]
	v_pk_mul_f32 v[234:235], v[234:235], s[18:19] op_sel_hi:[1,0]
	v_pk_mul_f32 v[232:233], v[232:233], s[18:19] op_sel_hi:[1,0]
	global_store_dwordx4 v[140:141], v[232:235], off offset:528
	s_cbranch_execnz .LBB0_2542
